# k01 + MFMA issue order n-major within each 8-group (srcA held for 4 MFMAs)
# baseline (speedup 1.0000x reference)
.LBB0_202:
	ds_read_b128 v[148:151], v167
	ds_read_b128 v[152:155], v167 offset:1024
	ds_read_b128 v[156:159], v167 offset:2048
	ds_read_b128 v[160:163], v167 offset:3072
	ds_read_b128 v[172:175], v168
	ds_read_b128 v[176:179], v168 offset:1024
	ds_read_b128 v[180:183], v168 offset:2048
	ds_read_b128 v[184:187], v168 offset:3072
	s_add_u32 s0, s28, 0xfffc0080
	s_addc_u32 s1, s29, -1
	s_cmp_eq_u32 s51, 12
	s_cselect_b32 s31, s21, s1
	s_cselect_b32 s30, s47, s0
	s_cselect_b32 s3, s19, s50
	s_cselect_b32 s2, s48, s49
	v_lshl_add_u64 v[220:221], s[28:29], 0, v[140:141]
	s_add_i32 m0, s27, 0xc000
	ds_read_b128 v[188:191], v169
	ds_read_b128 v[192:195], v169 offset:1024
	ds_read_b128 v[196:199], v169 offset:2048
	ds_read_b128 v[200:203], v169 offset:3072
	ds_read_b128 v[204:207], v169 offset:4096
	ds_read_b128 v[208:211], v169 offset:5120
	ds_read_b128 v[212:215], v169 offset:6144
	ds_read_b128 v[216:219], v169 offset:7168
	global_load_lds_dwordx4 v[220:221], off
	v_lshl_add_u64 v[220:221], s[28:29], 0, v[142:143]
	s_add_i32 m0, s27, 0xe000
	s_nop 0
	global_load_lds_dwordx4 v[220:221], off
	s_waitcnt vmcnt(8)
	s_waitcnt lgkmcnt(0)
	s_barrier
	s_setprio 1
	s_waitcnt lgkmcnt(0)
	v_mfma_f32_16x16x32_bf16 v[126:129], v[148:151], v[188:191], v[126:129]
	v_mfma_f32_16x16x32_bf16 v[110:113], v[148:151], v[196:199], v[110:113]
	v_mfma_f32_16x16x32_bf16 v[94:97], v[148:151], v[204:207], v[94:97]
	v_mfma_f32_16x16x32_bf16 v[78:81], v[148:151], v[212:215], v[78:81]
	v_mfma_f32_16x16x32_bf16 v[118:121], v[156:159], v[188:191], v[118:121]
	v_mfma_f32_16x16x32_bf16 v[106:109], v[156:159], v[196:199], v[106:109]
	v_mfma_f32_16x16x32_bf16 v[90:93], v[156:159], v[204:207], v[90:93]
	v_mfma_f32_16x16x32_bf16 v[74:77], v[156:159], v[212:215], v[74:77]
	v_mfma_f32_16x16x32_bf16 v[126:129], v[152:155], v[192:195], v[126:129]
	v_mfma_f32_16x16x32_bf16 v[110:113], v[152:155], v[200:203], v[110:113]
	v_mfma_f32_16x16x32_bf16 v[94:97], v[152:155], v[208:211], v[94:97]
	v_mfma_f32_16x16x32_bf16 v[78:81], v[152:155], v[216:219], v[78:81]
	v_mfma_f32_16x16x32_bf16 v[118:121], v[160:163], v[192:195], v[118:121]
	v_mfma_f32_16x16x32_bf16 v[106:109], v[160:163], v[200:203], v[106:109]
	v_mfma_f32_16x16x32_bf16 v[90:93], v[160:163], v[208:211], v[90:93]
	v_mfma_f32_16x16x32_bf16 v[74:77], v[160:163], v[216:219], v[74:77]
	s_setprio 0
	s_setprio 1
	v_mfma_f32_16x16x32_bf16 v[122:125], v[172:175], v[188:191], v[122:125]
	v_mfma_f32_16x16x32_bf16 v[102:105], v[172:175], v[196:199], v[102:105]
	v_mfma_f32_16x16x32_bf16 v[86:89], v[172:175], v[204:207], v[86:89]
	v_mfma_f32_16x16x32_bf16 v[70:73], v[172:175], v[212:215], v[70:73]
	v_mfma_f32_16x16x32_bf16 v[114:117], v[180:183], v[188:191], v[114:117]
	v_mfma_f32_16x16x32_bf16 v[98:101], v[180:183], v[196:199], v[98:101]
	v_mfma_f32_16x16x32_bf16 v[82:85], v[180:183], v[204:207], v[82:85]
	v_mfma_f32_16x16x32_bf16 v[66:69], v[180:183], v[212:215], v[66:69]
	v_mfma_f32_16x16x32_bf16 v[122:125], v[176:179], v[192:195], v[122:125]
	v_mfma_f32_16x16x32_bf16 v[102:105], v[176:179], v[200:203], v[102:105]
	v_mfma_f32_16x16x32_bf16 v[86:89], v[176:179], v[208:211], v[86:89]
	v_mfma_f32_16x16x32_bf16 v[70:73], v[176:179], v[216:219], v[70:73]
	v_mfma_f32_16x16x32_bf16 v[114:117], v[184:187], v[192:195], v[114:117]
	v_mfma_f32_16x16x32_bf16 v[98:101], v[184:187], v[200:203], v[98:101]
	v_mfma_f32_16x16x32_bf16 v[82:85], v[184:187], v[208:211], v[82:85]
	v_mfma_f32_16x16x32_bf16 v[66:69], v[184:187], v[216:219], v[66:69]
	s_setprio 0
	s_barrier
	s_add_i32 s0, s43, s36
	v_lshl_add_u64 v[220:221], s[2:3], 0, v[132:133]
	s_mov_b32 m0, s0
	ds_read_b128 v[188:191], v169 offset:16384
	ds_read_b128 v[192:195], v169 offset:17408
	ds_read_b128 v[196:199], v169 offset:18432
	ds_read_b128 v[200:203], v169 offset:19456
	ds_read_b128 v[204:207], v169 offset:20480
	ds_read_b128 v[208:211], v169 offset:21504
	ds_read_b128 v[212:215], v169 offset:22528
	ds_read_b128 v[216:219], v169 offset:23552
	global_load_lds_dwordx4 v[220:221], off
	s_add_i32 m0, s0, 0x2000
	s_add_u32 s0, s2, 0x40000
	v_lshl_add_u64 v[222:223], s[2:3], 0, v[136:137]
	s_addc_u32 s1, s3, 0
	s_add_i32 s52, s44, s36
	global_load_lds_dwordx4 v[222:223], off
	v_lshl_add_u64 v[224:225], s[0:1], 0, v[132:133]
	s_mov_b32 m0, s52
	v_lshl_add_u64 v[226:227], s[30:31], 0, v[134:135]
	global_load_lds_dwordx4 v[224:225], off
	v_lshl_add_u64 v[224:225], s[0:1], 0, v[136:137]
	s_add_i32 m0, s52, 0x2000
	s_nop 0
	global_load_lds_dwordx4 v[224:225], off
	v_lshl_add_u64 v[224:225], s[30:31], 0, v[130:131]
	s_mov_b32 m0, s27
	s_nop 0
	global_load_lds_dwordx4 v[224:225], off
	s_mov_b32 m0, s37
	s_nop 0
	global_load_lds_dwordx4 v[226:227], off
	s_waitcnt vmcnt(8)
	s_waitcnt lgkmcnt(0)
	s_barrier
	s_setprio 1
	s_waitcnt lgkmcnt(0)
	v_mfma_f32_16x16x32_bf16 v[62:65], v[148:151], v[188:191], v[62:65]
	v_mfma_f32_16x16x32_bf16 v[46:49], v[148:151], v[196:199], v[46:49]
	v_mfma_f32_16x16x32_bf16 v[30:33], v[148:151], v[204:207], v[30:33]
	v_mfma_f32_16x16x32_bf16 v[14:17], v[148:151], v[212:215], v[14:17]
	v_mfma_f32_16x16x32_bf16 v[58:61], v[156:159], v[188:191], v[58:61]
	v_mfma_f32_16x16x32_bf16 v[42:45], v[156:159], v[196:199], v[42:45]
	v_mfma_f32_16x16x32_bf16 v[26:29], v[156:159], v[204:207], v[26:29]
	v_mfma_f32_16x16x32_bf16 v[10:13], v[156:159], v[212:215], v[10:13]
	v_mfma_f32_16x16x32_bf16 v[62:65], v[152:155], v[192:195], v[62:65]
	v_mfma_f32_16x16x32_bf16 v[46:49], v[152:155], v[200:203], v[46:49]
	v_mfma_f32_16x16x32_bf16 v[30:33], v[152:155], v[208:211], v[30:33]
	v_mfma_f32_16x16x32_bf16 v[14:17], v[152:155], v[216:219], v[14:17]
	v_mfma_f32_16x16x32_bf16 v[58:61], v[160:163], v[192:195], v[58:61]
	v_mfma_f32_16x16x32_bf16 v[42:45], v[160:163], v[200:203], v[42:45]
	v_mfma_f32_16x16x32_bf16 v[26:29], v[160:163], v[208:211], v[26:29]
	v_mfma_f32_16x16x32_bf16 v[10:13], v[160:163], v[216:219], v[10:13]
	s_setprio 0
	s_setprio 1
	v_mfma_f32_16x16x32_bf16 v[54:57], v[172:175], v[188:191], v[54:57]
	v_mfma_f32_16x16x32_bf16 v[38:41], v[172:175], v[196:199], v[38:41]
	v_mfma_f32_16x16x32_bf16 v[22:25], v[172:175], v[204:207], v[22:25]
	v_mfma_f32_16x16x32_bf16 v[6:9], v[172:175], v[212:215], v[6:9]
	v_mfma_f32_16x16x32_bf16 v[50:53], v[180:183], v[188:191], v[50:53]
	v_mfma_f32_16x16x32_bf16 v[34:37], v[180:183], v[196:199], v[34:37]
	v_mfma_f32_16x16x32_bf16 v[18:21], v[180:183], v[204:207], v[18:21]
	v_mfma_f32_16x16x32_bf16 v[2:5], v[180:183], v[212:215], v[2:5]
	v_mfma_f32_16x16x32_bf16 v[54:57], v[176:179], v[192:195], v[54:57]
	v_mfma_f32_16x16x32_bf16 v[38:41], v[176:179], v[200:203], v[38:41]
	v_mfma_f32_16x16x32_bf16 v[22:25], v[176:179], v[208:211], v[22:25]
	v_mfma_f32_16x16x32_bf16 v[6:9], v[176:179], v[216:219], v[6:9]
	v_mfma_f32_16x16x32_bf16 v[50:53], v[184:187], v[192:195], v[50:53]
	v_mfma_f32_16x16x32_bf16 v[34:37], v[184:187], v[200:203], v[34:37]
	v_mfma_f32_16x16x32_bf16 v[18:21], v[184:187], v[208:211], v[18:21]
	v_mfma_f32_16x16x32_bf16 v[2:5], v[184:187], v[216:219], v[2:5]
	s_setprio 0
	s_barrier
	s_add_i32 s52, 0, 0x18000
	s_add_i32 s53, 0, 0x1c000
	v_add_u32_e32 v160, s52, v166
	v_add_u32_e32 v164, s53, v166
	ds_read_b128 v[148:151], v160
	ds_read_b128 v[152:155], v160 offset:1024
	ds_read_b128 v[156:159], v160 offset:2048
	ds_read_b128 v[160:163], v160 offset:3072
	ds_read_b128 v[172:175], v164
	ds_read_b128 v[176:179], v164 offset:1024
	ds_read_b128 v[180:183], v164 offset:2048
	ds_read_b128 v[184:187], v164 offset:3072
	s_add_u32 s0, s30, 0x40000
	s_addc_u32 s1, s31, 0
	s_mov_b32 m0, s38
	v_lshl_add_u64 v[228:229], s[0:1], 0, v[130:131]
	ds_read_b128 v[188:191], v169 offset:32768
	ds_read_b128 v[192:195], v169 offset:33792
	ds_read_b128 v[196:199], v169 offset:34816
	ds_read_b128 v[200:203], v169 offset:35840
	ds_read_b128 v[204:207], v169 offset:36864
	ds_read_b128 v[208:211], v169 offset:37888
	ds_read_b128 v[212:215], v169 offset:38912
	ds_read_b128 v[216:219], v169 offset:39936
	global_load_lds_dwordx4 v[228:229], off
	v_lshl_add_u64 v[228:229], s[0:1], 0, v[134:135]
	s_mov_b32 m0, s39
	s_nop 0
	global_load_lds_dwordx4 v[228:229], off
	s_waitcnt vmcnt(8)
	s_waitcnt lgkmcnt(0)
	s_barrier
	s_setprio 1
	s_waitcnt lgkmcnt(0)
	v_mfma_f32_16x16x32_bf16 v[126:129], v[148:151], v[188:191], v[126:129]
	v_mfma_f32_16x16x32_bf16 v[110:113], v[148:151], v[196:199], v[110:113]
	v_mfma_f32_16x16x32_bf16 v[94:97], v[148:151], v[204:207], v[94:97]
	v_mfma_f32_16x16x32_bf16 v[78:81], v[148:151], v[212:215], v[78:81]
	v_mfma_f32_16x16x32_bf16 v[118:121], v[156:159], v[188:191], v[118:121]
	v_mfma_f32_16x16x32_bf16 v[106:109], v[156:159], v[196:199], v[106:109]
	v_mfma_f32_16x16x32_bf16 v[90:93], v[156:159], v[204:207], v[90:93]
	v_mfma_f32_16x16x32_bf16 v[74:77], v[156:159], v[212:215], v[74:77]
	v_mfma_f32_16x16x32_bf16 v[126:129], v[152:155], v[192:195], v[126:129]
	v_mfma_f32_16x16x32_bf16 v[110:113], v[152:155], v[200:203], v[110:113]
	v_mfma_f32_16x16x32_bf16 v[94:97], v[152:155], v[208:211], v[94:97]
	v_mfma_f32_16x16x32_bf16 v[78:81], v[152:155], v[216:219], v[78:81]
	v_mfma_f32_16x16x32_bf16 v[118:121], v[160:163], v[192:195], v[118:121]
	v_mfma_f32_16x16x32_bf16 v[106:109], v[160:163], v[200:203], v[106:109]
	v_mfma_f32_16x16x32_bf16 v[90:93], v[160:163], v[208:211], v[90:93]
	v_mfma_f32_16x16x32_bf16 v[74:77], v[160:163], v[216:219], v[74:77]
	s_setprio 0
	s_setprio 1
	v_mfma_f32_16x16x32_bf16 v[122:125], v[172:175], v[188:191], v[122:125]
	v_mfma_f32_16x16x32_bf16 v[102:105], v[172:175], v[196:199], v[102:105]
	v_mfma_f32_16x16x32_bf16 v[86:89], v[172:175], v[204:207], v[86:89]
	v_mfma_f32_16x16x32_bf16 v[70:73], v[172:175], v[212:215], v[70:73]
	v_mfma_f32_16x16x32_bf16 v[114:117], v[180:183], v[188:191], v[114:117]
	v_mfma_f32_16x16x32_bf16 v[98:101], v[180:183], v[196:199], v[98:101]
	v_mfma_f32_16x16x32_bf16 v[82:85], v[180:183], v[204:207], v[82:85]
	v_mfma_f32_16x16x32_bf16 v[66:69], v[180:183], v[212:215], v[66:69]
	v_mfma_f32_16x16x32_bf16 v[122:125], v[176:179], v[192:195], v[122:125]
	v_mfma_f32_16x16x32_bf16 v[102:105], v[176:179], v[200:203], v[102:105]
	v_mfma_f32_16x16x32_bf16 v[86:89], v[176:179], v[208:211], v[86:89]
	v_mfma_f32_16x16x32_bf16 v[70:73], v[176:179], v[216:219], v[70:73]
	v_mfma_f32_16x16x32_bf16 v[114:117], v[184:187], v[192:195], v[114:117]
	v_mfma_f32_16x16x32_bf16 v[98:101], v[184:187], v[200:203], v[98:101]
	v_mfma_f32_16x16x32_bf16 v[82:85], v[184:187], v[208:211], v[82:85]
	v_mfma_f32_16x16x32_bf16 v[66:69], v[184:187], v[216:219], v[66:69]
	s_setprio 0
	s_barrier
	s_add_i32 s0, s52, s36
	v_lshl_add_u64 v[220:221], v[220:221], 0, s[14:15]
	s_mov_b32 m0, s0
	ds_read_b128 v[188:191], v169 offset:49152
	ds_read_b128 v[192:195], v169 offset:50176
	ds_read_b128 v[196:199], v169 offset:51200
	ds_read_b128 v[200:203], v169 offset:52224
	ds_read_b128 v[204:207], v169 offset:53248
	ds_read_b128 v[208:211], v169 offset:54272
	ds_read_b128 v[212:215], v169 offset:55296
	ds_read_b128 v[216:219], v169 offset:56320
	global_load_lds_dwordx4 v[220:221], off
	s_add_i32 m0, s0, 0x2000
	s_add_u32 s0, s2, 0x40080
	v_lshl_add_u64 v[220:221], v[222:223], 0, s[14:15]
	s_addc_u32 s1, s3, 0
	s_add_i32 s2, s53, s36
	global_load_lds_dwordx4 v[220:221], off
	v_lshl_add_u64 v[220:221], s[0:1], 0, v[132:133]
	s_mov_b32 m0, s2
	s_nop 0
	global_load_lds_dwordx4 v[220:221], off
	v_lshl_add_u64 v[220:221], s[0:1], 0, v[136:137]
	s_add_i32 m0, s2, 0x2000
	s_nop 0
	global_load_lds_dwordx4 v[220:221], off
	v_lshl_add_u64 v[220:221], v[224:225], 0, s[14:15]
	s_mov_b32 m0, s40
	s_nop 0
	global_load_lds_dwordx4 v[220:221], off
	v_lshl_add_u64 v[220:221], v[226:227], 0, s[14:15]
	s_mov_b32 m0, s41
	s_nop 0
	global_load_lds_dwordx4 v[220:221], off
	s_waitcnt vmcnt(8)
	s_waitcnt lgkmcnt(0)
	s_barrier
	s_setprio 1
	s_waitcnt lgkmcnt(0)
	v_mfma_f32_16x16x32_bf16 v[62:65], v[148:151], v[188:191], v[62:65]
	v_mfma_f32_16x16x32_bf16 v[46:49], v[148:151], v[196:199], v[46:49]
	v_mfma_f32_16x16x32_bf16 v[30:33], v[148:151], v[204:207], v[30:33]
	v_mfma_f32_16x16x32_bf16 v[14:17], v[148:151], v[212:215], v[14:17]
	v_mfma_f32_16x16x32_bf16 v[58:61], v[156:159], v[188:191], v[58:61]
	v_mfma_f32_16x16x32_bf16 v[42:45], v[156:159], v[196:199], v[42:45]
	v_mfma_f32_16x16x32_bf16 v[26:29], v[156:159], v[204:207], v[26:29]
	v_mfma_f32_16x16x32_bf16 v[10:13], v[156:159], v[212:215], v[10:13]
	v_mfma_f32_16x16x32_bf16 v[62:65], v[152:155], v[192:195], v[62:65]
	v_mfma_f32_16x16x32_bf16 v[46:49], v[152:155], v[200:203], v[46:49]
	v_mfma_f32_16x16x32_bf16 v[30:33], v[152:155], v[208:211], v[30:33]
	v_mfma_f32_16x16x32_bf16 v[14:17], v[152:155], v[216:219], v[14:17]
	v_mfma_f32_16x16x32_bf16 v[58:61], v[160:163], v[192:195], v[58:61]
	v_mfma_f32_16x16x32_bf16 v[42:45], v[160:163], v[200:203], v[42:45]
	v_mfma_f32_16x16x32_bf16 v[26:29], v[160:163], v[208:211], v[26:29]
	v_mfma_f32_16x16x32_bf16 v[10:13], v[160:163], v[216:219], v[10:13]
	s_setprio 0
	s_setprio 1
	v_mfma_f32_16x16x32_bf16 v[54:57], v[172:175], v[188:191], v[54:57]
	v_mfma_f32_16x16x32_bf16 v[38:41], v[172:175], v[196:199], v[38:41]
	v_mfma_f32_16x16x32_bf16 v[22:25], v[172:175], v[204:207], v[22:25]
	v_mfma_f32_16x16x32_bf16 v[6:9], v[172:175], v[212:215], v[6:9]
	v_mfma_f32_16x16x32_bf16 v[50:53], v[180:183], v[188:191], v[50:53]
	v_mfma_f32_16x16x32_bf16 v[34:37], v[180:183], v[196:199], v[34:37]
	v_mfma_f32_16x16x32_bf16 v[18:21], v[180:183], v[204:207], v[18:21]
	v_mfma_f32_16x16x32_bf16 v[2:5], v[180:183], v[212:215], v[2:5]
	v_mfma_f32_16x16x32_bf16 v[54:57], v[176:179], v[192:195], v[54:57]
	v_mfma_f32_16x16x32_bf16 v[38:41], v[176:179], v[200:203], v[38:41]
	v_mfma_f32_16x16x32_bf16 v[22:25], v[176:179], v[208:211], v[22:25]
	v_mfma_f32_16x16x32_bf16 v[6:9], v[176:179], v[216:219], v[6:9]
	v_mfma_f32_16x16x32_bf16 v[50:53], v[184:187], v[192:195], v[50:53]
	v_mfma_f32_16x16x32_bf16 v[34:37], v[184:187], v[200:203], v[34:37]
	v_mfma_f32_16x16x32_bf16 v[18:21], v[184:187], v[208:211], v[18:21]
	v_mfma_f32_16x16x32_bf16 v[2:5], v[184:187], v[216:219], v[2:5]
	s_setprio 0
	s_barrier
	s_add_i32 s51, s51, 2
	s_add_u32 s28, s28, 0x100
	s_addc_u32 s29, s29, 0
	s_add_u32 s49, s49, 0x100
	s_addc_u32 s50, s50, 0
	s_cmp_gt_u32 s51, 13
	s_cbranch_scc0 .LBB0_202
	s_and_b64 vcc, exec, s[16:17]
	s_cbranch_vccz .LBB0_205
	s_barrier

.LBB0_283:
	ds_read_b128 v[114:117], v228
	ds_read_b128 v[118:121], v228 offset:1024
	ds_read_b128 v[122:125], v228 offset:2048
	ds_read_b128 v[126:129], v228 offset:3072
	ds_read_b128 v[146:149], v229
	ds_read_b128 v[150:153], v229 offset:1024
	ds_read_b128 v[154:157], v229 offset:2048
	ds_read_b128 v[158:161], v229 offset:3072
	s_add_u32 s0, s10, 0xfffc0080
	s_addc_u32 s1, s11, -1
	s_cmp_eq_u32 s51, 12
	s_cselect_b32 s13, s7, s1
	s_cselect_b32 s12, s9, s0
	s_cselect_b32 s3, s27, s37
	s_cselect_b32 s2, s29, s36
	v_lshl_add_u64 v[212:213], s[10:11], 0, v[180:181]
	s_add_i32 m0, s40, 0xc000
	ds_read_b128 v[162:165], v230
	ds_read_b128 v[166:169], v230 offset:1024
	ds_read_b128 v[188:191], v230 offset:2048
	ds_read_b128 v[192:195], v230 offset:3072
	ds_read_b128 v[196:199], v230 offset:4096
	ds_read_b128 v[200:203], v230 offset:5120
	ds_read_b128 v[204:207], v230 offset:6144
	ds_read_b128 v[208:211], v230 offset:7168
	global_load_lds_dwordx4 v[212:213], off
	v_lshl_add_u64 v[212:213], s[10:11], 0, v[182:183]
	s_add_i32 m0, s40, 0xe000
	s_nop 0
	global_load_lds_dwordx4 v[212:213], off
	s_waitcnt vmcnt(8)
	s_waitcnt lgkmcnt(0)
	s_barrier
	s_setprio 1
	s_waitcnt lgkmcnt(0)
	v_mfma_f32_16x16x32_bf16 v[142:145], v[114:117], v[162:165], v[142:145]
	v_mfma_f32_16x16x32_bf16 v[134:137], v[114:117], v[188:191], v[134:137]
	v_mfma_f32_16x16x32_bf16 v[110:113], v[114:117], v[196:199], v[110:113]
	v_mfma_f32_16x16x32_bf16 v[102:105], v[114:117], v[204:207], v[102:105]
	v_mfma_f32_16x16x32_bf16 v[138:141], v[122:125], v[162:165], v[138:141]
	v_mfma_f32_16x16x32_bf16 v[130:133], v[122:125], v[188:191], v[130:133]
	v_mfma_f32_16x16x32_bf16 v[106:109], v[122:125], v[196:199], v[106:109]
	v_mfma_f32_16x16x32_bf16 v[98:101], v[122:125], v[204:207], v[98:101]
	v_mfma_f32_16x16x32_bf16 v[142:145], v[118:121], v[166:169], v[142:145]
	v_mfma_f32_16x16x32_bf16 v[134:137], v[118:121], v[192:195], v[134:137]
	v_mfma_f32_16x16x32_bf16 v[110:113], v[118:121], v[200:203], v[110:113]
	v_mfma_f32_16x16x32_bf16 v[102:105], v[118:121], v[208:211], v[102:105]
	v_mfma_f32_16x16x32_bf16 v[138:141], v[126:129], v[166:169], v[138:141]
	v_mfma_f32_16x16x32_bf16 v[130:133], v[126:129], v[192:195], v[130:133]
	v_mfma_f32_16x16x32_bf16 v[106:109], v[126:129], v[200:203], v[106:109]
	v_mfma_f32_16x16x32_bf16 v[98:101], v[126:129], v[208:211], v[98:101]
	s_setprio 0
	s_setprio 1
	v_mfma_f32_16x16x32_bf16 v[62:65], v[146:149], v[162:165], v[62:65]
	v_mfma_f32_16x16x32_bf16 v[54:57], v[146:149], v[188:191], v[54:57]
	v_mfma_f32_16x16x32_bf16 v[46:49], v[146:149], v[196:199], v[46:49]
	v_mfma_f32_16x16x32_bf16 v[38:41], v[146:149], v[204:207], v[38:41]
	v_mfma_f32_16x16x32_bf16 v[58:61], v[154:157], v[162:165], v[58:61]
	v_mfma_f32_16x16x32_bf16 v[50:53], v[154:157], v[188:191], v[50:53]
	v_mfma_f32_16x16x32_bf16 v[42:45], v[154:157], v[196:199], v[42:45]
	v_mfma_f32_16x16x32_bf16 v[34:37], v[154:157], v[204:207], v[34:37]
	v_mfma_f32_16x16x32_bf16 v[62:65], v[150:153], v[166:169], v[62:65]
	v_mfma_f32_16x16x32_bf16 v[54:57], v[150:153], v[192:195], v[54:57]
	v_mfma_f32_16x16x32_bf16 v[46:49], v[150:153], v[200:203], v[46:49]
	v_mfma_f32_16x16x32_bf16 v[38:41], v[150:153], v[208:211], v[38:41]
	v_mfma_f32_16x16x32_bf16 v[58:61], v[158:161], v[166:169], v[58:61]
	v_mfma_f32_16x16x32_bf16 v[50:53], v[158:161], v[192:195], v[50:53]
	v_mfma_f32_16x16x32_bf16 v[42:45], v[158:161], v[200:203], v[42:45]
	v_mfma_f32_16x16x32_bf16 v[34:37], v[158:161], v[208:211], v[34:37]
	s_setprio 0
	s_barrier
	s_add_i32 s0, s49, s39
	v_lshl_add_u64 v[212:213], s[2:3], 0, v[172:173]
	s_mov_b32 m0, s0
	ds_read_b128 v[162:165], v230 offset:16384
	ds_read_b128 v[166:169], v230 offset:17408
	ds_read_b128 v[188:191], v230 offset:18432
	ds_read_b128 v[192:195], v230 offset:19456
	ds_read_b128 v[196:199], v230 offset:20480
	ds_read_b128 v[200:203], v230 offset:21504
	ds_read_b128 v[204:207], v230 offset:22528
	ds_read_b128 v[208:211], v230 offset:23552
	global_load_lds_dwordx4 v[212:213], off
	s_add_i32 m0, s0, 0x2000
	s_add_u32 s0, s2, 0x40000
	v_lshl_add_u64 v[214:215], s[2:3], 0, v[176:177]
	s_addc_u32 s1, s3, 0
	s_add_i32 s52, s50, s39
	global_load_lds_dwordx4 v[214:215], off
	v_lshl_add_u64 v[216:217], s[0:1], 0, v[172:173]
	s_mov_b32 m0, s52
	v_lshl_add_u64 v[218:219], s[12:13], 0, v[174:175]
	global_load_lds_dwordx4 v[216:217], off
	v_lshl_add_u64 v[216:217], s[0:1], 0, v[176:177]
	s_add_i32 m0, s52, 0x2000
	s_nop 0
	global_load_lds_dwordx4 v[216:217], off
	v_lshl_add_u64 v[216:217], s[12:13], 0, v[170:171]
	s_mov_b32 m0, s40
	s_nop 0
	global_load_lds_dwordx4 v[216:217], off
	s_mov_b32 m0, s41
	s_nop 0
	global_load_lds_dwordx4 v[218:219], off
	s_waitcnt vmcnt(8)
	s_waitcnt lgkmcnt(0)
	s_barrier
	s_setprio 1
	s_waitcnt lgkmcnt(0)
	v_mfma_f32_16x16x32_bf16 v[94:97], v[114:117], v[162:165], v[94:97]
	v_mfma_f32_16x16x32_bf16 v[86:89], v[114:117], v[188:191], v[86:89]
	v_mfma_f32_16x16x32_bf16 v[78:81], v[114:117], v[196:199], v[78:81]
	v_mfma_f32_16x16x32_bf16 v[70:73], v[114:117], v[204:207], v[70:73]
	v_mfma_f32_16x16x32_bf16 v[90:93], v[122:125], v[162:165], v[90:93]
	v_mfma_f32_16x16x32_bf16 v[82:85], v[122:125], v[188:191], v[82:85]
	v_mfma_f32_16x16x32_bf16 v[74:77], v[122:125], v[196:199], v[74:77]
	v_mfma_f32_16x16x32_bf16 v[66:69], v[122:125], v[204:207], v[66:69]
	v_mfma_f32_16x16x32_bf16 v[94:97], v[118:121], v[166:169], v[94:97]
	v_mfma_f32_16x16x32_bf16 v[86:89], v[118:121], v[192:195], v[86:89]
	v_mfma_f32_16x16x32_bf16 v[78:81], v[118:121], v[200:203], v[78:81]
	v_mfma_f32_16x16x32_bf16 v[70:73], v[118:121], v[208:211], v[70:73]
	v_mfma_f32_16x16x32_bf16 v[90:93], v[126:129], v[166:169], v[90:93]
	v_mfma_f32_16x16x32_bf16 v[82:85], v[126:129], v[192:195], v[82:85]
	v_mfma_f32_16x16x32_bf16 v[74:77], v[126:129], v[200:203], v[74:77]
	v_mfma_f32_16x16x32_bf16 v[66:69], v[126:129], v[208:211], v[66:69]
	s_setprio 0
	s_setprio 1
	v_mfma_f32_16x16x32_bf16 v[30:33], v[146:149], v[162:165], v[30:33]
	v_mfma_f32_16x16x32_bf16 v[22:25], v[146:149], v[188:191], v[22:25]
	v_mfma_f32_16x16x32_bf16 v[14:17], v[146:149], v[196:199], v[14:17]
	v_mfma_f32_16x16x32_bf16 v[6:9], v[146:149], v[204:207], v[6:9]
	v_mfma_f32_16x16x32_bf16 v[26:29], v[154:157], v[162:165], v[26:29]
	v_mfma_f32_16x16x32_bf16 v[18:21], v[154:157], v[188:191], v[18:21]
	v_mfma_f32_16x16x32_bf16 v[10:13], v[154:157], v[196:199], v[10:13]
	v_mfma_f32_16x16x32_bf16 v[2:5], v[154:157], v[204:207], v[2:5]
	v_mfma_f32_16x16x32_bf16 v[30:33], v[150:153], v[166:169], v[30:33]
	v_mfma_f32_16x16x32_bf16 v[22:25], v[150:153], v[192:195], v[22:25]
	v_mfma_f32_16x16x32_bf16 v[14:17], v[150:153], v[200:203], v[14:17]
	v_mfma_f32_16x16x32_bf16 v[6:9], v[150:153], v[208:211], v[6:9]
	v_mfma_f32_16x16x32_bf16 v[26:29], v[158:161], v[166:169], v[26:29]
	v_mfma_f32_16x16x32_bf16 v[18:21], v[158:161], v[192:195], v[18:21]
	v_mfma_f32_16x16x32_bf16 v[10:13], v[158:161], v[200:203], v[10:13]
	v_mfma_f32_16x16x32_bf16 v[2:5], v[158:161], v[208:211], v[2:5]
	s_setprio 0
	s_barrier
	s_add_i32 s52, 0, 0x18000
	s_add_i32 s53, 0, 0x1c000
	v_add_u32_e32 v126, s52, v223
	v_add_u32_e32 v158, s53, v223
	ds_read_b128 v[114:117], v126
	ds_read_b128 v[118:121], v126 offset:1024
	ds_read_b128 v[122:125], v126 offset:2048
	ds_read_b128 v[126:129], v126 offset:3072
	ds_read_b128 v[146:149], v158
	ds_read_b128 v[150:153], v158 offset:1024
	ds_read_b128 v[154:157], v158 offset:2048
	ds_read_b128 v[158:161], v158 offset:3072
	s_add_u32 s0, s12, 0x40000
	s_addc_u32 s1, s13, 0
	s_mov_b32 m0, s42
	v_lshl_add_u64 v[220:221], s[0:1], 0, v[170:171]
	ds_read_b128 v[162:165], v230 offset:32768
	ds_read_b128 v[166:169], v230 offset:33792
	ds_read_b128 v[188:191], v230 offset:34816
	ds_read_b128 v[192:195], v230 offset:35840
	ds_read_b128 v[196:199], v230 offset:36864
	ds_read_b128 v[200:203], v230 offset:37888
	ds_read_b128 v[204:207], v230 offset:38912
	ds_read_b128 v[208:211], v230 offset:39936
	global_load_lds_dwordx4 v[220:221], off
	v_lshl_add_u64 v[220:221], s[0:1], 0, v[174:175]
	s_mov_b32 m0, s43
	s_nop 0
	global_load_lds_dwordx4 v[220:221], off
	s_waitcnt vmcnt(8)
	s_waitcnt lgkmcnt(0)
	s_barrier
	s_setprio 1
	s_waitcnt lgkmcnt(0)
	v_mfma_f32_16x16x32_bf16 v[142:145], v[114:117], v[162:165], v[142:145]
	v_mfma_f32_16x16x32_bf16 v[134:137], v[114:117], v[188:191], v[134:137]
	v_mfma_f32_16x16x32_bf16 v[110:113], v[114:117], v[196:199], v[110:113]
	v_mfma_f32_16x16x32_bf16 v[102:105], v[114:117], v[204:207], v[102:105]
	v_mfma_f32_16x16x32_bf16 v[138:141], v[122:125], v[162:165], v[138:141]
	v_mfma_f32_16x16x32_bf16 v[130:133], v[122:125], v[188:191], v[130:133]
	v_mfma_f32_16x16x32_bf16 v[106:109], v[122:125], v[196:199], v[106:109]
	v_mfma_f32_16x16x32_bf16 v[98:101], v[122:125], v[204:207], v[98:101]
	v_mfma_f32_16x16x32_bf16 v[142:145], v[118:121], v[166:169], v[142:145]
	v_mfma_f32_16x16x32_bf16 v[134:137], v[118:121], v[192:195], v[134:137]
	v_mfma_f32_16x16x32_bf16 v[110:113], v[118:121], v[200:203], v[110:113]
	v_mfma_f32_16x16x32_bf16 v[102:105], v[118:121], v[208:211], v[102:105]
	v_mfma_f32_16x16x32_bf16 v[138:141], v[126:129], v[166:169], v[138:141]
	v_mfma_f32_16x16x32_bf16 v[130:133], v[126:129], v[192:195], v[130:133]
	v_mfma_f32_16x16x32_bf16 v[106:109], v[126:129], v[200:203], v[106:109]
	v_mfma_f32_16x16x32_bf16 v[98:101], v[126:129], v[208:211], v[98:101]
	s_setprio 0
	s_setprio 1
	v_mfma_f32_16x16x32_bf16 v[62:65], v[146:149], v[162:165], v[62:65]
	v_mfma_f32_16x16x32_bf16 v[54:57], v[146:149], v[188:191], v[54:57]
	v_mfma_f32_16x16x32_bf16 v[46:49], v[146:149], v[196:199], v[46:49]
	v_mfma_f32_16x16x32_bf16 v[38:41], v[146:149], v[204:207], v[38:41]
	v_mfma_f32_16x16x32_bf16 v[58:61], v[154:157], v[162:165], v[58:61]
	v_mfma_f32_16x16x32_bf16 v[50:53], v[154:157], v[188:191], v[50:53]
	v_mfma_f32_16x16x32_bf16 v[42:45], v[154:157], v[196:199], v[42:45]
	v_mfma_f32_16x16x32_bf16 v[34:37], v[154:157], v[204:207], v[34:37]
	v_mfma_f32_16x16x32_bf16 v[62:65], v[150:153], v[166:169], v[62:65]
	v_mfma_f32_16x16x32_bf16 v[54:57], v[150:153], v[192:195], v[54:57]
	v_mfma_f32_16x16x32_bf16 v[46:49], v[150:153], v[200:203], v[46:49]
	v_mfma_f32_16x16x32_bf16 v[38:41], v[150:153], v[208:211], v[38:41]
	v_mfma_f32_16x16x32_bf16 v[58:61], v[158:161], v[166:169], v[58:61]
	v_mfma_f32_16x16x32_bf16 v[50:53], v[158:161], v[192:195], v[50:53]
	v_mfma_f32_16x16x32_bf16 v[42:45], v[158:161], v[200:203], v[42:45]
	v_mfma_f32_16x16x32_bf16 v[34:37], v[158:161], v[208:211], v[34:37]
	s_setprio 0
	s_barrier
	s_add_i32 s0, s52, s39
	v_lshl_add_u64 v[212:213], v[212:213], 0, s[22:23]
	s_mov_b32 m0, s0
	ds_read_b128 v[162:165], v230 offset:49152
	ds_read_b128 v[166:169], v230 offset:50176
	ds_read_b128 v[188:191], v230 offset:51200
	ds_read_b128 v[192:195], v230 offset:52224
	ds_read_b128 v[196:199], v230 offset:53248
	ds_read_b128 v[200:203], v230 offset:54272
	ds_read_b128 v[204:207], v230 offset:55296
	ds_read_b128 v[208:211], v230 offset:56320
	global_load_lds_dwordx4 v[212:213], off
	s_add_i32 m0, s0, 0x2000
	s_add_u32 s0, s2, 0x40080
	v_lshl_add_u64 v[212:213], v[214:215], 0, s[22:23]
	s_addc_u32 s1, s3, 0
	s_add_i32 s2, s53, s39
	global_load_lds_dwordx4 v[212:213], off
	v_lshl_add_u64 v[212:213], s[0:1], 0, v[172:173]
	s_mov_b32 m0, s2
	s_nop 0
	global_load_lds_dwordx4 v[212:213], off
	v_lshl_add_u64 v[212:213], s[0:1], 0, v[176:177]
	s_add_i32 m0, s2, 0x2000
	s_nop 0
	global_load_lds_dwordx4 v[212:213], off
	v_lshl_add_u64 v[212:213], v[216:217], 0, s[22:23]
	s_mov_b32 m0, s45
	s_nop 0
	global_load_lds_dwordx4 v[212:213], off
	v_lshl_add_u64 v[212:213], v[218:219], 0, s[22:23]
	s_mov_b32 m0, s46
	s_nop 0
	global_load_lds_dwordx4 v[212:213], off
	s_waitcnt vmcnt(8)
	s_waitcnt lgkmcnt(0)
	s_barrier
	s_setprio 1
	s_waitcnt lgkmcnt(0)
	v_mfma_f32_16x16x32_bf16 v[94:97], v[114:117], v[162:165], v[94:97]
	v_mfma_f32_16x16x32_bf16 v[86:89], v[114:117], v[188:191], v[86:89]
	v_mfma_f32_16x16x32_bf16 v[78:81], v[114:117], v[196:199], v[78:81]
	v_mfma_f32_16x16x32_bf16 v[70:73], v[114:117], v[204:207], v[70:73]
	v_mfma_f32_16x16x32_bf16 v[90:93], v[122:125], v[162:165], v[90:93]
	v_mfma_f32_16x16x32_bf16 v[82:85], v[122:125], v[188:191], v[82:85]
	v_mfma_f32_16x16x32_bf16 v[74:77], v[122:125], v[196:199], v[74:77]
	v_mfma_f32_16x16x32_bf16 v[66:69], v[122:125], v[204:207], v[66:69]
	v_mfma_f32_16x16x32_bf16 v[94:97], v[118:121], v[166:169], v[94:97]
	v_mfma_f32_16x16x32_bf16 v[86:89], v[118:121], v[192:195], v[86:89]
	v_mfma_f32_16x16x32_bf16 v[78:81], v[118:121], v[200:203], v[78:81]
	v_mfma_f32_16x16x32_bf16 v[70:73], v[118:121], v[208:211], v[70:73]
	v_mfma_f32_16x16x32_bf16 v[90:93], v[126:129], v[166:169], v[90:93]
	v_mfma_f32_16x16x32_bf16 v[82:85], v[126:129], v[192:195], v[82:85]
	v_mfma_f32_16x16x32_bf16 v[74:77], v[126:129], v[200:203], v[74:77]
	v_mfma_f32_16x16x32_bf16 v[66:69], v[126:129], v[208:211], v[66:69]
	s_setprio 0
	s_setprio 1
	v_mfma_f32_16x16x32_bf16 v[30:33], v[146:149], v[162:165], v[30:33]
	v_mfma_f32_16x16x32_bf16 v[22:25], v[146:149], v[188:191], v[22:25]
	v_mfma_f32_16x16x32_bf16 v[14:17], v[146:149], v[196:199], v[14:17]
	v_mfma_f32_16x16x32_bf16 v[6:9], v[146:149], v[204:207], v[6:9]
	v_mfma_f32_16x16x32_bf16 v[26:29], v[154:157], v[162:165], v[26:29]
	v_mfma_f32_16x16x32_bf16 v[18:21], v[154:157], v[188:191], v[18:21]
	v_mfma_f32_16x16x32_bf16 v[10:13], v[154:157], v[196:199], v[10:13]
	v_mfma_f32_16x16x32_bf16 v[2:5], v[154:157], v[204:207], v[2:5]
	v_mfma_f32_16x16x32_bf16 v[30:33], v[150:153], v[166:169], v[30:33]
	v_mfma_f32_16x16x32_bf16 v[22:25], v[150:153], v[192:195], v[22:25]
	v_mfma_f32_16x16x32_bf16 v[14:17], v[150:153], v[200:203], v[14:17]
	v_mfma_f32_16x16x32_bf16 v[6:9], v[150:153], v[208:211], v[6:9]
	v_mfma_f32_16x16x32_bf16 v[26:29], v[158:161], v[166:169], v[26:29]
	v_mfma_f32_16x16x32_bf16 v[18:21], v[158:161], v[192:195], v[18:21]
	v_mfma_f32_16x16x32_bf16 v[10:13], v[158:161], v[200:203], v[10:13]
	v_mfma_f32_16x16x32_bf16 v[2:5], v[158:161], v[208:211], v[2:5]
	s_setprio 0
	s_barrier
	s_add_i32 s51, s51, 2
	s_add_u32 s10, s10, 0x100
	s_addc_u32 s11, s11, 0
	s_add_u32 s36, s36, 0x100
	s_addc_u32 s37, s37, 0
	s_cmp_gt_u32 s51, 13
	s_cbranch_scc0 .LBB0_283
	s_and_b64 vcc, exec, s[24:25]
	s_cbranch_vccz .LBB0_286
	s_barrier

.LBB0_382:
	ds_read_b128 v[130:133], v211
	ds_read_b128 v[134:137], v211 offset:1024
	ds_read_b128 v[138:141], v211 offset:2048
	ds_read_b128 v[142:145], v211 offset:3072
	ds_read_b128 v[146:149], v212
	ds_read_b128 v[150:153], v212 offset:1024
	ds_read_b128 v[154:157], v212 offset:2048
	ds_read_b128 v[158:161], v212 offset:3072
	s_add_u32 s0, s28, 0xfffc0080
	s_addc_u32 s1, s29, -1
	s_cmp_eq_u32 s51, 12
	s_cselect_b32 s31, s11, s1
	s_cselect_b32 s30, s21, s0
	s_cselect_b32 s3, s19, s50
	s_cselect_b32 s2, s48, s49
	v_lshl_add_u64 v[220:221], s[28:29], 0, v[186:187]
	s_add_i32 m0, s27, 0xc000
	ds_read_b128 v[162:165], v213
	ds_read_b128 v[166:169], v213 offset:1024
	ds_read_b128 v[170:173], v213 offset:2048
	ds_read_b128 v[174:177], v213 offset:3072
	ds_read_b128 v[194:197], v213 offset:4096
	ds_read_b128 v[198:201], v213 offset:5120
	ds_read_b128 v[202:205], v213 offset:6144
	ds_read_b128 v[216:219], v213 offset:7168
	global_load_lds_dwordx4 v[220:221], off
	v_lshl_add_u64 v[220:221], s[28:29], 0, v[188:189]
	s_add_i32 m0, s27, 0xe000
	s_nop 0
	global_load_lds_dwordx4 v[220:221], off
	s_waitcnt vmcnt(8)
	s_waitcnt lgkmcnt(0)
	s_barrier
	s_setprio 1
	s_waitcnt lgkmcnt(0)
	v_mfma_f32_16x16x32_bf16 v[126:129], v[130:133], v[162:165], v[126:129]
	v_mfma_f32_16x16x32_bf16 v[110:113], v[130:133], v[170:173], v[110:113]
	v_mfma_f32_16x16x32_bf16 v[94:97], v[130:133], v[194:197], v[94:97]
	v_mfma_f32_16x16x32_bf16 v[78:81], v[130:133], v[202:205], v[78:81]
	v_mfma_f32_16x16x32_bf16 v[122:125], v[138:141], v[162:165], v[122:125]
	v_mfma_f32_16x16x32_bf16 v[106:109], v[138:141], v[170:173], v[106:109]
	v_mfma_f32_16x16x32_bf16 v[90:93], v[138:141], v[194:197], v[90:93]
	v_mfma_f32_16x16x32_bf16 v[74:77], v[138:141], v[202:205], v[74:77]
	v_mfma_f32_16x16x32_bf16 v[126:129], v[134:137], v[166:169], v[126:129]
	v_mfma_f32_16x16x32_bf16 v[110:113], v[134:137], v[174:177], v[110:113]
	v_mfma_f32_16x16x32_bf16 v[94:97], v[134:137], v[198:201], v[94:97]
	v_mfma_f32_16x16x32_bf16 v[78:81], v[134:137], v[216:219], v[78:81]
	v_mfma_f32_16x16x32_bf16 v[122:125], v[142:145], v[166:169], v[122:125]
	v_mfma_f32_16x16x32_bf16 v[106:109], v[142:145], v[174:177], v[106:109]
	v_mfma_f32_16x16x32_bf16 v[90:93], v[142:145], v[198:201], v[90:93]
	v_mfma_f32_16x16x32_bf16 v[74:77], v[142:145], v[216:219], v[74:77]
	s_setprio 0
	s_setprio 1
	v_mfma_f32_16x16x32_bf16 v[118:121], v[146:149], v[162:165], v[118:121]
	v_mfma_f32_16x16x32_bf16 v[102:105], v[146:149], v[170:173], v[102:105]
	v_mfma_f32_16x16x32_bf16 v[86:89], v[146:149], v[194:197], v[86:89]
	v_mfma_f32_16x16x32_bf16 v[70:73], v[146:149], v[202:205], v[70:73]
	v_mfma_f32_16x16x32_bf16 v[114:117], v[154:157], v[162:165], v[114:117]
	v_mfma_f32_16x16x32_bf16 v[98:101], v[154:157], v[170:173], v[98:101]
	v_mfma_f32_16x16x32_bf16 v[82:85], v[154:157], v[194:197], v[82:85]
	v_mfma_f32_16x16x32_bf16 v[66:69], v[154:157], v[202:205], v[66:69]
	v_mfma_f32_16x16x32_bf16 v[118:121], v[150:153], v[166:169], v[118:121]
	v_mfma_f32_16x16x32_bf16 v[102:105], v[150:153], v[174:177], v[102:105]
	v_mfma_f32_16x16x32_bf16 v[86:89], v[150:153], v[198:201], v[86:89]
	v_mfma_f32_16x16x32_bf16 v[70:73], v[150:153], v[216:219], v[70:73]
	v_mfma_f32_16x16x32_bf16 v[114:117], v[158:161], v[166:169], v[114:117]
	v_mfma_f32_16x16x32_bf16 v[98:101], v[158:161], v[174:177], v[98:101]
	v_mfma_f32_16x16x32_bf16 v[82:85], v[158:161], v[198:201], v[82:85]
	v_mfma_f32_16x16x32_bf16 v[66:69], v[158:161], v[216:219], v[66:69]
	s_setprio 0
	s_barrier
	s_add_i32 s0, s46, s37
	v_lshl_add_u64 v[220:221], s[2:3], 0, v[180:181]
	s_mov_b32 m0, s0
	ds_read_b128 v[162:165], v213 offset:16384
	ds_read_b128 v[166:169], v213 offset:17408
	ds_read_b128 v[170:173], v213 offset:18432
	ds_read_b128 v[174:177], v213 offset:19456
	ds_read_b128 v[194:197], v213 offset:20480
	ds_read_b128 v[198:201], v213 offset:21504
	ds_read_b128 v[202:205], v213 offset:22528
	ds_read_b128 v[216:219], v213 offset:23552
	global_load_lds_dwordx4 v[220:221], off
	s_add_i32 m0, s0, 0x2000
	s_add_u32 s0, s2, 0x40000
	v_lshl_add_u64 v[222:223], s[2:3], 0, v[184:185]
	s_addc_u32 s1, s3, 0
	s_add_i32 s52, s47, s37
	global_load_lds_dwordx4 v[222:223], off
	v_lshl_add_u64 v[224:225], s[0:1], 0, v[180:181]
	s_mov_b32 m0, s52
	v_lshl_add_u64 v[226:227], s[30:31], 0, v[182:183]
	global_load_lds_dwordx4 v[224:225], off
	v_lshl_add_u64 v[224:225], s[0:1], 0, v[184:185]
	s_add_i32 m0, s52, 0x2000
	s_nop 0
	global_load_lds_dwordx4 v[224:225], off
	v_lshl_add_u64 v[224:225], s[30:31], 0, v[178:179]
	s_mov_b32 m0, s27
	s_nop 0
	global_load_lds_dwordx4 v[224:225], off
	s_mov_b32 m0, s38
	s_nop 0
	global_load_lds_dwordx4 v[226:227], off
	s_waitcnt vmcnt(8)
	s_waitcnt lgkmcnt(0)
	s_barrier
	s_setprio 1
	s_waitcnt lgkmcnt(0)
	v_mfma_f32_16x16x32_bf16 v[62:65], v[130:133], v[162:165], v[62:65]
	v_mfma_f32_16x16x32_bf16 v[46:49], v[130:133], v[170:173], v[46:49]
	v_mfma_f32_16x16x32_bf16 v[30:33], v[130:133], v[194:197], v[30:33]
	v_mfma_f32_16x16x32_bf16 v[14:17], v[130:133], v[202:205], v[14:17]
	v_mfma_f32_16x16x32_bf16 v[58:61], v[138:141], v[162:165], v[58:61]
	v_mfma_f32_16x16x32_bf16 v[42:45], v[138:141], v[170:173], v[42:45]
	v_mfma_f32_16x16x32_bf16 v[26:29], v[138:141], v[194:197], v[26:29]
	v_mfma_f32_16x16x32_bf16 v[10:13], v[138:141], v[202:205], v[10:13]
	v_mfma_f32_16x16x32_bf16 v[62:65], v[134:137], v[166:169], v[62:65]
	v_mfma_f32_16x16x32_bf16 v[46:49], v[134:137], v[174:177], v[46:49]
	v_mfma_f32_16x16x32_bf16 v[30:33], v[134:137], v[198:201], v[30:33]
	v_mfma_f32_16x16x32_bf16 v[14:17], v[134:137], v[216:219], v[14:17]
	v_mfma_f32_16x16x32_bf16 v[58:61], v[142:145], v[166:169], v[58:61]
	v_mfma_f32_16x16x32_bf16 v[42:45], v[142:145], v[174:177], v[42:45]
	v_mfma_f32_16x16x32_bf16 v[26:29], v[142:145], v[198:201], v[26:29]
	v_mfma_f32_16x16x32_bf16 v[10:13], v[142:145], v[216:219], v[10:13]
	s_setprio 0
	s_setprio 1
	v_mfma_f32_16x16x32_bf16 v[54:57], v[146:149], v[162:165], v[54:57]
	v_mfma_f32_16x16x32_bf16 v[38:41], v[146:149], v[170:173], v[38:41]
	v_mfma_f32_16x16x32_bf16 v[22:25], v[146:149], v[194:197], v[22:25]
	v_mfma_f32_16x16x32_bf16 v[6:9], v[146:149], v[202:205], v[6:9]
	v_mfma_f32_16x16x32_bf16 v[50:53], v[154:157], v[162:165], v[50:53]
	v_mfma_f32_16x16x32_bf16 v[34:37], v[154:157], v[170:173], v[34:37]
	v_mfma_f32_16x16x32_bf16 v[18:21], v[154:157], v[194:197], v[18:21]
	v_mfma_f32_16x16x32_bf16 v[2:5], v[154:157], v[202:205], v[2:5]
	v_mfma_f32_16x16x32_bf16 v[54:57], v[150:153], v[166:169], v[54:57]
	v_mfma_f32_16x16x32_bf16 v[38:41], v[150:153], v[174:177], v[38:41]
	v_mfma_f32_16x16x32_bf16 v[22:25], v[150:153], v[198:201], v[22:25]
	v_mfma_f32_16x16x32_bf16 v[6:9], v[150:153], v[216:219], v[6:9]
	v_mfma_f32_16x16x32_bf16 v[50:53], v[158:161], v[166:169], v[50:53]
	v_mfma_f32_16x16x32_bf16 v[34:37], v[158:161], v[174:177], v[34:37]
	v_mfma_f32_16x16x32_bf16 v[18:21], v[158:161], v[198:201], v[18:21]
	v_mfma_f32_16x16x32_bf16 v[2:5], v[158:161], v[216:219], v[2:5]
	s_setprio 0
	s_barrier
	s_add_i32 s52, 0, 0x18000
	s_add_i32 s53, 0, 0x1c000
	v_add_u32_e32 v142, s52, v207
	v_add_u32_e32 v158, s53, v207
	ds_read_b128 v[130:133], v142
	ds_read_b128 v[134:137], v142 offset:1024
	ds_read_b128 v[138:141], v142 offset:2048
	ds_read_b128 v[142:145], v142 offset:3072
	ds_read_b128 v[146:149], v158
	ds_read_b128 v[150:153], v158 offset:1024
	ds_read_b128 v[154:157], v158 offset:2048
	ds_read_b128 v[158:161], v158 offset:3072
	s_add_u32 s0, s30, 0x40000
	s_addc_u32 s1, s31, 0
	s_mov_b32 m0, s39
	v_lshl_add_u64 v[228:229], s[0:1], 0, v[178:179]
	ds_read_b128 v[162:165], v213 offset:32768
	ds_read_b128 v[166:169], v213 offset:33792
	ds_read_b128 v[170:173], v213 offset:34816
	ds_read_b128 v[174:177], v213 offset:35840
	ds_read_b128 v[194:197], v213 offset:36864
	ds_read_b128 v[198:201], v213 offset:37888
	ds_read_b128 v[202:205], v213 offset:38912
	ds_read_b128 v[216:219], v213 offset:39936
	global_load_lds_dwordx4 v[228:229], off
	v_lshl_add_u64 v[228:229], s[0:1], 0, v[182:183]
	s_mov_b32 m0, s40
	s_nop 0
	global_load_lds_dwordx4 v[228:229], off
	s_waitcnt vmcnt(8)
	s_waitcnt lgkmcnt(0)
	s_barrier
	s_setprio 1
	s_waitcnt lgkmcnt(0)
	v_mfma_f32_16x16x32_bf16 v[126:129], v[130:133], v[162:165], v[126:129]
	v_mfma_f32_16x16x32_bf16 v[110:113], v[130:133], v[170:173], v[110:113]
	v_mfma_f32_16x16x32_bf16 v[94:97], v[130:133], v[194:197], v[94:97]
	v_mfma_f32_16x16x32_bf16 v[78:81], v[130:133], v[202:205], v[78:81]
	v_mfma_f32_16x16x32_bf16 v[122:125], v[138:141], v[162:165], v[122:125]
	v_mfma_f32_16x16x32_bf16 v[106:109], v[138:141], v[170:173], v[106:109]
	v_mfma_f32_16x16x32_bf16 v[90:93], v[138:141], v[194:197], v[90:93]
	v_mfma_f32_16x16x32_bf16 v[74:77], v[138:141], v[202:205], v[74:77]
	v_mfma_f32_16x16x32_bf16 v[126:129], v[134:137], v[166:169], v[126:129]
	v_mfma_f32_16x16x32_bf16 v[110:113], v[134:137], v[174:177], v[110:113]
	v_mfma_f32_16x16x32_bf16 v[94:97], v[134:137], v[198:201], v[94:97]
	v_mfma_f32_16x16x32_bf16 v[78:81], v[134:137], v[216:219], v[78:81]
	v_mfma_f32_16x16x32_bf16 v[122:125], v[142:145], v[166:169], v[122:125]
	v_mfma_f32_16x16x32_bf16 v[106:109], v[142:145], v[174:177], v[106:109]
	v_mfma_f32_16x16x32_bf16 v[90:93], v[142:145], v[198:201], v[90:93]
	v_mfma_f32_16x16x32_bf16 v[74:77], v[142:145], v[216:219], v[74:77]
	s_setprio 0
	s_setprio 1
	v_mfma_f32_16x16x32_bf16 v[118:121], v[146:149], v[162:165], v[118:121]
	v_mfma_f32_16x16x32_bf16 v[102:105], v[146:149], v[170:173], v[102:105]
	v_mfma_f32_16x16x32_bf16 v[86:89], v[146:149], v[194:197], v[86:89]
	v_mfma_f32_16x16x32_bf16 v[70:73], v[146:149], v[202:205], v[70:73]
	v_mfma_f32_16x16x32_bf16 v[114:117], v[154:157], v[162:165], v[114:117]
	v_mfma_f32_16x16x32_bf16 v[98:101], v[154:157], v[170:173], v[98:101]
	v_mfma_f32_16x16x32_bf16 v[82:85], v[154:157], v[194:197], v[82:85]
	v_mfma_f32_16x16x32_bf16 v[66:69], v[154:157], v[202:205], v[66:69]
	v_mfma_f32_16x16x32_bf16 v[118:121], v[150:153], v[166:169], v[118:121]
	v_mfma_f32_16x16x32_bf16 v[102:105], v[150:153], v[174:177], v[102:105]
	v_mfma_f32_16x16x32_bf16 v[86:89], v[150:153], v[198:201], v[86:89]
	v_mfma_f32_16x16x32_bf16 v[70:73], v[150:153], v[216:219], v[70:73]
	v_mfma_f32_16x16x32_bf16 v[114:117], v[158:161], v[166:169], v[114:117]
	v_mfma_f32_16x16x32_bf16 v[98:101], v[158:161], v[174:177], v[98:101]
	v_mfma_f32_16x16x32_bf16 v[82:85], v[158:161], v[198:201], v[82:85]
	v_mfma_f32_16x16x32_bf16 v[66:69], v[158:161], v[216:219], v[66:69]
	s_setprio 0
	s_barrier
	s_add_i32 s0, s52, s37
	v_lshl_add_u64 v[220:221], v[220:221], 0, s[14:15]
	s_mov_b32 m0, s0
	ds_read_b128 v[162:165], v213 offset:49152
	ds_read_b128 v[166:169], v213 offset:50176
	ds_read_b128 v[170:173], v213 offset:51200
	ds_read_b128 v[174:177], v213 offset:52224
	ds_read_b128 v[194:197], v213 offset:53248
	ds_read_b128 v[198:201], v213 offset:54272
	ds_read_b128 v[202:205], v213 offset:55296
	ds_read_b128 v[216:219], v213 offset:56320
	global_load_lds_dwordx4 v[220:221], off
	s_add_i32 m0, s0, 0x2000
	s_add_u32 s0, s2, 0x40080
	v_lshl_add_u64 v[220:221], v[222:223], 0, s[14:15]
	s_addc_u32 s1, s3, 0
	s_add_i32 s2, s53, s37
	global_load_lds_dwordx4 v[220:221], off
	v_lshl_add_u64 v[220:221], s[0:1], 0, v[180:181]
	s_mov_b32 m0, s2
	s_nop 0
	global_load_lds_dwordx4 v[220:221], off
	v_lshl_add_u64 v[220:221], s[0:1], 0, v[184:185]
	s_add_i32 m0, s2, 0x2000
	s_nop 0
	global_load_lds_dwordx4 v[220:221], off
	v_lshl_add_u64 v[220:221], v[224:225], 0, s[14:15]
	s_mov_b32 m0, s42
	s_nop 0
	global_load_lds_dwordx4 v[220:221], off
	v_lshl_add_u64 v[220:221], v[226:227], 0, s[14:15]
	s_mov_b32 m0, s43
	s_nop 0
	global_load_lds_dwordx4 v[220:221], off
	s_waitcnt vmcnt(8)
	s_waitcnt lgkmcnt(0)
	s_barrier
	s_setprio 1
	s_waitcnt lgkmcnt(0)
	v_mfma_f32_16x16x32_bf16 v[62:65], v[130:133], v[162:165], v[62:65]
	v_mfma_f32_16x16x32_bf16 v[46:49], v[130:133], v[170:173], v[46:49]
	v_mfma_f32_16x16x32_bf16 v[30:33], v[130:133], v[194:197], v[30:33]
	v_mfma_f32_16x16x32_bf16 v[14:17], v[130:133], v[202:205], v[14:17]
	v_mfma_f32_16x16x32_bf16 v[58:61], v[138:141], v[162:165], v[58:61]
	v_mfma_f32_16x16x32_bf16 v[42:45], v[138:141], v[170:173], v[42:45]
	v_mfma_f32_16x16x32_bf16 v[26:29], v[138:141], v[194:197], v[26:29]
	v_mfma_f32_16x16x32_bf16 v[10:13], v[138:141], v[202:205], v[10:13]
	v_mfma_f32_16x16x32_bf16 v[62:65], v[134:137], v[166:169], v[62:65]
	v_mfma_f32_16x16x32_bf16 v[46:49], v[134:137], v[174:177], v[46:49]
	v_mfma_f32_16x16x32_bf16 v[30:33], v[134:137], v[198:201], v[30:33]
	v_mfma_f32_16x16x32_bf16 v[14:17], v[134:137], v[216:219], v[14:17]
	v_mfma_f32_16x16x32_bf16 v[58:61], v[142:145], v[166:169], v[58:61]
	v_mfma_f32_16x16x32_bf16 v[42:45], v[142:145], v[174:177], v[42:45]
	v_mfma_f32_16x16x32_bf16 v[26:29], v[142:145], v[198:201], v[26:29]
	v_mfma_f32_16x16x32_bf16 v[10:13], v[142:145], v[216:219], v[10:13]
	s_setprio 0
	s_setprio 1
	v_mfma_f32_16x16x32_bf16 v[54:57], v[146:149], v[162:165], v[54:57]
	v_mfma_f32_16x16x32_bf16 v[38:41], v[146:149], v[170:173], v[38:41]
	v_mfma_f32_16x16x32_bf16 v[22:25], v[146:149], v[194:197], v[22:25]
	v_mfma_f32_16x16x32_bf16 v[6:9], v[146:149], v[202:205], v[6:9]
	v_mfma_f32_16x16x32_bf16 v[50:53], v[154:157], v[162:165], v[50:53]
	v_mfma_f32_16x16x32_bf16 v[34:37], v[154:157], v[170:173], v[34:37]
	v_mfma_f32_16x16x32_bf16 v[18:21], v[154:157], v[194:197], v[18:21]
	v_mfma_f32_16x16x32_bf16 v[2:5], v[154:157], v[202:205], v[2:5]
	v_mfma_f32_16x16x32_bf16 v[54:57], v[150:153], v[166:169], v[54:57]
	v_mfma_f32_16x16x32_bf16 v[38:41], v[150:153], v[174:177], v[38:41]
	v_mfma_f32_16x16x32_bf16 v[22:25], v[150:153], v[198:201], v[22:25]
	v_mfma_f32_16x16x32_bf16 v[6:9], v[150:153], v[216:219], v[6:9]
	v_mfma_f32_16x16x32_bf16 v[50:53], v[158:161], v[166:169], v[50:53]
	v_mfma_f32_16x16x32_bf16 v[34:37], v[158:161], v[174:177], v[34:37]
	v_mfma_f32_16x16x32_bf16 v[18:21], v[158:161], v[198:201], v[18:21]
	v_mfma_f32_16x16x32_bf16 v[2:5], v[158:161], v[216:219], v[2:5]
	s_setprio 0
	s_barrier
	s_add_i32 s51, s51, 2
	s_add_u32 s28, s28, 0x100
	s_addc_u32 s29, s29, 0
	s_add_u32 s49, s49, 0x100
	s_addc_u32 s50, s50, 0
	s_cmp_gt_u32 s51, 13
	s_cbranch_scc0 .LBB0_382
	s_and_b64 vcc, exec, s[16:17]
	s_cbranch_vccz .LBB0_385
	s_barrier

.LBB0_471:
	ds_read_b128 v[148:151], v167
	ds_read_b128 v[152:155], v167 offset:1024
	ds_read_b128 v[156:159], v167 offset:2048
	ds_read_b128 v[160:163], v167 offset:3072
	ds_read_b128 v[172:175], v168
	ds_read_b128 v[176:179], v168 offset:1024
	ds_read_b128 v[180:183], v168 offset:2048
	ds_read_b128 v[184:187], v168 offset:3072
	s_add_u32 s0, s28, 0xfffc0080
	s_addc_u32 s1, s29, -1
	s_cmp_eq_u32 s53, 12
	s_cselect_b32 s31, s21, s1
	s_cselect_b32 s30, s49, s0
	s_cselect_b32 s3, s19, s52
	s_cselect_b32 s2, s50, s51
	v_lshl_add_u64 v[220:221], s[28:29], 0, v[140:141]
	s_add_i32 m0, s38, 0xc000
	ds_read_b128 v[188:191], v169
	ds_read_b128 v[192:195], v169 offset:1024
	ds_read_b128 v[196:199], v169 offset:2048
	ds_read_b128 v[200:203], v169 offset:3072
	ds_read_b128 v[204:207], v169 offset:4096
	ds_read_b128 v[208:211], v169 offset:5120
	ds_read_b128 v[212:215], v169 offset:6144
	ds_read_b128 v[216:219], v169 offset:7168
	global_load_lds_dwordx4 v[220:221], off
	v_lshl_add_u64 v[220:221], s[28:29], 0, v[142:143]
	s_add_i32 m0, s38, 0xe000
	s_nop 0
	global_load_lds_dwordx4 v[220:221], off
	s_waitcnt vmcnt(8)
	s_waitcnt lgkmcnt(0)
	s_barrier
	s_setprio 1
	s_waitcnt lgkmcnt(0)
	v_mfma_f32_16x16x32_bf16 v[126:129], v[148:151], v[188:191], v[126:129]
	v_mfma_f32_16x16x32_bf16 v[110:113], v[148:151], v[196:199], v[110:113]
	v_mfma_f32_16x16x32_bf16 v[94:97], v[148:151], v[204:207], v[94:97]
	v_mfma_f32_16x16x32_bf16 v[78:81], v[148:151], v[212:215], v[78:81]
	v_mfma_f32_16x16x32_bf16 v[118:121], v[156:159], v[188:191], v[118:121]
	v_mfma_f32_16x16x32_bf16 v[102:105], v[156:159], v[196:199], v[102:105]
	v_mfma_f32_16x16x32_bf16 v[86:89], v[156:159], v[204:207], v[86:89]
	v_mfma_f32_16x16x32_bf16 v[70:73], v[156:159], v[212:215], v[70:73]
	v_mfma_f32_16x16x32_bf16 v[126:129], v[152:155], v[192:195], v[126:129]
	v_mfma_f32_16x16x32_bf16 v[110:113], v[152:155], v[200:203], v[110:113]
	v_mfma_f32_16x16x32_bf16 v[94:97], v[152:155], v[208:211], v[94:97]
	v_mfma_f32_16x16x32_bf16 v[78:81], v[152:155], v[216:219], v[78:81]
	v_mfma_f32_16x16x32_bf16 v[118:121], v[160:163], v[192:195], v[118:121]
	v_mfma_f32_16x16x32_bf16 v[102:105], v[160:163], v[200:203], v[102:105]
	v_mfma_f32_16x16x32_bf16 v[86:89], v[160:163], v[208:211], v[86:89]
	v_mfma_f32_16x16x32_bf16 v[70:73], v[160:163], v[216:219], v[70:73]
	s_setprio 0
	s_setprio 1
	v_mfma_f32_16x16x32_bf16 v[122:125], v[172:175], v[188:191], v[122:125]
	v_mfma_f32_16x16x32_bf16 v[106:109], v[172:175], v[196:199], v[106:109]
	v_mfma_f32_16x16x32_bf16 v[90:93], v[172:175], v[204:207], v[90:93]
	v_mfma_f32_16x16x32_bf16 v[74:77], v[172:175], v[212:215], v[74:77]
	v_mfma_f32_16x16x32_bf16 v[114:117], v[180:183], v[188:191], v[114:117]
	v_mfma_f32_16x16x32_bf16 v[98:101], v[180:183], v[196:199], v[98:101]
	v_mfma_f32_16x16x32_bf16 v[82:85], v[180:183], v[204:207], v[82:85]
	v_mfma_f32_16x16x32_bf16 v[66:69], v[180:183], v[212:215], v[66:69]
	v_mfma_f32_16x16x32_bf16 v[122:125], v[176:179], v[192:195], v[122:125]
	v_mfma_f32_16x16x32_bf16 v[106:109], v[176:179], v[200:203], v[106:109]
	v_mfma_f32_16x16x32_bf16 v[90:93], v[176:179], v[208:211], v[90:93]
	v_mfma_f32_16x16x32_bf16 v[74:77], v[176:179], v[216:219], v[74:77]
	v_mfma_f32_16x16x32_bf16 v[114:117], v[184:187], v[192:195], v[114:117]
	v_mfma_f32_16x16x32_bf16 v[98:101], v[184:187], v[200:203], v[98:101]
	v_mfma_f32_16x16x32_bf16 v[82:85], v[184:187], v[208:211], v[82:85]
	v_mfma_f32_16x16x32_bf16 v[66:69], v[184:187], v[216:219], v[66:69]
	s_setprio 0
	s_barrier
	s_add_i32 s0, s45, s35
	v_lshl_add_u64 v[220:221], s[2:3], 0, v[134:135]
	s_mov_b32 m0, s0
	ds_read_b128 v[188:191], v169 offset:16384
	ds_read_b128 v[192:195], v169 offset:17408
	ds_read_b128 v[196:199], v169 offset:18432
	ds_read_b128 v[200:203], v169 offset:19456
	ds_read_b128 v[204:207], v169 offset:20480
	ds_read_b128 v[208:211], v169 offset:21504
	ds_read_b128 v[212:215], v169 offset:22528
	ds_read_b128 v[216:219], v169 offset:23552
	global_load_lds_dwordx4 v[220:221], off
	s_add_i32 m0, s0, 0x2000
	s_add_u32 s0, s2, 0x40000
	v_lshl_add_u64 v[222:223], s[2:3], 0, v[130:131]
	s_addc_u32 s1, s3, 0
	s_add_i32 s54, s46, s35
	global_load_lds_dwordx4 v[222:223], off
	v_lshl_add_u64 v[224:225], s[0:1], 0, v[134:135]
	s_mov_b32 m0, s54
	v_lshl_add_u64 v[226:227], s[30:31], 0, v[132:133]
	global_load_lds_dwordx4 v[224:225], off
	v_lshl_add_u64 v[224:225], s[0:1], 0, v[130:131]
	s_add_i32 m0, s54, 0x2000
	s_nop 0
	global_load_lds_dwordx4 v[224:225], off
	v_lshl_add_u64 v[224:225], s[30:31], 0, v[136:137]
	s_mov_b32 m0, s38
	s_nop 0
	global_load_lds_dwordx4 v[224:225], off
	s_mov_b32 m0, s39
	s_nop 0
	global_load_lds_dwordx4 v[226:227], off
	s_waitcnt vmcnt(8)
	s_waitcnt lgkmcnt(0)
	s_barrier
	s_setprio 1
	s_waitcnt lgkmcnt(0)
	v_mfma_f32_16x16x32_bf16 v[62:65], v[148:151], v[188:191], v[62:65]
	v_mfma_f32_16x16x32_bf16 v[46:49], v[148:151], v[196:199], v[46:49]
	v_mfma_f32_16x16x32_bf16 v[30:33], v[148:151], v[204:207], v[30:33]
	v_mfma_f32_16x16x32_bf16 v[14:17], v[148:151], v[212:215], v[14:17]
	v_mfma_f32_16x16x32_bf16 v[54:57], v[156:159], v[188:191], v[54:57]
	v_mfma_f32_16x16x32_bf16 v[38:41], v[156:159], v[196:199], v[38:41]
	v_mfma_f32_16x16x32_bf16 v[22:25], v[156:159], v[204:207], v[22:25]
	v_mfma_f32_16x16x32_bf16 v[6:9], v[156:159], v[212:215], v[6:9]
	v_mfma_f32_16x16x32_bf16 v[62:65], v[152:155], v[192:195], v[62:65]
	v_mfma_f32_16x16x32_bf16 v[46:49], v[152:155], v[200:203], v[46:49]
	v_mfma_f32_16x16x32_bf16 v[30:33], v[152:155], v[208:211], v[30:33]
	v_mfma_f32_16x16x32_bf16 v[14:17], v[152:155], v[216:219], v[14:17]
	v_mfma_f32_16x16x32_bf16 v[54:57], v[160:163], v[192:195], v[54:57]
	v_mfma_f32_16x16x32_bf16 v[38:41], v[160:163], v[200:203], v[38:41]
	v_mfma_f32_16x16x32_bf16 v[22:25], v[160:163], v[208:211], v[22:25]
	v_mfma_f32_16x16x32_bf16 v[6:9], v[160:163], v[216:219], v[6:9]
	s_setprio 0
	s_setprio 1
	v_mfma_f32_16x16x32_bf16 v[58:61], v[172:175], v[188:191], v[58:61]
	v_mfma_f32_16x16x32_bf16 v[42:45], v[172:175], v[196:199], v[42:45]
	v_mfma_f32_16x16x32_bf16 v[26:29], v[172:175], v[204:207], v[26:29]
	v_mfma_f32_16x16x32_bf16 v[10:13], v[172:175], v[212:215], v[10:13]
	v_mfma_f32_16x16x32_bf16 v[50:53], v[180:183], v[188:191], v[50:53]
	v_mfma_f32_16x16x32_bf16 v[34:37], v[180:183], v[196:199], v[34:37]
	v_mfma_f32_16x16x32_bf16 v[18:21], v[180:183], v[204:207], v[18:21]
	v_mfma_f32_16x16x32_bf16 v[2:5], v[180:183], v[212:215], v[2:5]
	v_mfma_f32_16x16x32_bf16 v[58:61], v[176:179], v[192:195], v[58:61]
	v_mfma_f32_16x16x32_bf16 v[42:45], v[176:179], v[200:203], v[42:45]
	v_mfma_f32_16x16x32_bf16 v[26:29], v[176:179], v[208:211], v[26:29]
	v_mfma_f32_16x16x32_bf16 v[10:13], v[176:179], v[216:219], v[10:13]
	v_mfma_f32_16x16x32_bf16 v[50:53], v[184:187], v[192:195], v[50:53]
	v_mfma_f32_16x16x32_bf16 v[34:37], v[184:187], v[200:203], v[34:37]
	v_mfma_f32_16x16x32_bf16 v[18:21], v[184:187], v[208:211], v[18:21]
	v_mfma_f32_16x16x32_bf16 v[2:5], v[184:187], v[216:219], v[2:5]
	s_setprio 0
	s_barrier
	s_add_i32 s54, 0, 0x18000
	s_add_i32 s55, 0, 0x1c000
	v_add_u32_e32 v160, s54, v166
	v_add_u32_e32 v171, s55, v166
	ds_read_b128 v[148:151], v160
	ds_read_b128 v[152:155], v160 offset:1024
	ds_read_b128 v[156:159], v160 offset:2048
	ds_read_b128 v[160:163], v160 offset:3072
	ds_read_b128 v[172:175], v171
	ds_read_b128 v[176:179], v171 offset:1024
	ds_read_b128 v[180:183], v171 offset:2048
	ds_read_b128 v[184:187], v171 offset:3072
	s_add_u32 s0, s30, 0x40000
	s_addc_u32 s1, s31, 0
	s_mov_b32 m0, s40
	v_lshl_add_u64 v[228:229], s[0:1], 0, v[136:137]
	ds_read_b128 v[188:191], v169 offset:32768
	ds_read_b128 v[192:195], v169 offset:33792
	ds_read_b128 v[196:199], v169 offset:34816
	ds_read_b128 v[200:203], v169 offset:35840
	ds_read_b128 v[204:207], v169 offset:36864
	ds_read_b128 v[208:211], v169 offset:37888
	ds_read_b128 v[212:215], v169 offset:38912
	ds_read_b128 v[216:219], v169 offset:39936
	global_load_lds_dwordx4 v[228:229], off
	v_lshl_add_u64 v[228:229], s[0:1], 0, v[132:133]
	s_mov_b32 m0, s41
	s_nop 0
	global_load_lds_dwordx4 v[228:229], off
	s_waitcnt vmcnt(8)
	s_waitcnt lgkmcnt(0)
	s_barrier
	s_setprio 1
	s_waitcnt lgkmcnt(0)
	v_mfma_f32_16x16x32_bf16 v[126:129], v[148:151], v[188:191], v[126:129]
	v_mfma_f32_16x16x32_bf16 v[110:113], v[148:151], v[196:199], v[110:113]
	v_mfma_f32_16x16x32_bf16 v[94:97], v[148:151], v[204:207], v[94:97]
	v_mfma_f32_16x16x32_bf16 v[78:81], v[148:151], v[212:215], v[78:81]
	v_mfma_f32_16x16x32_bf16 v[118:121], v[156:159], v[188:191], v[118:121]
	v_mfma_f32_16x16x32_bf16 v[102:105], v[156:159], v[196:199], v[102:105]
	v_mfma_f32_16x16x32_bf16 v[86:89], v[156:159], v[204:207], v[86:89]
	v_mfma_f32_16x16x32_bf16 v[70:73], v[156:159], v[212:215], v[70:73]
	v_mfma_f32_16x16x32_bf16 v[126:129], v[152:155], v[192:195], v[126:129]
	v_mfma_f32_16x16x32_bf16 v[110:113], v[152:155], v[200:203], v[110:113]
	v_mfma_f32_16x16x32_bf16 v[94:97], v[152:155], v[208:211], v[94:97]
	v_mfma_f32_16x16x32_bf16 v[78:81], v[152:155], v[216:219], v[78:81]
	v_mfma_f32_16x16x32_bf16 v[118:121], v[160:163], v[192:195], v[118:121]
	v_mfma_f32_16x16x32_bf16 v[102:105], v[160:163], v[200:203], v[102:105]
	v_mfma_f32_16x16x32_bf16 v[86:89], v[160:163], v[208:211], v[86:89]
	v_mfma_f32_16x16x32_bf16 v[70:73], v[160:163], v[216:219], v[70:73]
	s_setprio 0
	s_setprio 1
	v_mfma_f32_16x16x32_bf16 v[122:125], v[172:175], v[188:191], v[122:125]
	v_mfma_f32_16x16x32_bf16 v[106:109], v[172:175], v[196:199], v[106:109]
	v_mfma_f32_16x16x32_bf16 v[90:93], v[172:175], v[204:207], v[90:93]
	v_mfma_f32_16x16x32_bf16 v[74:77], v[172:175], v[212:215], v[74:77]
	v_mfma_f32_16x16x32_bf16 v[114:117], v[180:183], v[188:191], v[114:117]
	v_mfma_f32_16x16x32_bf16 v[98:101], v[180:183], v[196:199], v[98:101]
	v_mfma_f32_16x16x32_bf16 v[82:85], v[180:183], v[204:207], v[82:85]
	v_mfma_f32_16x16x32_bf16 v[66:69], v[180:183], v[212:215], v[66:69]
	v_mfma_f32_16x16x32_bf16 v[122:125], v[176:179], v[192:195], v[122:125]
	v_mfma_f32_16x16x32_bf16 v[106:109], v[176:179], v[200:203], v[106:109]
	v_mfma_f32_16x16x32_bf16 v[90:93], v[176:179], v[208:211], v[90:93]
	v_mfma_f32_16x16x32_bf16 v[74:77], v[176:179], v[216:219], v[74:77]
	v_mfma_f32_16x16x32_bf16 v[114:117], v[184:187], v[192:195], v[114:117]
	v_mfma_f32_16x16x32_bf16 v[98:101], v[184:187], v[200:203], v[98:101]
	v_mfma_f32_16x16x32_bf16 v[82:85], v[184:187], v[208:211], v[82:85]
	v_mfma_f32_16x16x32_bf16 v[66:69], v[184:187], v[216:219], v[66:69]
	s_setprio 0
	s_barrier
	s_add_i32 s0, s54, s35
	v_lshl_add_u64 v[220:221], v[220:221], 0, s[14:15]
	s_mov_b32 m0, s0
	ds_read_b128 v[188:191], v169 offset:49152
	ds_read_b128 v[192:195], v169 offset:50176
	ds_read_b128 v[196:199], v169 offset:51200
	ds_read_b128 v[200:203], v169 offset:52224
	ds_read_b128 v[204:207], v169 offset:53248
	ds_read_b128 v[208:211], v169 offset:54272
	ds_read_b128 v[212:215], v169 offset:55296
	ds_read_b128 v[216:219], v169 offset:56320
	global_load_lds_dwordx4 v[220:221], off
	s_add_i32 m0, s0, 0x2000
	s_add_u32 s0, s2, 0x40080
	v_lshl_add_u64 v[220:221], v[222:223], 0, s[14:15]
	s_addc_u32 s1, s3, 0
	s_add_i32 s2, s55, s35
	global_load_lds_dwordx4 v[220:221], off
	v_lshl_add_u64 v[220:221], s[0:1], 0, v[134:135]
	s_mov_b32 m0, s2
	s_nop 0
	global_load_lds_dwordx4 v[220:221], off
	v_lshl_add_u64 v[220:221], s[0:1], 0, v[130:131]
	s_add_i32 m0, s2, 0x2000
	s_nop 0
	global_load_lds_dwordx4 v[220:221], off
	v_lshl_add_u64 v[220:221], v[224:225], 0, s[14:15]
	s_mov_b32 m0, s42
	s_nop 0
	global_load_lds_dwordx4 v[220:221], off
	v_lshl_add_u64 v[220:221], v[226:227], 0, s[14:15]
	s_mov_b32 m0, s43
	s_nop 0
	global_load_lds_dwordx4 v[220:221], off
	s_waitcnt vmcnt(8)
	s_waitcnt lgkmcnt(0)
	s_barrier
	s_setprio 1
	s_waitcnt lgkmcnt(0)
	v_mfma_f32_16x16x32_bf16 v[62:65], v[148:151], v[188:191], v[62:65]
	v_mfma_f32_16x16x32_bf16 v[46:49], v[148:151], v[196:199], v[46:49]
	v_mfma_f32_16x16x32_bf16 v[30:33], v[148:151], v[204:207], v[30:33]
	v_mfma_f32_16x16x32_bf16 v[14:17], v[148:151], v[212:215], v[14:17]
	v_mfma_f32_16x16x32_bf16 v[54:57], v[156:159], v[188:191], v[54:57]
	v_mfma_f32_16x16x32_bf16 v[38:41], v[156:159], v[196:199], v[38:41]
	v_mfma_f32_16x16x32_bf16 v[22:25], v[156:159], v[204:207], v[22:25]
	v_mfma_f32_16x16x32_bf16 v[6:9], v[156:159], v[212:215], v[6:9]
	v_mfma_f32_16x16x32_bf16 v[62:65], v[152:155], v[192:195], v[62:65]
	v_mfma_f32_16x16x32_bf16 v[46:49], v[152:155], v[200:203], v[46:49]
	v_mfma_f32_16x16x32_bf16 v[30:33], v[152:155], v[208:211], v[30:33]
	v_mfma_f32_16x16x32_bf16 v[14:17], v[152:155], v[216:219], v[14:17]
	v_mfma_f32_16x16x32_bf16 v[54:57], v[160:163], v[192:195], v[54:57]
	v_mfma_f32_16x16x32_bf16 v[38:41], v[160:163], v[200:203], v[38:41]
	v_mfma_f32_16x16x32_bf16 v[22:25], v[160:163], v[208:211], v[22:25]
	v_mfma_f32_16x16x32_bf16 v[6:9], v[160:163], v[216:219], v[6:9]
	s_setprio 0
	s_setprio 1
	v_mfma_f32_16x16x32_bf16 v[58:61], v[172:175], v[188:191], v[58:61]
	v_mfma_f32_16x16x32_bf16 v[42:45], v[172:175], v[196:199], v[42:45]
	v_mfma_f32_16x16x32_bf16 v[26:29], v[172:175], v[204:207], v[26:29]
	v_mfma_f32_16x16x32_bf16 v[10:13], v[172:175], v[212:215], v[10:13]
	v_mfma_f32_16x16x32_bf16 v[50:53], v[180:183], v[188:191], v[50:53]
	v_mfma_f32_16x16x32_bf16 v[34:37], v[180:183], v[196:199], v[34:37]
	v_mfma_f32_16x16x32_bf16 v[18:21], v[180:183], v[204:207], v[18:21]
	v_mfma_f32_16x16x32_bf16 v[2:5], v[180:183], v[212:215], v[2:5]
	v_mfma_f32_16x16x32_bf16 v[58:61], v[176:179], v[192:195], v[58:61]
	v_mfma_f32_16x16x32_bf16 v[42:45], v[176:179], v[200:203], v[42:45]
	v_mfma_f32_16x16x32_bf16 v[26:29], v[176:179], v[208:211], v[26:29]
	v_mfma_f32_16x16x32_bf16 v[10:13], v[176:179], v[216:219], v[10:13]
	v_mfma_f32_16x16x32_bf16 v[50:53], v[184:187], v[192:195], v[50:53]
	v_mfma_f32_16x16x32_bf16 v[34:37], v[184:187], v[200:203], v[34:37]
	v_mfma_f32_16x16x32_bf16 v[18:21], v[184:187], v[208:211], v[18:21]
	v_mfma_f32_16x16x32_bf16 v[2:5], v[184:187], v[216:219], v[2:5]
	s_setprio 0
	s_barrier
	s_add_i32 s53, s53, 2
	s_add_u32 s28, s28, 0x100
	s_addc_u32 s29, s29, 0
	s_add_u32 s51, s51, 0x100
	s_addc_u32 s52, s52, 0
	s_cmp_gt_u32 s53, 13
	s_cbranch_scc0 .LBB0_471
	s_and_b64 vcc, exec, s[16:17]
	s_cbranch_vccz .LBB0_474
	s_barrier

.LBB0_584:
	ds_read_b128 v[130:133], v187
	ds_read_b128 v[134:137], v187 offset:1024
	ds_read_b128 v[138:141], v187 offset:2048
	ds_read_b128 v[142:145], v187 offset:3072
	ds_read_b128 v[146:149], v188
	ds_read_b128 v[150:153], v188 offset:1024
	ds_read_b128 v[170:173], v188 offset:2048
	ds_read_b128 v[174:177], v188 offset:3072
	s_add_u32 s0, s22, 0xfff50080
	s_addc_u32 s1, s23, -1
	s_cmp_eq_u32 s47, 40
	s_cselect_b32 s25, s9, s1
	s_cselect_b32 s24, s8, s0
	s_cselect_b32 s3, s21, s46
	s_cselect_b32 s2, s20, s45
	v_lshl_add_u64 v[220:221], s[22:23], 0, v[162:163]
	s_add_i32 m0, s31, 0xc000
	ds_read_b128 v[178:181], v189
	ds_read_b128 v[192:195], v189 offset:1024
	ds_read_b128 v[196:199], v189 offset:2048
	ds_read_b128 v[200:203], v189 offset:3072
	ds_read_b128 v[204:207], v189 offset:4096
	ds_read_b128 v[208:211], v189 offset:5120
	ds_read_b128 v[212:215], v189 offset:6144
	ds_read_b128 v[216:219], v189 offset:7168
	global_load_lds_dwordx4 v[220:221], off
	v_lshl_add_u64 v[220:221], s[22:23], 0, v[164:165]
	s_add_i32 m0, s31, 0xe000
	s_nop 0
	global_load_lds_dwordx4 v[220:221], off
	s_waitcnt vmcnt(8)
	s_waitcnt lgkmcnt(0)
	s_barrier
	s_setprio 1
	s_waitcnt lgkmcnt(0)
	v_mfma_f32_16x16x32_bf16 v[126:129], v[130:133], v[178:181], v[126:129]
	v_mfma_f32_16x16x32_bf16 v[110:113], v[130:133], v[196:199], v[110:113]
	v_mfma_f32_16x16x32_bf16 v[94:97], v[130:133], v[204:207], v[94:97]
	v_mfma_f32_16x16x32_bf16 v[78:81], v[130:133], v[212:215], v[78:81]
	v_mfma_f32_16x16x32_bf16 v[122:125], v[138:141], v[178:181], v[122:125]
	v_mfma_f32_16x16x32_bf16 v[106:109], v[138:141], v[196:199], v[106:109]
	v_mfma_f32_16x16x32_bf16 v[90:93], v[138:141], v[204:207], v[90:93]
	v_mfma_f32_16x16x32_bf16 v[74:77], v[138:141], v[212:215], v[74:77]
	v_mfma_f32_16x16x32_bf16 v[126:129], v[134:137], v[192:195], v[126:129]
	v_mfma_f32_16x16x32_bf16 v[110:113], v[134:137], v[200:203], v[110:113]
	v_mfma_f32_16x16x32_bf16 v[94:97], v[134:137], v[208:211], v[94:97]
	v_mfma_f32_16x16x32_bf16 v[78:81], v[134:137], v[216:219], v[78:81]
	v_mfma_f32_16x16x32_bf16 v[122:125], v[142:145], v[192:195], v[122:125]
	v_mfma_f32_16x16x32_bf16 v[106:109], v[142:145], v[200:203], v[106:109]
	v_mfma_f32_16x16x32_bf16 v[90:93], v[142:145], v[208:211], v[90:93]
	v_mfma_f32_16x16x32_bf16 v[74:77], v[142:145], v[216:219], v[74:77]
	s_setprio 0
	s_setprio 1
	v_mfma_f32_16x16x32_bf16 v[118:121], v[146:149], v[178:181], v[118:121]
	v_mfma_f32_16x16x32_bf16 v[102:105], v[146:149], v[196:199], v[102:105]
	v_mfma_f32_16x16x32_bf16 v[86:89], v[146:149], v[204:207], v[86:89]
	v_mfma_f32_16x16x32_bf16 v[70:73], v[146:149], v[212:215], v[70:73]
	v_mfma_f32_16x16x32_bf16 v[114:117], v[170:173], v[178:181], v[114:117]
	v_mfma_f32_16x16x32_bf16 v[98:101], v[170:173], v[196:199], v[98:101]
	v_mfma_f32_16x16x32_bf16 v[82:85], v[170:173], v[204:207], v[82:85]
	v_mfma_f32_16x16x32_bf16 v[66:69], v[170:173], v[212:215], v[66:69]
	v_mfma_f32_16x16x32_bf16 v[118:121], v[150:153], v[192:195], v[118:121]
	v_mfma_f32_16x16x32_bf16 v[102:105], v[150:153], v[200:203], v[102:105]
	v_mfma_f32_16x16x32_bf16 v[86:89], v[150:153], v[208:211], v[86:89]
	v_mfma_f32_16x16x32_bf16 v[70:73], v[150:153], v[216:219], v[70:73]
	v_mfma_f32_16x16x32_bf16 v[114:117], v[174:177], v[192:195], v[114:117]
	v_mfma_f32_16x16x32_bf16 v[98:101], v[174:177], v[200:203], v[98:101]
	v_mfma_f32_16x16x32_bf16 v[82:85], v[174:177], v[208:211], v[82:85]
	v_mfma_f32_16x16x32_bf16 v[66:69], v[174:177], v[216:219], v[66:69]
	s_setprio 0
	s_barrier
	s_add_i32 s0, s41, s30
	v_lshl_add_u64 v[220:221], s[2:3], 0, v[156:157]
	s_mov_b32 m0, s0
	ds_read_b128 v[178:181], v189 offset:16384
	ds_read_b128 v[192:195], v189 offset:17408
	ds_read_b128 v[196:199], v189 offset:18432
	ds_read_b128 v[200:203], v189 offset:19456
	ds_read_b128 v[204:207], v189 offset:20480
	ds_read_b128 v[208:211], v189 offset:21504
	ds_read_b128 v[212:215], v189 offset:22528
	ds_read_b128 v[216:219], v189 offset:23552
	global_load_lds_dwordx4 v[220:221], off
	s_add_i32 m0, s0, 0x2000
	s_add_u32 s0, s2, 0xb0000
	v_lshl_add_u64 v[222:223], s[2:3], 0, v[160:161]
	s_addc_u32 s1, s3, 0
	s_add_i32 s48, s42, s30
	global_load_lds_dwordx4 v[222:223], off
	v_lshl_add_u64 v[224:225], s[0:1], 0, v[156:157]
	s_mov_b32 m0, s48
	v_lshl_add_u64 v[226:227], s[24:25], 0, v[158:159]
	global_load_lds_dwordx4 v[224:225], off
	v_lshl_add_u64 v[224:225], s[0:1], 0, v[160:161]
	s_add_i32 m0, s48, 0x2000
	s_nop 0
	global_load_lds_dwordx4 v[224:225], off
	v_lshl_add_u64 v[224:225], s[24:25], 0, v[154:155]
	s_mov_b32 m0, s31
	s_nop 0
	global_load_lds_dwordx4 v[224:225], off
	s_mov_b32 m0, s33
	s_nop 0
	global_load_lds_dwordx4 v[226:227], off
	s_waitcnt vmcnt(8)
	s_waitcnt lgkmcnt(0)
	s_barrier
	s_setprio 1
	s_waitcnt lgkmcnt(0)
	v_mfma_f32_16x16x32_bf16 v[62:65], v[130:133], v[178:181], v[62:65]
	v_mfma_f32_16x16x32_bf16 v[46:49], v[130:133], v[196:199], v[46:49]
	v_mfma_f32_16x16x32_bf16 v[30:33], v[130:133], v[204:207], v[30:33]
	v_mfma_f32_16x16x32_bf16 v[14:17], v[130:133], v[212:215], v[14:17]
	v_mfma_f32_16x16x32_bf16 v[58:61], v[138:141], v[178:181], v[58:61]
	v_mfma_f32_16x16x32_bf16 v[42:45], v[138:141], v[196:199], v[42:45]
	v_mfma_f32_16x16x32_bf16 v[26:29], v[138:141], v[204:207], v[26:29]
	v_mfma_f32_16x16x32_bf16 v[10:13], v[138:141], v[212:215], v[10:13]
	v_mfma_f32_16x16x32_bf16 v[62:65], v[134:137], v[192:195], v[62:65]
	v_mfma_f32_16x16x32_bf16 v[46:49], v[134:137], v[200:203], v[46:49]
	v_mfma_f32_16x16x32_bf16 v[30:33], v[134:137], v[208:211], v[30:33]
	v_mfma_f32_16x16x32_bf16 v[14:17], v[134:137], v[216:219], v[14:17]
	v_mfma_f32_16x16x32_bf16 v[58:61], v[142:145], v[192:195], v[58:61]
	v_mfma_f32_16x16x32_bf16 v[42:45], v[142:145], v[200:203], v[42:45]
	v_mfma_f32_16x16x32_bf16 v[26:29], v[142:145], v[208:211], v[26:29]
	v_mfma_f32_16x16x32_bf16 v[10:13], v[142:145], v[216:219], v[10:13]
	s_setprio 0
	s_setprio 1
	v_mfma_f32_16x16x32_bf16 v[54:57], v[146:149], v[178:181], v[54:57]
	v_mfma_f32_16x16x32_bf16 v[38:41], v[146:149], v[196:199], v[38:41]
	v_mfma_f32_16x16x32_bf16 v[22:25], v[146:149], v[204:207], v[22:25]
	v_mfma_f32_16x16x32_bf16 v[6:9], v[146:149], v[212:215], v[6:9]
	v_mfma_f32_16x16x32_bf16 v[50:53], v[170:173], v[178:181], v[50:53]
	v_mfma_f32_16x16x32_bf16 v[34:37], v[170:173], v[196:199], v[34:37]
	v_mfma_f32_16x16x32_bf16 v[18:21], v[170:173], v[204:207], v[18:21]
	v_mfma_f32_16x16x32_bf16 v[2:5], v[170:173], v[212:215], v[2:5]
	v_mfma_f32_16x16x32_bf16 v[54:57], v[150:153], v[192:195], v[54:57]
	v_mfma_f32_16x16x32_bf16 v[38:41], v[150:153], v[200:203], v[38:41]
	v_mfma_f32_16x16x32_bf16 v[22:25], v[150:153], v[208:211], v[22:25]
	v_mfma_f32_16x16x32_bf16 v[6:9], v[150:153], v[216:219], v[6:9]
	v_mfma_f32_16x16x32_bf16 v[50:53], v[174:177], v[192:195], v[50:53]
	v_mfma_f32_16x16x32_bf16 v[34:37], v[174:177], v[200:203], v[34:37]
	v_mfma_f32_16x16x32_bf16 v[18:21], v[174:177], v[208:211], v[18:21]
	v_mfma_f32_16x16x32_bf16 v[2:5], v[174:177], v[216:219], v[2:5]
	s_setprio 0
	s_barrier
	s_add_i32 s48, 0, 0x18000
	s_add_i32 s49, 0, 0x1c000
	v_add_u32_e32 v142, s48, v183
	v_add_u32_e32 v174, s49, v183
	ds_read_b128 v[130:133], v142
	ds_read_b128 v[134:137], v142 offset:1024
	ds_read_b128 v[138:141], v142 offset:2048
	ds_read_b128 v[142:145], v142 offset:3072
	ds_read_b128 v[146:149], v174
	ds_read_b128 v[150:153], v174 offset:1024
	ds_read_b128 v[170:173], v174 offset:2048
	ds_read_b128 v[174:177], v174 offset:3072
	s_add_u32 s0, s24, 0xb0000
	s_addc_u32 s1, s25, 0
	s_mov_b32 m0, s34
	v_lshl_add_u64 v[228:229], s[0:1], 0, v[154:155]
	ds_read_b128 v[178:181], v189 offset:32768
	ds_read_b128 v[192:195], v189 offset:33792
	ds_read_b128 v[196:199], v189 offset:34816
	ds_read_b128 v[200:203], v189 offset:35840
	ds_read_b128 v[204:207], v189 offset:36864
	ds_read_b128 v[208:211], v189 offset:37888
	ds_read_b128 v[212:215], v189 offset:38912
	ds_read_b128 v[216:219], v189 offset:39936
	global_load_lds_dwordx4 v[228:229], off
	v_lshl_add_u64 v[228:229], s[0:1], 0, v[158:159]
	s_mov_b32 m0, s35
	s_nop 0
	global_load_lds_dwordx4 v[228:229], off
	s_waitcnt vmcnt(8)
	s_waitcnt lgkmcnt(0)
	s_barrier
	s_setprio 1
	s_waitcnt lgkmcnt(0)
	v_mfma_f32_16x16x32_bf16 v[126:129], v[130:133], v[178:181], v[126:129]
	v_mfma_f32_16x16x32_bf16 v[110:113], v[130:133], v[196:199], v[110:113]
	v_mfma_f32_16x16x32_bf16 v[94:97], v[130:133], v[204:207], v[94:97]
	v_mfma_f32_16x16x32_bf16 v[78:81], v[130:133], v[212:215], v[78:81]
	v_mfma_f32_16x16x32_bf16 v[122:125], v[138:141], v[178:181], v[122:125]
	v_mfma_f32_16x16x32_bf16 v[106:109], v[138:141], v[196:199], v[106:109]
	v_mfma_f32_16x16x32_bf16 v[90:93], v[138:141], v[204:207], v[90:93]
	v_mfma_f32_16x16x32_bf16 v[74:77], v[138:141], v[212:215], v[74:77]
	v_mfma_f32_16x16x32_bf16 v[126:129], v[134:137], v[192:195], v[126:129]
	v_mfma_f32_16x16x32_bf16 v[110:113], v[134:137], v[200:203], v[110:113]
	v_mfma_f32_16x16x32_bf16 v[94:97], v[134:137], v[208:211], v[94:97]
	v_mfma_f32_16x16x32_bf16 v[78:81], v[134:137], v[216:219], v[78:81]
	v_mfma_f32_16x16x32_bf16 v[122:125], v[142:145], v[192:195], v[122:125]
	v_mfma_f32_16x16x32_bf16 v[106:109], v[142:145], v[200:203], v[106:109]
	v_mfma_f32_16x16x32_bf16 v[90:93], v[142:145], v[208:211], v[90:93]
	v_mfma_f32_16x16x32_bf16 v[74:77], v[142:145], v[216:219], v[74:77]
	s_setprio 0
	s_setprio 1
	v_mfma_f32_16x16x32_bf16 v[118:121], v[146:149], v[178:181], v[118:121]
	v_mfma_f32_16x16x32_bf16 v[102:105], v[146:149], v[196:199], v[102:105]
	v_mfma_f32_16x16x32_bf16 v[86:89], v[146:149], v[204:207], v[86:89]
	v_mfma_f32_16x16x32_bf16 v[70:73], v[146:149], v[212:215], v[70:73]
	v_mfma_f32_16x16x32_bf16 v[114:117], v[170:173], v[178:181], v[114:117]
	v_mfma_f32_16x16x32_bf16 v[98:101], v[170:173], v[196:199], v[98:101]
	v_mfma_f32_16x16x32_bf16 v[82:85], v[170:173], v[204:207], v[82:85]
	v_mfma_f32_16x16x32_bf16 v[66:69], v[170:173], v[212:215], v[66:69]
	v_mfma_f32_16x16x32_bf16 v[118:121], v[150:153], v[192:195], v[118:121]
	v_mfma_f32_16x16x32_bf16 v[102:105], v[150:153], v[200:203], v[102:105]
	v_mfma_f32_16x16x32_bf16 v[86:89], v[150:153], v[208:211], v[86:89]
	v_mfma_f32_16x16x32_bf16 v[70:73], v[150:153], v[216:219], v[70:73]
	v_mfma_f32_16x16x32_bf16 v[114:117], v[174:177], v[192:195], v[114:117]
	v_mfma_f32_16x16x32_bf16 v[98:101], v[174:177], v[200:203], v[98:101]
	v_mfma_f32_16x16x32_bf16 v[82:85], v[174:177], v[208:211], v[82:85]
	v_mfma_f32_16x16x32_bf16 v[66:69], v[174:177], v[216:219], v[66:69]
	s_setprio 0
	s_barrier
	s_add_i32 s0, s48, s30
	v_lshl_add_u64 v[220:221], v[220:221], 0, s[16:17]
	s_mov_b32 m0, s0
	ds_read_b128 v[178:181], v189 offset:49152
	ds_read_b128 v[192:195], v189 offset:50176
	ds_read_b128 v[196:199], v189 offset:51200
	ds_read_b128 v[200:203], v189 offset:52224
	ds_read_b128 v[204:207], v189 offset:53248
	ds_read_b128 v[208:211], v189 offset:54272
	ds_read_b128 v[212:215], v189 offset:55296
	ds_read_b128 v[216:219], v189 offset:56320
	global_load_lds_dwordx4 v[220:221], off
	s_add_i32 m0, s0, 0x2000
	s_add_u32 s0, s2, 0xb0080
	v_lshl_add_u64 v[220:221], v[222:223], 0, s[16:17]
	s_addc_u32 s1, s3, 0
	s_add_i32 s2, s49, s30
	global_load_lds_dwordx4 v[220:221], off
	v_lshl_add_u64 v[220:221], s[0:1], 0, v[156:157]
	s_mov_b32 m0, s2
	s_nop 0
	global_load_lds_dwordx4 v[220:221], off
	v_lshl_add_u64 v[220:221], s[0:1], 0, v[160:161]
	s_add_i32 m0, s2, 0x2000
	s_nop 0
	global_load_lds_dwordx4 v[220:221], off
	v_lshl_add_u64 v[220:221], v[224:225], 0, s[16:17]
	s_mov_b32 m0, s37
	s_nop 0
	global_load_lds_dwordx4 v[220:221], off
	v_lshl_add_u64 v[220:221], v[226:227], 0, s[16:17]
	s_mov_b32 m0, s38
	s_nop 0
	global_load_lds_dwordx4 v[220:221], off
	s_waitcnt vmcnt(8)
	s_waitcnt lgkmcnt(0)
	s_barrier
	s_setprio 1
	s_waitcnt lgkmcnt(0)
	v_mfma_f32_16x16x32_bf16 v[62:65], v[130:133], v[178:181], v[62:65]
	v_mfma_f32_16x16x32_bf16 v[46:49], v[130:133], v[196:199], v[46:49]
	v_mfma_f32_16x16x32_bf16 v[30:33], v[130:133], v[204:207], v[30:33]
	v_mfma_f32_16x16x32_bf16 v[14:17], v[130:133], v[212:215], v[14:17]
	v_mfma_f32_16x16x32_bf16 v[58:61], v[138:141], v[178:181], v[58:61]
	v_mfma_f32_16x16x32_bf16 v[42:45], v[138:141], v[196:199], v[42:45]
	v_mfma_f32_16x16x32_bf16 v[26:29], v[138:141], v[204:207], v[26:29]
	v_mfma_f32_16x16x32_bf16 v[10:13], v[138:141], v[212:215], v[10:13]
	v_mfma_f32_16x16x32_bf16 v[62:65], v[134:137], v[192:195], v[62:65]
	v_mfma_f32_16x16x32_bf16 v[46:49], v[134:137], v[200:203], v[46:49]
	v_mfma_f32_16x16x32_bf16 v[30:33], v[134:137], v[208:211], v[30:33]
	v_mfma_f32_16x16x32_bf16 v[14:17], v[134:137], v[216:219], v[14:17]
	v_mfma_f32_16x16x32_bf16 v[58:61], v[142:145], v[192:195], v[58:61]
	v_mfma_f32_16x16x32_bf16 v[42:45], v[142:145], v[200:203], v[42:45]
	v_mfma_f32_16x16x32_bf16 v[26:29], v[142:145], v[208:211], v[26:29]
	v_mfma_f32_16x16x32_bf16 v[10:13], v[142:145], v[216:219], v[10:13]
	s_setprio 0
	s_setprio 1
	v_mfma_f32_16x16x32_bf16 v[54:57], v[146:149], v[178:181], v[54:57]
	v_mfma_f32_16x16x32_bf16 v[38:41], v[146:149], v[196:199], v[38:41]
	v_mfma_f32_16x16x32_bf16 v[22:25], v[146:149], v[204:207], v[22:25]
	v_mfma_f32_16x16x32_bf16 v[6:9], v[146:149], v[212:215], v[6:9]
	v_mfma_f32_16x16x32_bf16 v[50:53], v[170:173], v[178:181], v[50:53]
	v_mfma_f32_16x16x32_bf16 v[34:37], v[170:173], v[196:199], v[34:37]
	v_mfma_f32_16x16x32_bf16 v[18:21], v[170:173], v[204:207], v[18:21]
	v_mfma_f32_16x16x32_bf16 v[2:5], v[170:173], v[212:215], v[2:5]
	v_mfma_f32_16x16x32_bf16 v[54:57], v[150:153], v[192:195], v[54:57]
	v_mfma_f32_16x16x32_bf16 v[38:41], v[150:153], v[200:203], v[38:41]
	v_mfma_f32_16x16x32_bf16 v[22:25], v[150:153], v[208:211], v[22:25]
	v_mfma_f32_16x16x32_bf16 v[6:9], v[150:153], v[216:219], v[6:9]
	v_mfma_f32_16x16x32_bf16 v[50:53], v[174:177], v[192:195], v[50:53]
	v_mfma_f32_16x16x32_bf16 v[34:37], v[174:177], v[200:203], v[34:37]
	v_mfma_f32_16x16x32_bf16 v[18:21], v[174:177], v[208:211], v[18:21]
	v_mfma_f32_16x16x32_bf16 v[2:5], v[174:177], v[216:219], v[2:5]
	s_setprio 0
	s_barrier
	s_add_i32 s47, s47, 2
	s_add_u32 s22, s22, 0x100
	s_addc_u32 s23, s23, 0
	s_add_u32 s45, s45, 0x100
	s_addc_u32 s46, s46, 0
	s_cmp_gt_u32 s47, 41
	s_cbranch_scc0 .LBB0_584
	s_and_b64 vcc, exec, s[18:19]
	s_cbranch_vccz .LBB0_587
	s_barrier

.LBB0_675:
	ds_read_b128 v[82:85], v219
	ds_read_b128 v[86:89], v219 offset:1024
	ds_read_b128 v[94:97], v219 offset:2048
	ds_read_b128 v[102:105], v219 offset:3072
	ds_read_b128 v[110:113], v220
	ds_read_b128 v[118:121], v220 offset:1024
	ds_read_b128 v[138:141], v220 offset:2048
	ds_read_b128 v[158:161], v220 offset:3072
	s_add_u32 s0, s8, 0xfffc0080
	s_addc_u32 s1, s9, -1
	s_cmp_eq_u32 s51, 12
	s_cselect_b32 s31, s7, s1
	s_cselect_b32 s30, s23, s0
	s_cselect_b32 s3, s21, s50
	s_cselect_b32 s2, s34, s35
	v_lshl_add_u64 v[224:225], s[8:9], 0, v[190:191]
	s_add_i32 m0, s29, 0xc000
	ds_read_b128 v[162:165], v221
	ds_read_b128 v[166:169], v221 offset:1024
	ds_read_b128 v[170:173], v221 offset:2048
	ds_read_b128 v[174:177], v221 offset:3072
	ds_read_b128 v[198:201], v221 offset:4096
	ds_read_b128 v[202:205], v221 offset:5120
	ds_read_b128 v[206:209], v221 offset:6144
	ds_read_b128 v[210:213], v221 offset:7168
	global_load_lds_dwordx4 v[224:225], off
	v_lshl_add_u64 v[224:225], s[8:9], 0, v[192:193]
	s_add_i32 m0, s29, 0xe000
	s_nop 0
	global_load_lds_dwordx4 v[224:225], off
	s_waitcnt vmcnt(8)
	s_waitcnt lgkmcnt(0)
	s_barrier
	s_setprio 1
	s_waitcnt lgkmcnt(0)
	v_mfma_f32_16x16x32_bf16 v[154:157], v[82:85], v[162:165], v[154:157]
	v_mfma_f32_16x16x32_bf16 v[134:137], v[82:85], v[170:173], v[134:137]
	v_mfma_f32_16x16x32_bf16 v[114:117], v[82:85], v[198:201], v[114:117]
	v_mfma_f32_16x16x32_bf16 v[78:81], v[82:85], v[206:209], v[78:81]
	v_mfma_f32_16x16x32_bf16 v[150:153], v[94:97], v[162:165], v[150:153]
	v_mfma_f32_16x16x32_bf16 v[130:133], v[94:97], v[170:173], v[130:133]
	v_mfma_f32_16x16x32_bf16 v[106:109], v[94:97], v[198:201], v[106:109]
	v_mfma_f32_16x16x32_bf16 v[74:77], v[94:97], v[206:209], v[74:77]
	v_mfma_f32_16x16x32_bf16 v[154:157], v[86:89], v[166:169], v[154:157]
	v_mfma_f32_16x16x32_bf16 v[134:137], v[86:89], v[174:177], v[134:137]
	v_mfma_f32_16x16x32_bf16 v[114:117], v[86:89], v[202:205], v[114:117]
	v_mfma_f32_16x16x32_bf16 v[78:81], v[86:89], v[210:213], v[78:81]
	v_mfma_f32_16x16x32_bf16 v[150:153], v[102:105], v[166:169], v[150:153]
	v_mfma_f32_16x16x32_bf16 v[130:133], v[102:105], v[174:177], v[130:133]
	v_mfma_f32_16x16x32_bf16 v[106:109], v[102:105], v[202:205], v[106:109]
	v_mfma_f32_16x16x32_bf16 v[74:77], v[102:105], v[210:213], v[74:77]
	s_setprio 0
	s_setprio 1
	v_mfma_f32_16x16x32_bf16 v[146:149], v[110:113], v[162:165], v[146:149]
	v_mfma_f32_16x16x32_bf16 v[126:129], v[110:113], v[170:173], v[126:129]
	v_mfma_f32_16x16x32_bf16 v[98:101], v[110:113], v[198:201], v[98:101]
	v_mfma_f32_16x16x32_bf16 v[70:73], v[110:113], v[206:209], v[70:73]
	v_mfma_f32_16x16x32_bf16 v[142:145], v[138:141], v[162:165], v[142:145]
	v_mfma_f32_16x16x32_bf16 v[122:125], v[138:141], v[170:173], v[122:125]
	v_mfma_f32_16x16x32_bf16 v[90:93], v[138:141], v[198:201], v[90:93]
	v_mfma_f32_16x16x32_bf16 v[66:69], v[138:141], v[206:209], v[66:69]
	v_mfma_f32_16x16x32_bf16 v[146:149], v[118:121], v[166:169], v[146:149]
	v_mfma_f32_16x16x32_bf16 v[126:129], v[118:121], v[174:177], v[126:129]
	v_mfma_f32_16x16x32_bf16 v[98:101], v[118:121], v[202:205], v[98:101]
	v_mfma_f32_16x16x32_bf16 v[70:73], v[118:121], v[210:213], v[70:73]
	v_mfma_f32_16x16x32_bf16 v[142:145], v[158:161], v[166:169], v[142:145]
	v_mfma_f32_16x16x32_bf16 v[122:125], v[158:161], v[174:177], v[122:125]
	v_mfma_f32_16x16x32_bf16 v[90:93], v[158:161], v[202:205], v[90:93]
	v_mfma_f32_16x16x32_bf16 v[66:69], v[158:161], v[210:213], v[66:69]
	s_setprio 0
	s_barrier
	s_add_i32 s0, s48, s36
	v_lshl_add_u64 v[224:225], s[2:3], 0, v[182:183]
	s_mov_b32 m0, s0
	ds_read_b128 v[162:165], v221 offset:16384
	ds_read_b128 v[166:169], v221 offset:17408
	ds_read_b128 v[170:173], v221 offset:18432
	ds_read_b128 v[174:177], v221 offset:19456
	ds_read_b128 v[198:201], v221 offset:20480
	ds_read_b128 v[202:205], v221 offset:21504
	ds_read_b128 v[206:209], v221 offset:22528
	ds_read_b128 v[210:213], v221 offset:23552
	global_load_lds_dwordx4 v[224:225], off
	s_add_i32 m0, s0, 0x2000
	s_add_u32 s0, s2, 0x40000
	v_lshl_add_u64 v[226:227], s[2:3], 0, v[186:187]
	s_addc_u32 s1, s3, 0
	s_add_i32 s52, s49, s36
	global_load_lds_dwordx4 v[226:227], off
	v_lshl_add_u64 v[228:229], s[0:1], 0, v[182:183]
	s_mov_b32 m0, s52
	v_lshl_add_u64 v[230:231], s[30:31], 0, v[184:185]
	global_load_lds_dwordx4 v[228:229], off
	v_lshl_add_u64 v[228:229], s[0:1], 0, v[186:187]
	s_add_i32 m0, s52, 0x2000
	s_nop 0
	global_load_lds_dwordx4 v[228:229], off
	v_lshl_add_u64 v[228:229], s[30:31], 0, v[180:181]
	s_mov_b32 m0, s29
	s_nop 0
	global_load_lds_dwordx4 v[228:229], off
	s_mov_b32 m0, s37
	s_nop 0
	global_load_lds_dwordx4 v[230:231], off
	s_waitcnt vmcnt(8)
	s_waitcnt lgkmcnt(0)
	s_barrier
	s_setprio 1
	s_waitcnt lgkmcnt(0)
	v_mfma_f32_16x16x32_bf16 v[62:65], v[82:85], v[162:165], v[62:65]
	v_mfma_f32_16x16x32_bf16 v[46:49], v[82:85], v[170:173], v[46:49]
	v_mfma_f32_16x16x32_bf16 v[30:33], v[82:85], v[198:201], v[30:33]
	v_mfma_f32_16x16x32_bf16 v[14:17], v[82:85], v[206:209], v[14:17]
	v_mfma_f32_16x16x32_bf16 v[58:61], v[94:97], v[162:165], v[58:61]
	v_mfma_f32_16x16x32_bf16 v[42:45], v[94:97], v[170:173], v[42:45]
	v_mfma_f32_16x16x32_bf16 v[26:29], v[94:97], v[198:201], v[26:29]
	v_mfma_f32_16x16x32_bf16 v[10:13], v[94:97], v[206:209], v[10:13]
	v_mfma_f32_16x16x32_bf16 v[62:65], v[86:89], v[166:169], v[62:65]
	v_mfma_f32_16x16x32_bf16 v[46:49], v[86:89], v[174:177], v[46:49]
	v_mfma_f32_16x16x32_bf16 v[30:33], v[86:89], v[202:205], v[30:33]
	v_mfma_f32_16x16x32_bf16 v[14:17], v[86:89], v[210:213], v[14:17]
	v_mfma_f32_16x16x32_bf16 v[58:61], v[102:105], v[166:169], v[58:61]
	v_mfma_f32_16x16x32_bf16 v[42:45], v[102:105], v[174:177], v[42:45]
	v_mfma_f32_16x16x32_bf16 v[26:29], v[102:105], v[202:205], v[26:29]
	v_mfma_f32_16x16x32_bf16 v[10:13], v[102:105], v[210:213], v[10:13]
	s_setprio 0
	s_setprio 1
	v_mfma_f32_16x16x32_bf16 v[54:57], v[110:113], v[162:165], v[54:57]
	v_mfma_f32_16x16x32_bf16 v[38:41], v[110:113], v[170:173], v[38:41]
	v_mfma_f32_16x16x32_bf16 v[22:25], v[110:113], v[198:201], v[22:25]
	v_mfma_f32_16x16x32_bf16 v[6:9], v[110:113], v[206:209], v[6:9]
	v_mfma_f32_16x16x32_bf16 v[50:53], v[138:141], v[162:165], v[50:53]
	v_mfma_f32_16x16x32_bf16 v[34:37], v[138:141], v[170:173], v[34:37]
	v_mfma_f32_16x16x32_bf16 v[18:21], v[138:141], v[198:201], v[18:21]
	v_mfma_f32_16x16x32_bf16 v[2:5], v[138:141], v[206:209], v[2:5]
	v_mfma_f32_16x16x32_bf16 v[54:57], v[118:121], v[166:169], v[54:57]
	v_mfma_f32_16x16x32_bf16 v[38:41], v[118:121], v[174:177], v[38:41]
	v_mfma_f32_16x16x32_bf16 v[22:25], v[118:121], v[202:205], v[22:25]
	v_mfma_f32_16x16x32_bf16 v[6:9], v[118:121], v[210:213], v[6:9]
	v_mfma_f32_16x16x32_bf16 v[50:53], v[158:161], v[166:169], v[50:53]
	v_mfma_f32_16x16x32_bf16 v[34:37], v[158:161], v[174:177], v[34:37]
	v_mfma_f32_16x16x32_bf16 v[18:21], v[158:161], v[202:205], v[18:21]
	v_mfma_f32_16x16x32_bf16 v[2:5], v[158:161], v[210:213], v[2:5]
	s_setprio 0
	s_barrier
	s_add_i32 s52, 0, 0x18000
	s_add_i32 s53, 0, 0x1c000
	v_add_u32_e32 v102, s52, v218
	v_add_u32_e32 v158, s53, v218
	ds_read_b128 v[82:85], v102
	ds_read_b128 v[86:89], v102 offset:1024
	ds_read_b128 v[94:97], v102 offset:2048
	ds_read_b128 v[102:105], v102 offset:3072
	ds_read_b128 v[110:113], v158
	ds_read_b128 v[118:121], v158 offset:1024
	ds_read_b128 v[138:141], v158 offset:2048
	ds_read_b128 v[158:161], v158 offset:3072
	s_add_u32 s0, s30, 0x40000
	s_addc_u32 s1, s31, 0
	s_mov_b32 m0, s38
	v_lshl_add_u64 v[232:233], s[0:1], 0, v[180:181]
	ds_read_b128 v[162:165], v221 offset:32768
	ds_read_b128 v[166:169], v221 offset:33792
	ds_read_b128 v[170:173], v221 offset:34816
	ds_read_b128 v[174:177], v221 offset:35840
	ds_read_b128 v[198:201], v221 offset:36864
	ds_read_b128 v[202:205], v221 offset:37888
	ds_read_b128 v[206:209], v221 offset:38912
	ds_read_b128 v[210:213], v221 offset:39936
	global_load_lds_dwordx4 v[232:233], off
	v_lshl_add_u64 v[232:233], s[0:1], 0, v[184:185]
	s_mov_b32 m0, s39
	s_nop 0
	global_load_lds_dwordx4 v[232:233], off
	s_waitcnt vmcnt(8)
	s_waitcnt lgkmcnt(0)
	s_barrier
	s_setprio 1
	s_waitcnt lgkmcnt(0)
	v_mfma_f32_16x16x32_bf16 v[154:157], v[82:85], v[162:165], v[154:157]
	v_mfma_f32_16x16x32_bf16 v[134:137], v[82:85], v[170:173], v[134:137]
	v_mfma_f32_16x16x32_bf16 v[114:117], v[82:85], v[198:201], v[114:117]
	v_mfma_f32_16x16x32_bf16 v[78:81], v[82:85], v[206:209], v[78:81]
	v_mfma_f32_16x16x32_bf16 v[150:153], v[94:97], v[162:165], v[150:153]
	v_mfma_f32_16x16x32_bf16 v[130:133], v[94:97], v[170:173], v[130:133]
	v_mfma_f32_16x16x32_bf16 v[106:109], v[94:97], v[198:201], v[106:109]
	v_mfma_f32_16x16x32_bf16 v[74:77], v[94:97], v[206:209], v[74:77]
	v_mfma_f32_16x16x32_bf16 v[154:157], v[86:89], v[166:169], v[154:157]
	v_mfma_f32_16x16x32_bf16 v[134:137], v[86:89], v[174:177], v[134:137]
	v_mfma_f32_16x16x32_bf16 v[114:117], v[86:89], v[202:205], v[114:117]
	v_mfma_f32_16x16x32_bf16 v[78:81], v[86:89], v[210:213], v[78:81]
	v_mfma_f32_16x16x32_bf16 v[150:153], v[102:105], v[166:169], v[150:153]
	v_mfma_f32_16x16x32_bf16 v[130:133], v[102:105], v[174:177], v[130:133]
	v_mfma_f32_16x16x32_bf16 v[106:109], v[102:105], v[202:205], v[106:109]
	v_mfma_f32_16x16x32_bf16 v[74:77], v[102:105], v[210:213], v[74:77]
	s_setprio 0
	s_setprio 1
	v_mfma_f32_16x16x32_bf16 v[146:149], v[110:113], v[162:165], v[146:149]
	v_mfma_f32_16x16x32_bf16 v[126:129], v[110:113], v[170:173], v[126:129]
	v_mfma_f32_16x16x32_bf16 v[98:101], v[110:113], v[198:201], v[98:101]
	v_mfma_f32_16x16x32_bf16 v[70:73], v[110:113], v[206:209], v[70:73]
	v_mfma_f32_16x16x32_bf16 v[142:145], v[138:141], v[162:165], v[142:145]
	v_mfma_f32_16x16x32_bf16 v[122:125], v[138:141], v[170:173], v[122:125]
	v_mfma_f32_16x16x32_bf16 v[90:93], v[138:141], v[198:201], v[90:93]
	v_mfma_f32_16x16x32_bf16 v[66:69], v[138:141], v[206:209], v[66:69]
	v_mfma_f32_16x16x32_bf16 v[146:149], v[118:121], v[166:169], v[146:149]
	v_mfma_f32_16x16x32_bf16 v[126:129], v[118:121], v[174:177], v[126:129]
	v_mfma_f32_16x16x32_bf16 v[98:101], v[118:121], v[202:205], v[98:101]
	v_mfma_f32_16x16x32_bf16 v[70:73], v[118:121], v[210:213], v[70:73]
	v_mfma_f32_16x16x32_bf16 v[142:145], v[158:161], v[166:169], v[142:145]
	v_mfma_f32_16x16x32_bf16 v[122:125], v[158:161], v[174:177], v[122:125]
	v_mfma_f32_16x16x32_bf16 v[90:93], v[158:161], v[202:205], v[90:93]
	v_mfma_f32_16x16x32_bf16 v[66:69], v[158:161], v[210:213], v[66:69]
	s_setprio 0
	s_barrier
	s_add_i32 s0, s52, s36
	v_lshl_add_u64 v[224:225], v[224:225], 0, s[12:13]
	s_mov_b32 m0, s0
	ds_read_b128 v[162:165], v221 offset:49152
	ds_read_b128 v[166:169], v221 offset:50176
	ds_read_b128 v[170:173], v221 offset:51200
	ds_read_b128 v[174:177], v221 offset:52224
	ds_read_b128 v[198:201], v221 offset:53248
	ds_read_b128 v[202:205], v221 offset:54272
	ds_read_b128 v[206:209], v221 offset:55296
	ds_read_b128 v[210:213], v221 offset:56320
	global_load_lds_dwordx4 v[224:225], off
	s_add_i32 m0, s0, 0x2000
	s_add_u32 s0, s2, 0x40080
	v_lshl_add_u64 v[224:225], v[226:227], 0, s[12:13]
	s_addc_u32 s1, s3, 0
	s_add_i32 s2, s53, s36
	global_load_lds_dwordx4 v[224:225], off
	v_lshl_add_u64 v[224:225], s[0:1], 0, v[182:183]
	s_mov_b32 m0, s2
	s_nop 0
	global_load_lds_dwordx4 v[224:225], off
	v_lshl_add_u64 v[224:225], s[0:1], 0, v[186:187]
	s_add_i32 m0, s2, 0x2000
	s_nop 0
	global_load_lds_dwordx4 v[224:225], off
	v_lshl_add_u64 v[224:225], v[228:229], 0, s[12:13]
	s_mov_b32 m0, s44
	s_nop 0
	global_load_lds_dwordx4 v[224:225], off
	v_lshl_add_u64 v[224:225], v[230:231], 0, s[12:13]
	s_mov_b32 m0, s45
	s_nop 0
	global_load_lds_dwordx4 v[224:225], off
	s_waitcnt vmcnt(8)
	s_waitcnt lgkmcnt(0)
	s_barrier
	s_setprio 1
	s_waitcnt lgkmcnt(0)
	v_mfma_f32_16x16x32_bf16 v[62:65], v[82:85], v[162:165], v[62:65]
	v_mfma_f32_16x16x32_bf16 v[46:49], v[82:85], v[170:173], v[46:49]
	v_mfma_f32_16x16x32_bf16 v[30:33], v[82:85], v[198:201], v[30:33]
	v_mfma_f32_16x16x32_bf16 v[14:17], v[82:85], v[206:209], v[14:17]
	v_mfma_f32_16x16x32_bf16 v[58:61], v[94:97], v[162:165], v[58:61]
	v_mfma_f32_16x16x32_bf16 v[42:45], v[94:97], v[170:173], v[42:45]
	v_mfma_f32_16x16x32_bf16 v[26:29], v[94:97], v[198:201], v[26:29]
	v_mfma_f32_16x16x32_bf16 v[10:13], v[94:97], v[206:209], v[10:13]
	v_mfma_f32_16x16x32_bf16 v[62:65], v[86:89], v[166:169], v[62:65]
	v_mfma_f32_16x16x32_bf16 v[46:49], v[86:89], v[174:177], v[46:49]
	v_mfma_f32_16x16x32_bf16 v[30:33], v[86:89], v[202:205], v[30:33]
	v_mfma_f32_16x16x32_bf16 v[14:17], v[86:89], v[210:213], v[14:17]
	v_mfma_f32_16x16x32_bf16 v[58:61], v[102:105], v[166:169], v[58:61]
	v_mfma_f32_16x16x32_bf16 v[42:45], v[102:105], v[174:177], v[42:45]
	v_mfma_f32_16x16x32_bf16 v[26:29], v[102:105], v[202:205], v[26:29]
	v_mfma_f32_16x16x32_bf16 v[10:13], v[102:105], v[210:213], v[10:13]
	s_setprio 0
	s_setprio 1
	v_mfma_f32_16x16x32_bf16 v[54:57], v[110:113], v[162:165], v[54:57]
	v_mfma_f32_16x16x32_bf16 v[38:41], v[110:113], v[170:173], v[38:41]
	v_mfma_f32_16x16x32_bf16 v[22:25], v[110:113], v[198:201], v[22:25]
	v_mfma_f32_16x16x32_bf16 v[6:9], v[110:113], v[206:209], v[6:9]
	v_mfma_f32_16x16x32_bf16 v[50:53], v[138:141], v[162:165], v[50:53]
	v_mfma_f32_16x16x32_bf16 v[34:37], v[138:141], v[170:173], v[34:37]
	v_mfma_f32_16x16x32_bf16 v[18:21], v[138:141], v[198:201], v[18:21]
	v_mfma_f32_16x16x32_bf16 v[2:5], v[138:141], v[206:209], v[2:5]
	v_mfma_f32_16x16x32_bf16 v[54:57], v[118:121], v[166:169], v[54:57]
	v_mfma_f32_16x16x32_bf16 v[38:41], v[118:121], v[174:177], v[38:41]
	v_mfma_f32_16x16x32_bf16 v[22:25], v[118:121], v[202:205], v[22:25]
	v_mfma_f32_16x16x32_bf16 v[6:9], v[118:121], v[210:213], v[6:9]
	v_mfma_f32_16x16x32_bf16 v[50:53], v[158:161], v[166:169], v[50:53]
	v_mfma_f32_16x16x32_bf16 v[34:37], v[158:161], v[174:177], v[34:37]
	v_mfma_f32_16x16x32_bf16 v[18:21], v[158:161], v[202:205], v[18:21]
	v_mfma_f32_16x16x32_bf16 v[2:5], v[158:161], v[210:213], v[2:5]
	s_setprio 0
	s_barrier
	s_add_i32 s51, s51, 2
	s_add_u32 s8, s8, 0x100
	s_addc_u32 s9, s9, 0
	s_add_u32 s35, s35, 0x100
	s_addc_u32 s50, s50, 0
	s_cmp_gt_u32 s51, 13
	s_cbranch_scc0 .LBB0_675
	s_and_b64 vcc, exec, s[14:15]
	s_cbranch_vccz .LBB0_678
	s_barrier

.LBB0_920:
	ds_read_b128 v[130:133], v187
	ds_read_b128 v[134:137], v187 offset:1024
	ds_read_b128 v[138:141], v187 offset:2048
	ds_read_b128 v[142:145], v187 offset:3072
	ds_read_b128 v[146:149], v188
	ds_read_b128 v[150:153], v188 offset:1024
	ds_read_b128 v[170:173], v188 offset:2048
	ds_read_b128 v[174:177], v188 offset:3072
	s_add_u32 s0, s28, 0xfffc0080
	s_addc_u32 s1, s29, -1
	s_cmp_eq_u32 s51, 12
	s_cselect_b32 s31, s11, s1
	s_cselect_b32 s30, s21, s0
	s_cselect_b32 s3, s19, s50
	s_cselect_b32 s2, s48, s49
	v_lshl_add_u64 v[220:221], s[28:29], 0, v[162:163]
	s_add_i32 m0, s27, 0xc000
	ds_read_b128 v[178:181], v189
	ds_read_b128 v[192:195], v189 offset:1024
	ds_read_b128 v[196:199], v189 offset:2048
	ds_read_b128 v[200:203], v189 offset:3072
	ds_read_b128 v[204:207], v189 offset:4096
	ds_read_b128 v[208:211], v189 offset:5120
	ds_read_b128 v[212:215], v189 offset:6144
	ds_read_b128 v[216:219], v189 offset:7168
	global_load_lds_dwordx4 v[220:221], off
	v_lshl_add_u64 v[220:221], s[28:29], 0, v[164:165]
	s_add_i32 m0, s27, 0xe000
	s_nop 0
	global_load_lds_dwordx4 v[220:221], off
	s_waitcnt vmcnt(8)
	s_waitcnt lgkmcnt(0)
	s_barrier
	s_setprio 1
	s_waitcnt lgkmcnt(0)
	v_mfma_f32_16x16x32_bf16 v[126:129], v[130:133], v[178:181], v[126:129]
	v_mfma_f32_16x16x32_bf16 v[110:113], v[130:133], v[196:199], v[110:113]
	v_mfma_f32_16x16x32_bf16 v[94:97], v[130:133], v[204:207], v[94:97]
	v_mfma_f32_16x16x32_bf16 v[78:81], v[130:133], v[212:215], v[78:81]
	v_mfma_f32_16x16x32_bf16 v[122:125], v[138:141], v[178:181], v[122:125]
	v_mfma_f32_16x16x32_bf16 v[106:109], v[138:141], v[196:199], v[106:109]
	v_mfma_f32_16x16x32_bf16 v[90:93], v[138:141], v[204:207], v[90:93]
	v_mfma_f32_16x16x32_bf16 v[74:77], v[138:141], v[212:215], v[74:77]
	v_mfma_f32_16x16x32_bf16 v[126:129], v[134:137], v[192:195], v[126:129]
	v_mfma_f32_16x16x32_bf16 v[110:113], v[134:137], v[200:203], v[110:113]
	v_mfma_f32_16x16x32_bf16 v[94:97], v[134:137], v[208:211], v[94:97]
	v_mfma_f32_16x16x32_bf16 v[78:81], v[134:137], v[216:219], v[78:81]
	v_mfma_f32_16x16x32_bf16 v[122:125], v[142:145], v[192:195], v[122:125]
	v_mfma_f32_16x16x32_bf16 v[106:109], v[142:145], v[200:203], v[106:109]
	v_mfma_f32_16x16x32_bf16 v[90:93], v[142:145], v[208:211], v[90:93]
	v_mfma_f32_16x16x32_bf16 v[74:77], v[142:145], v[216:219], v[74:77]
	s_setprio 0
	s_setprio 1
	v_mfma_f32_16x16x32_bf16 v[118:121], v[146:149], v[178:181], v[118:121]
	v_mfma_f32_16x16x32_bf16 v[102:105], v[146:149], v[196:199], v[102:105]
	v_mfma_f32_16x16x32_bf16 v[86:89], v[146:149], v[204:207], v[86:89]
	v_mfma_f32_16x16x32_bf16 v[70:73], v[146:149], v[212:215], v[70:73]
	v_mfma_f32_16x16x32_bf16 v[114:117], v[170:173], v[178:181], v[114:117]
	v_mfma_f32_16x16x32_bf16 v[98:101], v[170:173], v[196:199], v[98:101]
	v_mfma_f32_16x16x32_bf16 v[82:85], v[170:173], v[204:207], v[82:85]
	v_mfma_f32_16x16x32_bf16 v[66:69], v[170:173], v[212:215], v[66:69]
	v_mfma_f32_16x16x32_bf16 v[118:121], v[150:153], v[192:195], v[118:121]
	v_mfma_f32_16x16x32_bf16 v[102:105], v[150:153], v[200:203], v[102:105]
	v_mfma_f32_16x16x32_bf16 v[86:89], v[150:153], v[208:211], v[86:89]
	v_mfma_f32_16x16x32_bf16 v[70:73], v[150:153], v[216:219], v[70:73]
	v_mfma_f32_16x16x32_bf16 v[114:117], v[174:177], v[192:195], v[114:117]
	v_mfma_f32_16x16x32_bf16 v[98:101], v[174:177], v[200:203], v[98:101]
	v_mfma_f32_16x16x32_bf16 v[82:85], v[174:177], v[208:211], v[82:85]
	v_mfma_f32_16x16x32_bf16 v[66:69], v[174:177], v[216:219], v[66:69]
	s_setprio 0
	s_barrier
	s_add_i32 s0, s46, s37
	v_lshl_add_u64 v[220:221], s[2:3], 0, v[156:157]
	s_mov_b32 m0, s0
	ds_read_b128 v[178:181], v189 offset:16384
	ds_read_b128 v[192:195], v189 offset:17408
	ds_read_b128 v[196:199], v189 offset:18432
	ds_read_b128 v[200:203], v189 offset:19456
	ds_read_b128 v[204:207], v189 offset:20480
	ds_read_b128 v[208:211], v189 offset:21504
	ds_read_b128 v[212:215], v189 offset:22528
	ds_read_b128 v[216:219], v189 offset:23552
	global_load_lds_dwordx4 v[220:221], off
	s_add_i32 m0, s0, 0x2000
	s_add_u32 s0, s2, 0x40000
	v_lshl_add_u64 v[222:223], s[2:3], 0, v[160:161]
	s_addc_u32 s1, s3, 0
	s_add_i32 s52, s47, s37
	global_load_lds_dwordx4 v[222:223], off
	v_lshl_add_u64 v[224:225], s[0:1], 0, v[156:157]
	s_mov_b32 m0, s52
	v_lshl_add_u64 v[226:227], s[30:31], 0, v[158:159]
	global_load_lds_dwordx4 v[224:225], off
	v_lshl_add_u64 v[224:225], s[0:1], 0, v[160:161]
	s_add_i32 m0, s52, 0x2000
	s_nop 0
	global_load_lds_dwordx4 v[224:225], off
	v_lshl_add_u64 v[224:225], s[30:31], 0, v[154:155]
	s_mov_b32 m0, s27
	s_nop 0
	global_load_lds_dwordx4 v[224:225], off
	s_mov_b32 m0, s38
	s_nop 0
	global_load_lds_dwordx4 v[226:227], off
	s_waitcnt vmcnt(8)
	s_waitcnt lgkmcnt(0)
	s_barrier
	s_setprio 1
	s_waitcnt lgkmcnt(0)
	v_mfma_f32_16x16x32_bf16 v[62:65], v[130:133], v[178:181], v[62:65]
	v_mfma_f32_16x16x32_bf16 v[46:49], v[130:133], v[196:199], v[46:49]
	v_mfma_f32_16x16x32_bf16 v[30:33], v[130:133], v[204:207], v[30:33]
	v_mfma_f32_16x16x32_bf16 v[14:17], v[130:133], v[212:215], v[14:17]
	v_mfma_f32_16x16x32_bf16 v[58:61], v[138:141], v[178:181], v[58:61]
	v_mfma_f32_16x16x32_bf16 v[42:45], v[138:141], v[196:199], v[42:45]
	v_mfma_f32_16x16x32_bf16 v[26:29], v[138:141], v[204:207], v[26:29]
	v_mfma_f32_16x16x32_bf16 v[10:13], v[138:141], v[212:215], v[10:13]
	v_mfma_f32_16x16x32_bf16 v[62:65], v[134:137], v[192:195], v[62:65]
	v_mfma_f32_16x16x32_bf16 v[46:49], v[134:137], v[200:203], v[46:49]
	v_mfma_f32_16x16x32_bf16 v[30:33], v[134:137], v[208:211], v[30:33]
	v_mfma_f32_16x16x32_bf16 v[14:17], v[134:137], v[216:219], v[14:17]
	v_mfma_f32_16x16x32_bf16 v[58:61], v[142:145], v[192:195], v[58:61]
	v_mfma_f32_16x16x32_bf16 v[42:45], v[142:145], v[200:203], v[42:45]
	v_mfma_f32_16x16x32_bf16 v[26:29], v[142:145], v[208:211], v[26:29]
	v_mfma_f32_16x16x32_bf16 v[10:13], v[142:145], v[216:219], v[10:13]
	s_setprio 0
	s_setprio 1
	v_mfma_f32_16x16x32_bf16 v[54:57], v[146:149], v[178:181], v[54:57]
	v_mfma_f32_16x16x32_bf16 v[38:41], v[146:149], v[196:199], v[38:41]
	v_mfma_f32_16x16x32_bf16 v[22:25], v[146:149], v[204:207], v[22:25]
	v_mfma_f32_16x16x32_bf16 v[6:9], v[146:149], v[212:215], v[6:9]
	v_mfma_f32_16x16x32_bf16 v[50:53], v[170:173], v[178:181], v[50:53]
	v_mfma_f32_16x16x32_bf16 v[34:37], v[170:173], v[196:199], v[34:37]
	v_mfma_f32_16x16x32_bf16 v[18:21], v[170:173], v[204:207], v[18:21]
	v_mfma_f32_16x16x32_bf16 v[2:5], v[170:173], v[212:215], v[2:5]
	v_mfma_f32_16x16x32_bf16 v[54:57], v[150:153], v[192:195], v[54:57]
	v_mfma_f32_16x16x32_bf16 v[38:41], v[150:153], v[200:203], v[38:41]
	v_mfma_f32_16x16x32_bf16 v[22:25], v[150:153], v[208:211], v[22:25]
	v_mfma_f32_16x16x32_bf16 v[6:9], v[150:153], v[216:219], v[6:9]
	v_mfma_f32_16x16x32_bf16 v[50:53], v[174:177], v[192:195], v[50:53]
	v_mfma_f32_16x16x32_bf16 v[34:37], v[174:177], v[200:203], v[34:37]
	v_mfma_f32_16x16x32_bf16 v[18:21], v[174:177], v[208:211], v[18:21]
	v_mfma_f32_16x16x32_bf16 v[2:5], v[174:177], v[216:219], v[2:5]
	s_setprio 0
	s_barrier
	s_add_i32 s52, 0, 0x18000
	s_add_i32 s53, 0, 0x1c000
	v_add_u32_e32 v142, s52, v183
	v_add_u32_e32 v174, s53, v183
	ds_read_b128 v[130:133], v142
	ds_read_b128 v[134:137], v142 offset:1024
	ds_read_b128 v[138:141], v142 offset:2048
	ds_read_b128 v[142:145], v142 offset:3072
	ds_read_b128 v[146:149], v174
	ds_read_b128 v[150:153], v174 offset:1024
	ds_read_b128 v[170:173], v174 offset:2048
	ds_read_b128 v[174:177], v174 offset:3072
	s_add_u32 s0, s30, 0x40000
	s_addc_u32 s1, s31, 0
	s_mov_b32 m0, s39
	v_lshl_add_u64 v[228:229], s[0:1], 0, v[154:155]
	ds_read_b128 v[178:181], v189 offset:32768
	ds_read_b128 v[192:195], v189 offset:33792
	ds_read_b128 v[196:199], v189 offset:34816
	ds_read_b128 v[200:203], v189 offset:35840
	ds_read_b128 v[204:207], v189 offset:36864
	ds_read_b128 v[208:211], v189 offset:37888
	ds_read_b128 v[212:215], v189 offset:38912
	ds_read_b128 v[216:219], v189 offset:39936
	global_load_lds_dwordx4 v[228:229], off
	v_lshl_add_u64 v[228:229], s[0:1], 0, v[158:159]
	s_mov_b32 m0, s40
	s_nop 0
	global_load_lds_dwordx4 v[228:229], off
	s_waitcnt vmcnt(8)
	s_waitcnt lgkmcnt(0)
	s_barrier
	s_setprio 1
	s_waitcnt lgkmcnt(0)
	v_mfma_f32_16x16x32_bf16 v[126:129], v[130:133], v[178:181], v[126:129]
	v_mfma_f32_16x16x32_bf16 v[110:113], v[130:133], v[196:199], v[110:113]
	v_mfma_f32_16x16x32_bf16 v[94:97], v[130:133], v[204:207], v[94:97]
	v_mfma_f32_16x16x32_bf16 v[78:81], v[130:133], v[212:215], v[78:81]
	v_mfma_f32_16x16x32_bf16 v[122:125], v[138:141], v[178:181], v[122:125]
	v_mfma_f32_16x16x32_bf16 v[106:109], v[138:141], v[196:199], v[106:109]
	v_mfma_f32_16x16x32_bf16 v[90:93], v[138:141], v[204:207], v[90:93]
	v_mfma_f32_16x16x32_bf16 v[74:77], v[138:141], v[212:215], v[74:77]
	v_mfma_f32_16x16x32_bf16 v[126:129], v[134:137], v[192:195], v[126:129]
	v_mfma_f32_16x16x32_bf16 v[110:113], v[134:137], v[200:203], v[110:113]
	v_mfma_f32_16x16x32_bf16 v[94:97], v[134:137], v[208:211], v[94:97]
	v_mfma_f32_16x16x32_bf16 v[78:81], v[134:137], v[216:219], v[78:81]
	v_mfma_f32_16x16x32_bf16 v[122:125], v[142:145], v[192:195], v[122:125]
	v_mfma_f32_16x16x32_bf16 v[106:109], v[142:145], v[200:203], v[106:109]
	v_mfma_f32_16x16x32_bf16 v[90:93], v[142:145], v[208:211], v[90:93]
	v_mfma_f32_16x16x32_bf16 v[74:77], v[142:145], v[216:219], v[74:77]
	s_setprio 0
	s_setprio 1
	v_mfma_f32_16x16x32_bf16 v[118:121], v[146:149], v[178:181], v[118:121]
	v_mfma_f32_16x16x32_bf16 v[102:105], v[146:149], v[196:199], v[102:105]
	v_mfma_f32_16x16x32_bf16 v[86:89], v[146:149], v[204:207], v[86:89]
	v_mfma_f32_16x16x32_bf16 v[70:73], v[146:149], v[212:215], v[70:73]
	v_mfma_f32_16x16x32_bf16 v[114:117], v[170:173], v[178:181], v[114:117]
	v_mfma_f32_16x16x32_bf16 v[98:101], v[170:173], v[196:199], v[98:101]
	v_mfma_f32_16x16x32_bf16 v[82:85], v[170:173], v[204:207], v[82:85]
	v_mfma_f32_16x16x32_bf16 v[66:69], v[170:173], v[212:215], v[66:69]
	v_mfma_f32_16x16x32_bf16 v[118:121], v[150:153], v[192:195], v[118:121]
	v_mfma_f32_16x16x32_bf16 v[102:105], v[150:153], v[200:203], v[102:105]
	v_mfma_f32_16x16x32_bf16 v[86:89], v[150:153], v[208:211], v[86:89]
	v_mfma_f32_16x16x32_bf16 v[70:73], v[150:153], v[216:219], v[70:73]
	v_mfma_f32_16x16x32_bf16 v[114:117], v[174:177], v[192:195], v[114:117]
	v_mfma_f32_16x16x32_bf16 v[98:101], v[174:177], v[200:203], v[98:101]
	v_mfma_f32_16x16x32_bf16 v[82:85], v[174:177], v[208:211], v[82:85]
	v_mfma_f32_16x16x32_bf16 v[66:69], v[174:177], v[216:219], v[66:69]
	s_setprio 0
	s_barrier
	s_add_i32 s0, s52, s37
	v_lshl_add_u64 v[220:221], v[220:221], 0, s[14:15]
	s_mov_b32 m0, s0
	ds_read_b128 v[178:181], v189 offset:49152
	ds_read_b128 v[192:195], v189 offset:50176
	ds_read_b128 v[196:199], v189 offset:51200
	ds_read_b128 v[200:203], v189 offset:52224
	ds_read_b128 v[204:207], v189 offset:53248
	ds_read_b128 v[208:211], v189 offset:54272
	ds_read_b128 v[212:215], v189 offset:55296
	ds_read_b128 v[216:219], v189 offset:56320
	global_load_lds_dwordx4 v[220:221], off
	s_add_i32 m0, s0, 0x2000
	s_add_u32 s0, s2, 0x40080
	v_lshl_add_u64 v[220:221], v[222:223], 0, s[14:15]
	s_addc_u32 s1, s3, 0
	s_add_i32 s2, s53, s37
	global_load_lds_dwordx4 v[220:221], off
	v_lshl_add_u64 v[220:221], s[0:1], 0, v[156:157]
	s_mov_b32 m0, s2
	s_nop 0
	global_load_lds_dwordx4 v[220:221], off
	v_lshl_add_u64 v[220:221], s[0:1], 0, v[160:161]
	s_add_i32 m0, s2, 0x2000
	s_nop 0
	global_load_lds_dwordx4 v[220:221], off
	v_lshl_add_u64 v[220:221], v[224:225], 0, s[14:15]
	s_mov_b32 m0, s42
	s_nop 0
	global_load_lds_dwordx4 v[220:221], off
	v_lshl_add_u64 v[220:221], v[226:227], 0, s[14:15]
	s_mov_b32 m0, s43
	s_nop 0
	global_load_lds_dwordx4 v[220:221], off
	s_waitcnt vmcnt(8)
	s_waitcnt lgkmcnt(0)
	s_barrier
	s_setprio 1
	s_waitcnt lgkmcnt(0)
	v_mfma_f32_16x16x32_bf16 v[62:65], v[130:133], v[178:181], v[62:65]
	v_mfma_f32_16x16x32_bf16 v[46:49], v[130:133], v[196:199], v[46:49]
	v_mfma_f32_16x16x32_bf16 v[30:33], v[130:133], v[204:207], v[30:33]
	v_mfma_f32_16x16x32_bf16 v[14:17], v[130:133], v[212:215], v[14:17]
	v_mfma_f32_16x16x32_bf16 v[58:61], v[138:141], v[178:181], v[58:61]
	v_mfma_f32_16x16x32_bf16 v[42:45], v[138:141], v[196:199], v[42:45]
	v_mfma_f32_16x16x32_bf16 v[26:29], v[138:141], v[204:207], v[26:29]
	v_mfma_f32_16x16x32_bf16 v[10:13], v[138:141], v[212:215], v[10:13]
	v_mfma_f32_16x16x32_bf16 v[62:65], v[134:137], v[192:195], v[62:65]
	v_mfma_f32_16x16x32_bf16 v[46:49], v[134:137], v[200:203], v[46:49]
	v_mfma_f32_16x16x32_bf16 v[30:33], v[134:137], v[208:211], v[30:33]
	v_mfma_f32_16x16x32_bf16 v[14:17], v[134:137], v[216:219], v[14:17]
	v_mfma_f32_16x16x32_bf16 v[58:61], v[142:145], v[192:195], v[58:61]
	v_mfma_f32_16x16x32_bf16 v[42:45], v[142:145], v[200:203], v[42:45]
	v_mfma_f32_16x16x32_bf16 v[26:29], v[142:145], v[208:211], v[26:29]
	v_mfma_f32_16x16x32_bf16 v[10:13], v[142:145], v[216:219], v[10:13]
	s_setprio 0
	s_setprio 1
	v_mfma_f32_16x16x32_bf16 v[54:57], v[146:149], v[178:181], v[54:57]
	v_mfma_f32_16x16x32_bf16 v[38:41], v[146:149], v[196:199], v[38:41]
	v_mfma_f32_16x16x32_bf16 v[22:25], v[146:149], v[204:207], v[22:25]
	v_mfma_f32_16x16x32_bf16 v[6:9], v[146:149], v[212:215], v[6:9]
	v_mfma_f32_16x16x32_bf16 v[50:53], v[170:173], v[178:181], v[50:53]
	v_mfma_f32_16x16x32_bf16 v[34:37], v[170:173], v[196:199], v[34:37]
	v_mfma_f32_16x16x32_bf16 v[18:21], v[170:173], v[204:207], v[18:21]
	v_mfma_f32_16x16x32_bf16 v[2:5], v[170:173], v[212:215], v[2:5]
	v_mfma_f32_16x16x32_bf16 v[54:57], v[150:153], v[192:195], v[54:57]
	v_mfma_f32_16x16x32_bf16 v[38:41], v[150:153], v[200:203], v[38:41]
	v_mfma_f32_16x16x32_bf16 v[22:25], v[150:153], v[208:211], v[22:25]
	v_mfma_f32_16x16x32_bf16 v[6:9], v[150:153], v[216:219], v[6:9]
	v_mfma_f32_16x16x32_bf16 v[50:53], v[174:177], v[192:195], v[50:53]
	v_mfma_f32_16x16x32_bf16 v[34:37], v[174:177], v[200:203], v[34:37]
	v_mfma_f32_16x16x32_bf16 v[18:21], v[174:177], v[208:211], v[18:21]
	v_mfma_f32_16x16x32_bf16 v[2:5], v[174:177], v[216:219], v[2:5]
	s_setprio 0
	s_barrier
	s_add_i32 s51, s51, 2
	s_add_u32 s28, s28, 0x100
	s_addc_u32 s29, s29, 0
	s_add_u32 s49, s49, 0x100
	s_addc_u32 s50, s50, 0
	s_cmp_gt_u32 s51, 13
	s_cbranch_scc0 .LBB0_920
	s_and_b64 vcc, exec, s[16:17]
	s_cbranch_vccz .LBB0_923
	s_barrier

.LBB0_1009:
	ds_read_b128 v[148:151], v167
	ds_read_b128 v[152:155], v167 offset:1024
	ds_read_b128 v[156:159], v167 offset:2048
	ds_read_b128 v[160:163], v167 offset:3072
	ds_read_b128 v[172:175], v168
	ds_read_b128 v[176:179], v168 offset:1024
	ds_read_b128 v[180:183], v168 offset:2048
	ds_read_b128 v[184:187], v168 offset:3072
	s_add_u32 s0, s28, 0xfffc0080
	s_addc_u32 s1, s29, -1
	s_cmp_eq_u32 s53, 12
	s_cselect_b32 s31, s21, s1
	s_cselect_b32 s30, s49, s0
	s_cselect_b32 s3, s19, s52
	s_cselect_b32 s2, s50, s51
	v_lshl_add_u64 v[220:221], s[28:29], 0, v[140:141]
	s_add_i32 m0, s27, 0xc000
	ds_read_b128 v[188:191], v169
	ds_read_b128 v[192:195], v169 offset:1024
	ds_read_b128 v[196:199], v169 offset:2048
	ds_read_b128 v[200:203], v169 offset:3072
	ds_read_b128 v[204:207], v169 offset:4096
	ds_read_b128 v[208:211], v169 offset:5120
	ds_read_b128 v[212:215], v169 offset:6144
	ds_read_b128 v[216:219], v169 offset:7168
	global_load_lds_dwordx4 v[220:221], off
	v_lshl_add_u64 v[220:221], s[28:29], 0, v[142:143]
	s_add_i32 m0, s27, 0xe000
	s_nop 0
	global_load_lds_dwordx4 v[220:221], off
	s_waitcnt vmcnt(8)
	s_waitcnt lgkmcnt(0)
	s_barrier
	s_setprio 1
	s_waitcnt lgkmcnt(0)
	v_mfma_f32_16x16x32_bf16 v[126:129], v[148:151], v[188:191], v[126:129]
	v_mfma_f32_16x16x32_bf16 v[110:113], v[148:151], v[196:199], v[110:113]
	v_mfma_f32_16x16x32_bf16 v[94:97], v[148:151], v[204:207], v[94:97]
	v_mfma_f32_16x16x32_bf16 v[78:81], v[148:151], v[212:215], v[78:81]
	v_mfma_f32_16x16x32_bf16 v[118:121], v[156:159], v[188:191], v[118:121]
	v_mfma_f32_16x16x32_bf16 v[102:105], v[156:159], v[196:199], v[102:105]
	v_mfma_f32_16x16x32_bf16 v[86:89], v[156:159], v[204:207], v[86:89]
	v_mfma_f32_16x16x32_bf16 v[70:73], v[156:159], v[212:215], v[70:73]
	v_mfma_f32_16x16x32_bf16 v[126:129], v[152:155], v[192:195], v[126:129]
	v_mfma_f32_16x16x32_bf16 v[110:113], v[152:155], v[200:203], v[110:113]
	v_mfma_f32_16x16x32_bf16 v[94:97], v[152:155], v[208:211], v[94:97]
	v_mfma_f32_16x16x32_bf16 v[78:81], v[152:155], v[216:219], v[78:81]
	v_mfma_f32_16x16x32_bf16 v[118:121], v[160:163], v[192:195], v[118:121]
	v_mfma_f32_16x16x32_bf16 v[102:105], v[160:163], v[200:203], v[102:105]
	v_mfma_f32_16x16x32_bf16 v[86:89], v[160:163], v[208:211], v[86:89]
	v_mfma_f32_16x16x32_bf16 v[70:73], v[160:163], v[216:219], v[70:73]
	s_setprio 0
	s_setprio 1
	v_mfma_f32_16x16x32_bf16 v[122:125], v[172:175], v[188:191], v[122:125]
	v_mfma_f32_16x16x32_bf16 v[106:109], v[172:175], v[196:199], v[106:109]
	v_mfma_f32_16x16x32_bf16 v[90:93], v[172:175], v[204:207], v[90:93]
	v_mfma_f32_16x16x32_bf16 v[74:77], v[172:175], v[212:215], v[74:77]
	v_mfma_f32_16x16x32_bf16 v[114:117], v[180:183], v[188:191], v[114:117]
	v_mfma_f32_16x16x32_bf16 v[98:101], v[180:183], v[196:199], v[98:101]
	v_mfma_f32_16x16x32_bf16 v[82:85], v[180:183], v[204:207], v[82:85]
	v_mfma_f32_16x16x32_bf16 v[66:69], v[180:183], v[212:215], v[66:69]
	v_mfma_f32_16x16x32_bf16 v[122:125], v[176:179], v[192:195], v[122:125]
	v_mfma_f32_16x16x32_bf16 v[106:109], v[176:179], v[200:203], v[106:109]
	v_mfma_f32_16x16x32_bf16 v[90:93], v[176:179], v[208:211], v[90:93]
	v_mfma_f32_16x16x32_bf16 v[74:77], v[176:179], v[216:219], v[74:77]
	v_mfma_f32_16x16x32_bf16 v[114:117], v[184:187], v[192:195], v[114:117]
	v_mfma_f32_16x16x32_bf16 v[98:101], v[184:187], v[200:203], v[98:101]
	v_mfma_f32_16x16x32_bf16 v[82:85], v[184:187], v[208:211], v[82:85]
	v_mfma_f32_16x16x32_bf16 v[66:69], v[184:187], v[216:219], v[66:69]
	s_setprio 0
	s_barrier
	s_add_i32 s0, s44, s35
	v_lshl_add_u64 v[220:221], s[2:3], 0, v[134:135]
	s_mov_b32 m0, s0
	ds_read_b128 v[188:191], v169 offset:16384
	ds_read_b128 v[192:195], v169 offset:17408
	ds_read_b128 v[196:199], v169 offset:18432
	ds_read_b128 v[200:203], v169 offset:19456
	ds_read_b128 v[204:207], v169 offset:20480
	ds_read_b128 v[208:211], v169 offset:21504
	ds_read_b128 v[212:215], v169 offset:22528
	ds_read_b128 v[216:219], v169 offset:23552
	global_load_lds_dwordx4 v[220:221], off
	s_add_i32 m0, s0, 0x2000
	s_add_u32 s0, s2, 0x40000
	v_lshl_add_u64 v[222:223], s[2:3], 0, v[130:131]
	s_addc_u32 s1, s3, 0
	s_add_i32 s54, s45, s35
	global_load_lds_dwordx4 v[222:223], off
	v_lshl_add_u64 v[224:225], s[0:1], 0, v[134:135]
	s_mov_b32 m0, s54
	v_lshl_add_u64 v[226:227], s[30:31], 0, v[132:133]
	global_load_lds_dwordx4 v[224:225], off
	v_lshl_add_u64 v[224:225], s[0:1], 0, v[130:131]
	s_add_i32 m0, s54, 0x2000
	s_nop 0
	global_load_lds_dwordx4 v[224:225], off
	v_lshl_add_u64 v[224:225], s[30:31], 0, v[136:137]
	s_mov_b32 m0, s27
	s_nop 0
	global_load_lds_dwordx4 v[224:225], off
	s_mov_b32 m0, s38
	s_nop 0
	global_load_lds_dwordx4 v[226:227], off
	s_waitcnt vmcnt(8)
	s_waitcnt lgkmcnt(0)
	s_barrier
	s_setprio 1
	s_waitcnt lgkmcnt(0)
	v_mfma_f32_16x16x32_bf16 v[62:65], v[148:151], v[188:191], v[62:65]
	v_mfma_f32_16x16x32_bf16 v[46:49], v[148:151], v[196:199], v[46:49]
	v_mfma_f32_16x16x32_bf16 v[30:33], v[148:151], v[204:207], v[30:33]
	v_mfma_f32_16x16x32_bf16 v[14:17], v[148:151], v[212:215], v[14:17]
	v_mfma_f32_16x16x32_bf16 v[54:57], v[156:159], v[188:191], v[54:57]
	v_mfma_f32_16x16x32_bf16 v[38:41], v[156:159], v[196:199], v[38:41]
	v_mfma_f32_16x16x32_bf16 v[22:25], v[156:159], v[204:207], v[22:25]
	v_mfma_f32_16x16x32_bf16 v[6:9], v[156:159], v[212:215], v[6:9]
	v_mfma_f32_16x16x32_bf16 v[62:65], v[152:155], v[192:195], v[62:65]
	v_mfma_f32_16x16x32_bf16 v[46:49], v[152:155], v[200:203], v[46:49]
	v_mfma_f32_16x16x32_bf16 v[30:33], v[152:155], v[208:211], v[30:33]
	v_mfma_f32_16x16x32_bf16 v[14:17], v[152:155], v[216:219], v[14:17]
	v_mfma_f32_16x16x32_bf16 v[54:57], v[160:163], v[192:195], v[54:57]
	v_mfma_f32_16x16x32_bf16 v[38:41], v[160:163], v[200:203], v[38:41]
	v_mfma_f32_16x16x32_bf16 v[22:25], v[160:163], v[208:211], v[22:25]
	v_mfma_f32_16x16x32_bf16 v[6:9], v[160:163], v[216:219], v[6:9]
	s_setprio 0
	s_setprio 1
	v_mfma_f32_16x16x32_bf16 v[58:61], v[172:175], v[188:191], v[58:61]
	v_mfma_f32_16x16x32_bf16 v[42:45], v[172:175], v[196:199], v[42:45]
	v_mfma_f32_16x16x32_bf16 v[26:29], v[172:175], v[204:207], v[26:29]
	v_mfma_f32_16x16x32_bf16 v[10:13], v[172:175], v[212:215], v[10:13]
	v_mfma_f32_16x16x32_bf16 v[50:53], v[180:183], v[188:191], v[50:53]
	v_mfma_f32_16x16x32_bf16 v[34:37], v[180:183], v[196:199], v[34:37]
	v_mfma_f32_16x16x32_bf16 v[18:21], v[180:183], v[204:207], v[18:21]
	v_mfma_f32_16x16x32_bf16 v[2:5], v[180:183], v[212:215], v[2:5]
	v_mfma_f32_16x16x32_bf16 v[58:61], v[176:179], v[192:195], v[58:61]
	v_mfma_f32_16x16x32_bf16 v[42:45], v[176:179], v[200:203], v[42:45]
	v_mfma_f32_16x16x32_bf16 v[26:29], v[176:179], v[208:211], v[26:29]
	v_mfma_f32_16x16x32_bf16 v[10:13], v[176:179], v[216:219], v[10:13]
	v_mfma_f32_16x16x32_bf16 v[50:53], v[184:187], v[192:195], v[50:53]
	v_mfma_f32_16x16x32_bf16 v[34:37], v[184:187], v[200:203], v[34:37]
	v_mfma_f32_16x16x32_bf16 v[18:21], v[184:187], v[208:211], v[18:21]
	v_mfma_f32_16x16x32_bf16 v[2:5], v[184:187], v[216:219], v[2:5]
	s_setprio 0
	s_barrier
	s_add_i32 s54, 0, 0x18000
	s_add_i32 s55, 0, 0x1c000
	v_add_u32_e32 v160, s54, v166
	v_add_u32_e32 v171, s55, v166
	ds_read_b128 v[148:151], v160
	ds_read_b128 v[152:155], v160 offset:1024
	ds_read_b128 v[156:159], v160 offset:2048
	ds_read_b128 v[160:163], v160 offset:3072
	ds_read_b128 v[172:175], v171
	ds_read_b128 v[176:179], v171 offset:1024
	ds_read_b128 v[180:183], v171 offset:2048
	ds_read_b128 v[184:187], v171 offset:3072
	s_add_u32 s0, s30, 0x40000
	s_addc_u32 s1, s31, 0
	s_mov_b32 m0, s39
	v_lshl_add_u64 v[228:229], s[0:1], 0, v[136:137]
	ds_read_b128 v[188:191], v169 offset:32768
	ds_read_b128 v[192:195], v169 offset:33792
	ds_read_b128 v[196:199], v169 offset:34816
	ds_read_b128 v[200:203], v169 offset:35840
	ds_read_b128 v[204:207], v169 offset:36864
	ds_read_b128 v[208:211], v169 offset:37888
	ds_read_b128 v[212:215], v169 offset:38912
	ds_read_b128 v[216:219], v169 offset:39936
	global_load_lds_dwordx4 v[228:229], off
	v_lshl_add_u64 v[228:229], s[0:1], 0, v[132:133]
	s_mov_b32 m0, s40
	s_nop 0
	global_load_lds_dwordx4 v[228:229], off
	s_waitcnt vmcnt(8)
	s_waitcnt lgkmcnt(0)
	s_barrier
	s_setprio 1
	s_waitcnt lgkmcnt(0)
	v_mfma_f32_16x16x32_bf16 v[126:129], v[148:151], v[188:191], v[126:129]
	v_mfma_f32_16x16x32_bf16 v[110:113], v[148:151], v[196:199], v[110:113]
	v_mfma_f32_16x16x32_bf16 v[94:97], v[148:151], v[204:207], v[94:97]
	v_mfma_f32_16x16x32_bf16 v[78:81], v[148:151], v[212:215], v[78:81]
	v_mfma_f32_16x16x32_bf16 v[118:121], v[156:159], v[188:191], v[118:121]
	v_mfma_f32_16x16x32_bf16 v[102:105], v[156:159], v[196:199], v[102:105]
	v_mfma_f32_16x16x32_bf16 v[86:89], v[156:159], v[204:207], v[86:89]
	v_mfma_f32_16x16x32_bf16 v[70:73], v[156:159], v[212:215], v[70:73]
	v_mfma_f32_16x16x32_bf16 v[126:129], v[152:155], v[192:195], v[126:129]
	v_mfma_f32_16x16x32_bf16 v[110:113], v[152:155], v[200:203], v[110:113]
	v_mfma_f32_16x16x32_bf16 v[94:97], v[152:155], v[208:211], v[94:97]
	v_mfma_f32_16x16x32_bf16 v[78:81], v[152:155], v[216:219], v[78:81]
	v_mfma_f32_16x16x32_bf16 v[118:121], v[160:163], v[192:195], v[118:121]
	v_mfma_f32_16x16x32_bf16 v[102:105], v[160:163], v[200:203], v[102:105]
	v_mfma_f32_16x16x32_bf16 v[86:89], v[160:163], v[208:211], v[86:89]
	v_mfma_f32_16x16x32_bf16 v[70:73], v[160:163], v[216:219], v[70:73]
	s_setprio 0
	s_setprio 1
	v_mfma_f32_16x16x32_bf16 v[122:125], v[172:175], v[188:191], v[122:125]
	v_mfma_f32_16x16x32_bf16 v[106:109], v[172:175], v[196:199], v[106:109]
	v_mfma_f32_16x16x32_bf16 v[90:93], v[172:175], v[204:207], v[90:93]
	v_mfma_f32_16x16x32_bf16 v[74:77], v[172:175], v[212:215], v[74:77]
	v_mfma_f32_16x16x32_bf16 v[114:117], v[180:183], v[188:191], v[114:117]
	v_mfma_f32_16x16x32_bf16 v[98:101], v[180:183], v[196:199], v[98:101]
	v_mfma_f32_16x16x32_bf16 v[82:85], v[180:183], v[204:207], v[82:85]
	v_mfma_f32_16x16x32_bf16 v[66:69], v[180:183], v[212:215], v[66:69]
	v_mfma_f32_16x16x32_bf16 v[122:125], v[176:179], v[192:195], v[122:125]
	v_mfma_f32_16x16x32_bf16 v[106:109], v[176:179], v[200:203], v[106:109]
	v_mfma_f32_16x16x32_bf16 v[90:93], v[176:179], v[208:211], v[90:93]
	v_mfma_f32_16x16x32_bf16 v[74:77], v[176:179], v[216:219], v[74:77]
	v_mfma_f32_16x16x32_bf16 v[114:117], v[184:187], v[192:195], v[114:117]
	v_mfma_f32_16x16x32_bf16 v[98:101], v[184:187], v[200:203], v[98:101]
	v_mfma_f32_16x16x32_bf16 v[82:85], v[184:187], v[208:211], v[82:85]
	v_mfma_f32_16x16x32_bf16 v[66:69], v[184:187], v[216:219], v[66:69]
	s_setprio 0
	s_barrier
	s_add_i32 s0, s54, s35
	v_lshl_add_u64 v[220:221], v[220:221], 0, s[14:15]
	s_mov_b32 m0, s0
	ds_read_b128 v[188:191], v169 offset:49152
	ds_read_b128 v[192:195], v169 offset:50176
	ds_read_b128 v[196:199], v169 offset:51200
	ds_read_b128 v[200:203], v169 offset:52224
	ds_read_b128 v[204:207], v169 offset:53248
	ds_read_b128 v[208:211], v169 offset:54272
	ds_read_b128 v[212:215], v169 offset:55296
	ds_read_b128 v[216:219], v169 offset:56320
	global_load_lds_dwordx4 v[220:221], off
	s_add_i32 m0, s0, 0x2000
	s_add_u32 s0, s2, 0x40080
	v_lshl_add_u64 v[220:221], v[222:223], 0, s[14:15]
	s_addc_u32 s1, s3, 0
	s_add_i32 s2, s55, s35
	global_load_lds_dwordx4 v[220:221], off
	v_lshl_add_u64 v[220:221], s[0:1], 0, v[134:135]
	s_mov_b32 m0, s2
	s_nop 0
	global_load_lds_dwordx4 v[220:221], off
	v_lshl_add_u64 v[220:221], s[0:1], 0, v[130:131]
	s_add_i32 m0, s2, 0x2000
	s_nop 0
	global_load_lds_dwordx4 v[220:221], off
	v_lshl_add_u64 v[220:221], v[224:225], 0, s[14:15]
	s_mov_b32 m0, s41
	s_nop 0
	global_load_lds_dwordx4 v[220:221], off
	v_lshl_add_u64 v[220:221], v[226:227], 0, s[14:15]
	s_mov_b32 m0, s42
	s_nop 0
	global_load_lds_dwordx4 v[220:221], off
	s_waitcnt vmcnt(8)
	s_waitcnt lgkmcnt(0)
	s_barrier
	s_setprio 1
	s_waitcnt lgkmcnt(0)
	v_mfma_f32_16x16x32_bf16 v[62:65], v[148:151], v[188:191], v[62:65]
	v_mfma_f32_16x16x32_bf16 v[46:49], v[148:151], v[196:199], v[46:49]
	v_mfma_f32_16x16x32_bf16 v[30:33], v[148:151], v[204:207], v[30:33]
	v_mfma_f32_16x16x32_bf16 v[14:17], v[148:151], v[212:215], v[14:17]
	v_mfma_f32_16x16x32_bf16 v[54:57], v[156:159], v[188:191], v[54:57]
	v_mfma_f32_16x16x32_bf16 v[38:41], v[156:159], v[196:199], v[38:41]
	v_mfma_f32_16x16x32_bf16 v[22:25], v[156:159], v[204:207], v[22:25]
	v_mfma_f32_16x16x32_bf16 v[6:9], v[156:159], v[212:215], v[6:9]
	v_mfma_f32_16x16x32_bf16 v[62:65], v[152:155], v[192:195], v[62:65]
	v_mfma_f32_16x16x32_bf16 v[46:49], v[152:155], v[200:203], v[46:49]
	v_mfma_f32_16x16x32_bf16 v[30:33], v[152:155], v[208:211], v[30:33]
	v_mfma_f32_16x16x32_bf16 v[14:17], v[152:155], v[216:219], v[14:17]
	v_mfma_f32_16x16x32_bf16 v[54:57], v[160:163], v[192:195], v[54:57]
	v_mfma_f32_16x16x32_bf16 v[38:41], v[160:163], v[200:203], v[38:41]
	v_mfma_f32_16x16x32_bf16 v[22:25], v[160:163], v[208:211], v[22:25]
	v_mfma_f32_16x16x32_bf16 v[6:9], v[160:163], v[216:219], v[6:9]
	s_setprio 0
	s_setprio 1
	v_mfma_f32_16x16x32_bf16 v[58:61], v[172:175], v[188:191], v[58:61]
	v_mfma_f32_16x16x32_bf16 v[42:45], v[172:175], v[196:199], v[42:45]
	v_mfma_f32_16x16x32_bf16 v[26:29], v[172:175], v[204:207], v[26:29]
	v_mfma_f32_16x16x32_bf16 v[10:13], v[172:175], v[212:215], v[10:13]
	v_mfma_f32_16x16x32_bf16 v[50:53], v[180:183], v[188:191], v[50:53]
	v_mfma_f32_16x16x32_bf16 v[34:37], v[180:183], v[196:199], v[34:37]
	v_mfma_f32_16x16x32_bf16 v[18:21], v[180:183], v[204:207], v[18:21]
	v_mfma_f32_16x16x32_bf16 v[2:5], v[180:183], v[212:215], v[2:5]
	v_mfma_f32_16x16x32_bf16 v[58:61], v[176:179], v[192:195], v[58:61]
	v_mfma_f32_16x16x32_bf16 v[42:45], v[176:179], v[200:203], v[42:45]
	v_mfma_f32_16x16x32_bf16 v[26:29], v[176:179], v[208:211], v[26:29]
	v_mfma_f32_16x16x32_bf16 v[10:13], v[176:179], v[216:219], v[10:13]
	v_mfma_f32_16x16x32_bf16 v[50:53], v[184:187], v[192:195], v[50:53]
	v_mfma_f32_16x16x32_bf16 v[34:37], v[184:187], v[200:203], v[34:37]
	v_mfma_f32_16x16x32_bf16 v[18:21], v[184:187], v[208:211], v[18:21]
	v_mfma_f32_16x16x32_bf16 v[2:5], v[184:187], v[216:219], v[2:5]
	s_setprio 0
	s_barrier
	s_add_i32 s53, s53, 2
	s_add_u32 s28, s28, 0x100
	s_addc_u32 s29, s29, 0
	s_add_u32 s51, s51, 0x100
	s_addc_u32 s52, s52, 0
	s_cmp_gt_u32 s53, 13
	s_cbranch_scc0 .LBB0_1009
	s_and_b64 vcc, exec, s[16:17]
	s_cbranch_vccz .LBB0_1012
	s_barrier

.LBB0_1123:
	ds_read_b128 v[130:133], v187
	ds_read_b128 v[134:137], v187 offset:1024
	ds_read_b128 v[138:141], v187 offset:2048
	ds_read_b128 v[142:145], v187 offset:3072
	ds_read_b128 v[146:149], v188
	ds_read_b128 v[150:153], v188 offset:1024
	ds_read_b128 v[170:173], v188 offset:2048
	ds_read_b128 v[174:177], v188 offset:3072
	s_add_u32 s0, s24, 0xfff50080
	s_addc_u32 s1, s25, -1
	s_cmp_eq_u32 s49, 40
	s_cselect_b32 s27, s9, s1
	s_cselect_b32 s26, s8, s0
	s_cselect_b32 s3, s23, s48
	s_cselect_b32 s2, s22, s47
	v_lshl_add_u64 v[220:221], s[24:25], 0, v[162:163]
	s_add_i32 m0, s34, 0xc000
	ds_read_b128 v[178:181], v189
	ds_read_b128 v[192:195], v189 offset:1024
	ds_read_b128 v[196:199], v189 offset:2048
	ds_read_b128 v[200:203], v189 offset:3072
	ds_read_b128 v[204:207], v189 offset:4096
	ds_read_b128 v[208:211], v189 offset:5120
	ds_read_b128 v[212:215], v189 offset:6144
	ds_read_b128 v[216:219], v189 offset:7168
	global_load_lds_dwordx4 v[220:221], off
	v_lshl_add_u64 v[220:221], s[24:25], 0, v[164:165]
	s_add_i32 m0, s34, 0xe000
	s_nop 0
	global_load_lds_dwordx4 v[220:221], off
	s_waitcnt vmcnt(8)
	s_waitcnt lgkmcnt(0)
	s_barrier
	s_setprio 1
	s_waitcnt lgkmcnt(0)
	v_mfma_f32_16x16x32_bf16 v[126:129], v[130:133], v[178:181], v[126:129]
	v_mfma_f32_16x16x32_bf16 v[110:113], v[130:133], v[196:199], v[110:113]
	v_mfma_f32_16x16x32_bf16 v[94:97], v[130:133], v[204:207], v[94:97]
	v_mfma_f32_16x16x32_bf16 v[78:81], v[130:133], v[212:215], v[78:81]
	v_mfma_f32_16x16x32_bf16 v[122:125], v[138:141], v[178:181], v[122:125]
	v_mfma_f32_16x16x32_bf16 v[106:109], v[138:141], v[196:199], v[106:109]
	v_mfma_f32_16x16x32_bf16 v[90:93], v[138:141], v[204:207], v[90:93]
	v_mfma_f32_16x16x32_bf16 v[74:77], v[138:141], v[212:215], v[74:77]
	v_mfma_f32_16x16x32_bf16 v[126:129], v[134:137], v[192:195], v[126:129]
	v_mfma_f32_16x16x32_bf16 v[110:113], v[134:137], v[200:203], v[110:113]
	v_mfma_f32_16x16x32_bf16 v[94:97], v[134:137], v[208:211], v[94:97]
	v_mfma_f32_16x16x32_bf16 v[78:81], v[134:137], v[216:219], v[78:81]
	v_mfma_f32_16x16x32_bf16 v[122:125], v[142:145], v[192:195], v[122:125]
	v_mfma_f32_16x16x32_bf16 v[106:109], v[142:145], v[200:203], v[106:109]
	v_mfma_f32_16x16x32_bf16 v[90:93], v[142:145], v[208:211], v[90:93]
	v_mfma_f32_16x16x32_bf16 v[74:77], v[142:145], v[216:219], v[74:77]
	s_setprio 0
	s_setprio 1
	v_mfma_f32_16x16x32_bf16 v[118:121], v[146:149], v[178:181], v[118:121]
	v_mfma_f32_16x16x32_bf16 v[102:105], v[146:149], v[196:199], v[102:105]
	v_mfma_f32_16x16x32_bf16 v[86:89], v[146:149], v[204:207], v[86:89]
	v_mfma_f32_16x16x32_bf16 v[70:73], v[146:149], v[212:215], v[70:73]
	v_mfma_f32_16x16x32_bf16 v[114:117], v[170:173], v[178:181], v[114:117]
	v_mfma_f32_16x16x32_bf16 v[98:101], v[170:173], v[196:199], v[98:101]
	v_mfma_f32_16x16x32_bf16 v[82:85], v[170:173], v[204:207], v[82:85]
	v_mfma_f32_16x16x32_bf16 v[66:69], v[170:173], v[212:215], v[66:69]
	v_mfma_f32_16x16x32_bf16 v[118:121], v[150:153], v[192:195], v[118:121]
	v_mfma_f32_16x16x32_bf16 v[102:105], v[150:153], v[200:203], v[102:105]
	v_mfma_f32_16x16x32_bf16 v[86:89], v[150:153], v[208:211], v[86:89]
	v_mfma_f32_16x16x32_bf16 v[70:73], v[150:153], v[216:219], v[70:73]
	v_mfma_f32_16x16x32_bf16 v[114:117], v[174:177], v[192:195], v[114:117]
	v_mfma_f32_16x16x32_bf16 v[98:101], v[174:177], v[200:203], v[98:101]
	v_mfma_f32_16x16x32_bf16 v[82:85], v[174:177], v[208:211], v[82:85]
	v_mfma_f32_16x16x32_bf16 v[66:69], v[174:177], v[216:219], v[66:69]
	s_setprio 0
	s_barrier
	s_add_i32 s0, s43, s33
	v_lshl_add_u64 v[220:221], s[2:3], 0, v[156:157]
	s_mov_b32 m0, s0
	ds_read_b128 v[178:181], v189 offset:16384
	ds_read_b128 v[192:195], v189 offset:17408
	ds_read_b128 v[196:199], v189 offset:18432
	ds_read_b128 v[200:203], v189 offset:19456
	ds_read_b128 v[204:207], v189 offset:20480
	ds_read_b128 v[208:211], v189 offset:21504
	ds_read_b128 v[212:215], v189 offset:22528
	ds_read_b128 v[216:219], v189 offset:23552
	global_load_lds_dwordx4 v[220:221], off
	s_add_i32 m0, s0, 0x2000
	s_add_u32 s0, s2, 0xb0000
	v_lshl_add_u64 v[222:223], s[2:3], 0, v[160:161]
	s_addc_u32 s1, s3, 0
	s_add_i32 s50, s44, s33
	global_load_lds_dwordx4 v[222:223], off
	v_lshl_add_u64 v[224:225], s[0:1], 0, v[156:157]
	s_mov_b32 m0, s50
	v_lshl_add_u64 v[226:227], s[26:27], 0, v[158:159]
	global_load_lds_dwordx4 v[224:225], off
	v_lshl_add_u64 v[224:225], s[0:1], 0, v[160:161]
	s_add_i32 m0, s50, 0x2000
	s_nop 0
	global_load_lds_dwordx4 v[224:225], off
	v_lshl_add_u64 v[224:225], s[26:27], 0, v[154:155]
	s_mov_b32 m0, s34
	s_nop 0
	global_load_lds_dwordx4 v[224:225], off
	s_mov_b32 m0, s35
	s_nop 0
	global_load_lds_dwordx4 v[226:227], off
	s_waitcnt vmcnt(8)
	s_waitcnt lgkmcnt(0)
	s_barrier
	s_setprio 1
	s_waitcnt lgkmcnt(0)
	v_mfma_f32_16x16x32_bf16 v[62:65], v[130:133], v[178:181], v[62:65]
	v_mfma_f32_16x16x32_bf16 v[46:49], v[130:133], v[196:199], v[46:49]
	v_mfma_f32_16x16x32_bf16 v[30:33], v[130:133], v[204:207], v[30:33]
	v_mfma_f32_16x16x32_bf16 v[14:17], v[130:133], v[212:215], v[14:17]
	v_mfma_f32_16x16x32_bf16 v[58:61], v[138:141], v[178:181], v[58:61]
	v_mfma_f32_16x16x32_bf16 v[42:45], v[138:141], v[196:199], v[42:45]
	v_mfma_f32_16x16x32_bf16 v[26:29], v[138:141], v[204:207], v[26:29]
	v_mfma_f32_16x16x32_bf16 v[10:13], v[138:141], v[212:215], v[10:13]
	v_mfma_f32_16x16x32_bf16 v[62:65], v[134:137], v[192:195], v[62:65]
	v_mfma_f32_16x16x32_bf16 v[46:49], v[134:137], v[200:203], v[46:49]
	v_mfma_f32_16x16x32_bf16 v[30:33], v[134:137], v[208:211], v[30:33]
	v_mfma_f32_16x16x32_bf16 v[14:17], v[134:137], v[216:219], v[14:17]
	v_mfma_f32_16x16x32_bf16 v[58:61], v[142:145], v[192:195], v[58:61]
	v_mfma_f32_16x16x32_bf16 v[42:45], v[142:145], v[200:203], v[42:45]
	v_mfma_f32_16x16x32_bf16 v[26:29], v[142:145], v[208:211], v[26:29]
	v_mfma_f32_16x16x32_bf16 v[10:13], v[142:145], v[216:219], v[10:13]
	s_setprio 0
	s_setprio 1
	v_mfma_f32_16x16x32_bf16 v[54:57], v[146:149], v[178:181], v[54:57]
	v_mfma_f32_16x16x32_bf16 v[38:41], v[146:149], v[196:199], v[38:41]
	v_mfma_f32_16x16x32_bf16 v[22:25], v[146:149], v[204:207], v[22:25]
	v_mfma_f32_16x16x32_bf16 v[6:9], v[146:149], v[212:215], v[6:9]
	v_mfma_f32_16x16x32_bf16 v[50:53], v[170:173], v[178:181], v[50:53]
	v_mfma_f32_16x16x32_bf16 v[34:37], v[170:173], v[196:199], v[34:37]
	v_mfma_f32_16x16x32_bf16 v[18:21], v[170:173], v[204:207], v[18:21]
	v_mfma_f32_16x16x32_bf16 v[2:5], v[170:173], v[212:215], v[2:5]
	v_mfma_f32_16x16x32_bf16 v[54:57], v[150:153], v[192:195], v[54:57]
	v_mfma_f32_16x16x32_bf16 v[38:41], v[150:153], v[200:203], v[38:41]
	v_mfma_f32_16x16x32_bf16 v[22:25], v[150:153], v[208:211], v[22:25]
	v_mfma_f32_16x16x32_bf16 v[6:9], v[150:153], v[216:219], v[6:9]
	v_mfma_f32_16x16x32_bf16 v[50:53], v[174:177], v[192:195], v[50:53]
	v_mfma_f32_16x16x32_bf16 v[34:37], v[174:177], v[200:203], v[34:37]
	v_mfma_f32_16x16x32_bf16 v[18:21], v[174:177], v[208:211], v[18:21]
	v_mfma_f32_16x16x32_bf16 v[2:5], v[174:177], v[216:219], v[2:5]
	s_setprio 0
	s_barrier
	s_add_i32 s50, 0, 0x18000
	s_add_i32 s51, 0, 0x1c000
	v_add_u32_e32 v142, s50, v183
	v_add_u32_e32 v174, s51, v183
	ds_read_b128 v[130:133], v142
	ds_read_b128 v[134:137], v142 offset:1024
	ds_read_b128 v[138:141], v142 offset:2048
	ds_read_b128 v[142:145], v142 offset:3072
	ds_read_b128 v[146:149], v174
	ds_read_b128 v[150:153], v174 offset:1024
	ds_read_b128 v[170:173], v174 offset:2048
	ds_read_b128 v[174:177], v174 offset:3072
	s_add_u32 s0, s26, 0xb0000
	s_addc_u32 s1, s27, 0
	s_mov_b32 m0, s36
	v_lshl_add_u64 v[228:229], s[0:1], 0, v[154:155]
	ds_read_b128 v[178:181], v189 offset:32768
	ds_read_b128 v[192:195], v189 offset:33792
	ds_read_b128 v[196:199], v189 offset:34816
	ds_read_b128 v[200:203], v189 offset:35840
	ds_read_b128 v[204:207], v189 offset:36864
	ds_read_b128 v[208:211], v189 offset:37888
	ds_read_b128 v[212:215], v189 offset:38912
	ds_read_b128 v[216:219], v189 offset:39936
	global_load_lds_dwordx4 v[228:229], off
	v_lshl_add_u64 v[228:229], s[0:1], 0, v[158:159]
	s_mov_b32 m0, s37
	s_nop 0
	global_load_lds_dwordx4 v[228:229], off
	s_waitcnt vmcnt(8)
	s_waitcnt lgkmcnt(0)
	s_barrier
	s_setprio 1
	s_waitcnt lgkmcnt(0)
	v_mfma_f32_16x16x32_bf16 v[126:129], v[130:133], v[178:181], v[126:129]
	v_mfma_f32_16x16x32_bf16 v[110:113], v[130:133], v[196:199], v[110:113]
	v_mfma_f32_16x16x32_bf16 v[94:97], v[130:133], v[204:207], v[94:97]
	v_mfma_f32_16x16x32_bf16 v[78:81], v[130:133], v[212:215], v[78:81]
	v_mfma_f32_16x16x32_bf16 v[122:125], v[138:141], v[178:181], v[122:125]
	v_mfma_f32_16x16x32_bf16 v[106:109], v[138:141], v[196:199], v[106:109]
	v_mfma_f32_16x16x32_bf16 v[90:93], v[138:141], v[204:207], v[90:93]
	v_mfma_f32_16x16x32_bf16 v[74:77], v[138:141], v[212:215], v[74:77]
	v_mfma_f32_16x16x32_bf16 v[126:129], v[134:137], v[192:195], v[126:129]
	v_mfma_f32_16x16x32_bf16 v[110:113], v[134:137], v[200:203], v[110:113]
	v_mfma_f32_16x16x32_bf16 v[94:97], v[134:137], v[208:211], v[94:97]
	v_mfma_f32_16x16x32_bf16 v[78:81], v[134:137], v[216:219], v[78:81]
	v_mfma_f32_16x16x32_bf16 v[122:125], v[142:145], v[192:195], v[122:125]
	v_mfma_f32_16x16x32_bf16 v[106:109], v[142:145], v[200:203], v[106:109]
	v_mfma_f32_16x16x32_bf16 v[90:93], v[142:145], v[208:211], v[90:93]
	v_mfma_f32_16x16x32_bf16 v[74:77], v[142:145], v[216:219], v[74:77]
	s_setprio 0
	s_setprio 1
	v_mfma_f32_16x16x32_bf16 v[118:121], v[146:149], v[178:181], v[118:121]
	v_mfma_f32_16x16x32_bf16 v[102:105], v[146:149], v[196:199], v[102:105]
	v_mfma_f32_16x16x32_bf16 v[86:89], v[146:149], v[204:207], v[86:89]
	v_mfma_f32_16x16x32_bf16 v[70:73], v[146:149], v[212:215], v[70:73]
	v_mfma_f32_16x16x32_bf16 v[114:117], v[170:173], v[178:181], v[114:117]
	v_mfma_f32_16x16x32_bf16 v[98:101], v[170:173], v[196:199], v[98:101]
	v_mfma_f32_16x16x32_bf16 v[82:85], v[170:173], v[204:207], v[82:85]
	v_mfma_f32_16x16x32_bf16 v[66:69], v[170:173], v[212:215], v[66:69]
	v_mfma_f32_16x16x32_bf16 v[118:121], v[150:153], v[192:195], v[118:121]
	v_mfma_f32_16x16x32_bf16 v[102:105], v[150:153], v[200:203], v[102:105]
	v_mfma_f32_16x16x32_bf16 v[86:89], v[150:153], v[208:211], v[86:89]
	v_mfma_f32_16x16x32_bf16 v[70:73], v[150:153], v[216:219], v[70:73]
	v_mfma_f32_16x16x32_bf16 v[114:117], v[174:177], v[192:195], v[114:117]
	v_mfma_f32_16x16x32_bf16 v[98:101], v[174:177], v[200:203], v[98:101]
	v_mfma_f32_16x16x32_bf16 v[82:85], v[174:177], v[208:211], v[82:85]
	v_mfma_f32_16x16x32_bf16 v[66:69], v[174:177], v[216:219], v[66:69]
	s_setprio 0
	s_barrier
	s_add_i32 s0, s50, s33
	v_lshl_add_u64 v[220:221], v[220:221], 0, s[16:17]
	s_mov_b32 m0, s0
	ds_read_b128 v[178:181], v189 offset:49152
	ds_read_b128 v[192:195], v189 offset:50176
	ds_read_b128 v[196:199], v189 offset:51200
	ds_read_b128 v[200:203], v189 offset:52224
	ds_read_b128 v[204:207], v189 offset:53248
	ds_read_b128 v[208:211], v189 offset:54272
	ds_read_b128 v[212:215], v189 offset:55296
	ds_read_b128 v[216:219], v189 offset:56320
	global_load_lds_dwordx4 v[220:221], off
	s_add_i32 m0, s0, 0x2000
	s_add_u32 s0, s2, 0xb0080
	v_lshl_add_u64 v[220:221], v[222:223], 0, s[16:17]
	s_addc_u32 s1, s3, 0
	s_add_i32 s2, s51, s33
	global_load_lds_dwordx4 v[220:221], off
	v_lshl_add_u64 v[220:221], s[0:1], 0, v[156:157]
	s_mov_b32 m0, s2
	s_nop 0
	global_load_lds_dwordx4 v[220:221], off
	v_lshl_add_u64 v[220:221], s[0:1], 0, v[160:161]
	s_add_i32 m0, s2, 0x2000
	s_nop 0
	global_load_lds_dwordx4 v[220:221], off
	v_lshl_add_u64 v[220:221], v[224:225], 0, s[16:17]
	s_mov_b32 m0, s39
	s_nop 0
	global_load_lds_dwordx4 v[220:221], off
	v_lshl_add_u64 v[220:221], v[226:227], 0, s[16:17]
	s_mov_b32 m0, s40
	s_nop 0
	global_load_lds_dwordx4 v[220:221], off
	s_waitcnt vmcnt(8)
	s_waitcnt lgkmcnt(0)
	s_barrier
	s_setprio 1
	s_waitcnt lgkmcnt(0)
	v_mfma_f32_16x16x32_bf16 v[62:65], v[130:133], v[178:181], v[62:65]
	v_mfma_f32_16x16x32_bf16 v[46:49], v[130:133], v[196:199], v[46:49]
	v_mfma_f32_16x16x32_bf16 v[30:33], v[130:133], v[204:207], v[30:33]
	v_mfma_f32_16x16x32_bf16 v[14:17], v[130:133], v[212:215], v[14:17]
	v_mfma_f32_16x16x32_bf16 v[58:61], v[138:141], v[178:181], v[58:61]
	v_mfma_f32_16x16x32_bf16 v[42:45], v[138:141], v[196:199], v[42:45]
	v_mfma_f32_16x16x32_bf16 v[26:29], v[138:141], v[204:207], v[26:29]
	v_mfma_f32_16x16x32_bf16 v[10:13], v[138:141], v[212:215], v[10:13]
	v_mfma_f32_16x16x32_bf16 v[62:65], v[134:137], v[192:195], v[62:65]
	v_mfma_f32_16x16x32_bf16 v[46:49], v[134:137], v[200:203], v[46:49]
	v_mfma_f32_16x16x32_bf16 v[30:33], v[134:137], v[208:211], v[30:33]
	v_mfma_f32_16x16x32_bf16 v[14:17], v[134:137], v[216:219], v[14:17]
	v_mfma_f32_16x16x32_bf16 v[58:61], v[142:145], v[192:195], v[58:61]
	v_mfma_f32_16x16x32_bf16 v[42:45], v[142:145], v[200:203], v[42:45]
	v_mfma_f32_16x16x32_bf16 v[26:29], v[142:145], v[208:211], v[26:29]
	v_mfma_f32_16x16x32_bf16 v[10:13], v[142:145], v[216:219], v[10:13]
	s_setprio 0
	s_setprio 1
	v_mfma_f32_16x16x32_bf16 v[54:57], v[146:149], v[178:181], v[54:57]
	v_mfma_f32_16x16x32_bf16 v[38:41], v[146:149], v[196:199], v[38:41]
	v_mfma_f32_16x16x32_bf16 v[22:25], v[146:149], v[204:207], v[22:25]
	v_mfma_f32_16x16x32_bf16 v[6:9], v[146:149], v[212:215], v[6:9]
	v_mfma_f32_16x16x32_bf16 v[50:53], v[170:173], v[178:181], v[50:53]
	v_mfma_f32_16x16x32_bf16 v[34:37], v[170:173], v[196:199], v[34:37]
	v_mfma_f32_16x16x32_bf16 v[18:21], v[170:173], v[204:207], v[18:21]
	v_mfma_f32_16x16x32_bf16 v[2:5], v[170:173], v[212:215], v[2:5]
	v_mfma_f32_16x16x32_bf16 v[54:57], v[150:153], v[192:195], v[54:57]
	v_mfma_f32_16x16x32_bf16 v[38:41], v[150:153], v[200:203], v[38:41]
	v_mfma_f32_16x16x32_bf16 v[22:25], v[150:153], v[208:211], v[22:25]
	v_mfma_f32_16x16x32_bf16 v[6:9], v[150:153], v[216:219], v[6:9]
	v_mfma_f32_16x16x32_bf16 v[50:53], v[174:177], v[192:195], v[50:53]
	v_mfma_f32_16x16x32_bf16 v[34:37], v[174:177], v[200:203], v[34:37]
	v_mfma_f32_16x16x32_bf16 v[18:21], v[174:177], v[208:211], v[18:21]
	v_mfma_f32_16x16x32_bf16 v[2:5], v[174:177], v[216:219], v[2:5]
	s_setprio 0
	s_barrier
	s_add_i32 s49, s49, 2
	s_add_u32 s24, s24, 0x100
	s_addc_u32 s25, s25, 0
	s_add_u32 s47, s47, 0x100
	s_addc_u32 s48, s48, 0
	s_cmp_gt_u32 s49, 41
	s_cbranch_scc0 .LBB0_1123
	s_and_b64 vcc, exec, s[18:19]
	s_cbranch_vccz .LBB0_1126
	s_barrier

.LBB0_1214:
	ds_read_b128 v[62:65], v208
	ds_read_b128 v[78:81], v208 offset:1024
	ds_read_b128 v[98:101], v208 offset:2048
	ds_read_b128 v[118:121], v208 offset:3072
	ds_read_b128 v[138:141], v209
	ds_read_b128 v[150:153], v209 offset:1024
	ds_read_b128 v[154:157], v209 offset:2048
	ds_read_b128 v[178:181], v209 offset:3072
	s_add_u32 s0, s38, 0xfffc0080
	s_addc_u32 s1, s39, -1
	s_cmp_eq_u32 s58, 12
	s_cselect_b32 s41, s7, s1
	s_cselect_b32 s40, s9, s0
	s_cselect_b32 s3, s10, s57
	s_cselect_b32 s2, s29, s31
	v_lshl_add_u64 v[202:203], s[38:39], 0, v[170:171]
	s_add_i32 m0, s43, 0xc000
	ds_read_b128 v[182:185], v210
	ds_read_b128 v[186:189], v210 offset:1024
	ds_read_b128 v[190:193], v210 offset:2048
	ds_read_b128 v[194:197], v210 offset:3072
	ds_read_b128 v[198:201], v210 offset:4096
	ds_read_b128 v[212:215], v210 offset:5120
	ds_read_b128 v[216:219], v210 offset:6144
	ds_read_b128 v[220:223], v210 offset:7168
	global_load_lds_dwordx4 v[202:203], off
	v_lshl_add_u64 v[202:203], s[38:39], 0, v[172:173]
	s_add_i32 m0, s43, 0xe000
	s_nop 0
	global_load_lds_dwordx4 v[202:203], off
	s_waitcnt vmcnt(8)
	s_waitcnt lgkmcnt(0)
	s_barrier
	s_setprio 1
	s_waitcnt lgkmcnt(0)
	v_mfma_f32_16x16x32_bf16 v[146:149], v[62:65], v[182:185], v[146:149]
	v_mfma_f32_16x16x32_bf16 v[126:129], v[62:65], v[190:193], v[126:129]
	v_mfma_f32_16x16x32_bf16 v[106:109], v[62:65], v[198:201], v[106:109]
	v_mfma_f32_16x16x32_bf16 v[86:89], v[62:65], v[216:219], v[86:89]
	v_mfma_f32_16x16x32_bf16 v[142:145], v[98:101], v[182:185], v[142:145]
	v_mfma_f32_16x16x32_bf16 v[122:125], v[98:101], v[190:193], v[122:125]
	v_mfma_f32_16x16x32_bf16 v[102:105], v[98:101], v[198:201], v[102:105]
	v_mfma_f32_16x16x32_bf16 v[82:85], v[98:101], v[216:219], v[82:85]
	v_mfma_f32_16x16x32_bf16 v[146:149], v[78:81], v[186:189], v[146:149]
	v_mfma_f32_16x16x32_bf16 v[126:129], v[78:81], v[194:197], v[126:129]
	v_mfma_f32_16x16x32_bf16 v[106:109], v[78:81], v[212:215], v[106:109]
	v_mfma_f32_16x16x32_bf16 v[86:89], v[78:81], v[220:223], v[86:89]
	v_mfma_f32_16x16x32_bf16 v[142:145], v[118:121], v[186:189], v[142:145]
	v_mfma_f32_16x16x32_bf16 v[122:125], v[118:121], v[194:197], v[122:125]
	v_mfma_f32_16x16x32_bf16 v[102:105], v[118:121], v[212:215], v[102:105]
	v_mfma_f32_16x16x32_bf16 v[82:85], v[118:121], v[220:223], v[82:85]
	s_setprio 0
	s_setprio 1
	v_mfma_f32_16x16x32_bf16 v[134:137], v[138:141], v[182:185], v[134:137]
	v_mfma_f32_16x16x32_bf16 v[114:117], v[138:141], v[190:193], v[114:117]
	v_mfma_f32_16x16x32_bf16 v[94:97], v[138:141], v[198:201], v[94:97]
	v_mfma_f32_16x16x32_bf16 v[74:77], v[138:141], v[216:219], v[74:77]
	v_mfma_f32_16x16x32_bf16 v[130:133], v[154:157], v[182:185], v[130:133]
	v_mfma_f32_16x16x32_bf16 v[110:113], v[154:157], v[190:193], v[110:113]
	v_mfma_f32_16x16x32_bf16 v[90:93], v[154:157], v[198:201], v[90:93]
	v_mfma_f32_16x16x32_bf16 v[70:73], v[154:157], v[216:219], v[70:73]
	v_mfma_f32_16x16x32_bf16 v[134:137], v[150:153], v[186:189], v[134:137]
	v_mfma_f32_16x16x32_bf16 v[114:117], v[150:153], v[194:197], v[114:117]
	v_mfma_f32_16x16x32_bf16 v[94:97], v[150:153], v[212:215], v[94:97]
	v_mfma_f32_16x16x32_bf16 v[74:77], v[150:153], v[220:223], v[74:77]
	v_mfma_f32_16x16x32_bf16 v[130:133], v[178:181], v[186:189], v[130:133]
	v_mfma_f32_16x16x32_bf16 v[110:113], v[178:181], v[194:197], v[110:113]
	v_mfma_f32_16x16x32_bf16 v[90:93], v[178:181], v[212:215], v[90:93]
	v_mfma_f32_16x16x32_bf16 v[70:73], v[178:181], v[220:223], v[70:73]
	s_setprio 0
	s_barrier
	s_add_i32 s0, s53, s42
	v_lshl_add_u64 v[202:203], s[2:3], 0, v[162:163]
	s_mov_b32 m0, s0
	ds_read_b128 v[182:185], v210 offset:16384
	ds_read_b128 v[186:189], v210 offset:17408
	ds_read_b128 v[190:193], v210 offset:18432
	ds_read_b128 v[194:197], v210 offset:19456
	ds_read_b128 v[198:201], v210 offset:20480
	ds_read_b128 v[212:215], v210 offset:21504
	ds_read_b128 v[216:219], v210 offset:22528
	ds_read_b128 v[220:223], v210 offset:23552
	global_load_lds_dwordx4 v[202:203], off
	s_add_i32 m0, s0, 0x2000
	s_add_u32 s0, s2, 0x40000
	v_lshl_add_u64 v[224:225], s[2:3], 0, v[166:167]
	s_addc_u32 s1, s3, 0
	s_add_i32 s59, s54, s42
	global_load_lds_dwordx4 v[224:225], off
	v_lshl_add_u64 v[226:227], s[0:1], 0, v[162:163]
	s_mov_b32 m0, s59
	v_lshl_add_u64 v[228:229], s[40:41], 0, v[164:165]
	global_load_lds_dwordx4 v[226:227], off
	v_lshl_add_u64 v[226:227], s[0:1], 0, v[166:167]
	s_add_i32 m0, s59, 0x2000
	s_nop 0
	global_load_lds_dwordx4 v[226:227], off
	v_lshl_add_u64 v[226:227], s[40:41], 0, v[160:161]
	s_mov_b32 m0, s43
	s_nop 0
	global_load_lds_dwordx4 v[226:227], off
	s_mov_b32 m0, s44
	s_nop 0
	global_load_lds_dwordx4 v[228:229], off
	s_waitcnt vmcnt(8)
	s_waitcnt lgkmcnt(0)
	s_barrier
	s_setprio 1
	s_waitcnt lgkmcnt(0)
	v_mfma_f32_16x16x32_bf16 v[66:69], v[62:65], v[182:185], v[66:69]
	v_mfma_f32_16x16x32_bf16 v[46:49], v[62:65], v[190:193], v[46:49]
	v_mfma_f32_16x16x32_bf16 v[30:33], v[62:65], v[198:201], v[30:33]
	v_mfma_f32_16x16x32_bf16 v[14:17], v[62:65], v[216:219], v[14:17]
	v_mfma_f32_16x16x32_bf16 v[58:61], v[98:101], v[182:185], v[58:61]
	v_mfma_f32_16x16x32_bf16 v[42:45], v[98:101], v[190:193], v[42:45]
	v_mfma_f32_16x16x32_bf16 v[26:29], v[98:101], v[198:201], v[26:29]
	v_mfma_f32_16x16x32_bf16 v[10:13], v[98:101], v[216:219], v[10:13]
	v_mfma_f32_16x16x32_bf16 v[66:69], v[78:81], v[186:189], v[66:69]
	v_mfma_f32_16x16x32_bf16 v[46:49], v[78:81], v[194:197], v[46:49]
	v_mfma_f32_16x16x32_bf16 v[30:33], v[78:81], v[212:215], v[30:33]
	v_mfma_f32_16x16x32_bf16 v[14:17], v[78:81], v[220:223], v[14:17]
	v_mfma_f32_16x16x32_bf16 v[58:61], v[118:121], v[186:189], v[58:61]
	v_mfma_f32_16x16x32_bf16 v[42:45], v[118:121], v[194:197], v[42:45]
	v_mfma_f32_16x16x32_bf16 v[26:29], v[118:121], v[212:215], v[26:29]
	v_mfma_f32_16x16x32_bf16 v[10:13], v[118:121], v[220:223], v[10:13]
	s_setprio 0
	s_setprio 1
	v_mfma_f32_16x16x32_bf16 v[54:57], v[138:141], v[182:185], v[54:57]
	v_mfma_f32_16x16x32_bf16 v[38:41], v[138:141], v[190:193], v[38:41]
	v_mfma_f32_16x16x32_bf16 v[22:25], v[138:141], v[198:201], v[22:25]
	v_mfma_f32_16x16x32_bf16 v[6:9], v[138:141], v[216:219], v[6:9]
	v_mfma_f32_16x16x32_bf16 v[50:53], v[154:157], v[182:185], v[50:53]
	v_mfma_f32_16x16x32_bf16 v[34:37], v[154:157], v[190:193], v[34:37]
	v_mfma_f32_16x16x32_bf16 v[18:21], v[154:157], v[198:201], v[18:21]
	v_mfma_f32_16x16x32_bf16 v[2:5], v[154:157], v[216:219], v[2:5]
	v_mfma_f32_16x16x32_bf16 v[54:57], v[150:153], v[186:189], v[54:57]
	v_mfma_f32_16x16x32_bf16 v[38:41], v[150:153], v[194:197], v[38:41]
	v_mfma_f32_16x16x32_bf16 v[22:25], v[150:153], v[212:215], v[22:25]
	v_mfma_f32_16x16x32_bf16 v[6:9], v[150:153], v[220:223], v[6:9]
	v_mfma_f32_16x16x32_bf16 v[50:53], v[178:181], v[186:189], v[50:53]
	v_mfma_f32_16x16x32_bf16 v[34:37], v[178:181], v[194:197], v[34:37]
	v_mfma_f32_16x16x32_bf16 v[18:21], v[178:181], v[212:215], v[18:21]
	v_mfma_f32_16x16x32_bf16 v[2:5], v[178:181], v[220:223], v[2:5]
	s_setprio 0
	s_barrier
	s_add_i32 s59, 0, 0x18000
	s_add_i32 s60, 0, 0x1c000
	v_add_u32_e32 v118, s59, v206
	v_add_u32_e32 v168, s60, v206
	ds_read_b128 v[62:65], v118
	ds_read_b128 v[78:81], v118 offset:1024
	ds_read_b128 v[98:101], v118 offset:2048
	ds_read_b128 v[118:121], v118 offset:3072
	ds_read_b128 v[138:141], v168
	ds_read_b128 v[150:153], v168 offset:1024
	ds_read_b128 v[154:157], v168 offset:2048
	ds_read_b128 v[178:181], v168 offset:3072
	s_add_u32 s0, s40, 0x40000
	s_addc_u32 s1, s41, 0
	s_mov_b32 m0, s45
	v_lshl_add_u64 v[230:231], s[0:1], 0, v[160:161]
	ds_read_b128 v[182:185], v210 offset:32768
	ds_read_b128 v[186:189], v210 offset:33792
	ds_read_b128 v[190:193], v210 offset:34816
	ds_read_b128 v[194:197], v210 offset:35840
	ds_read_b128 v[198:201], v210 offset:36864
	ds_read_b128 v[212:215], v210 offset:37888
	ds_read_b128 v[216:219], v210 offset:38912
	ds_read_b128 v[220:223], v210 offset:39936
	global_load_lds_dwordx4 v[230:231], off
	v_lshl_add_u64 v[230:231], s[0:1], 0, v[164:165]
	s_mov_b32 m0, s46
	s_nop 0
	global_load_lds_dwordx4 v[230:231], off
	s_waitcnt vmcnt(8)
	s_waitcnt lgkmcnt(0)
	s_barrier
	s_setprio 1
	s_waitcnt lgkmcnt(0)
	v_mfma_f32_16x16x32_bf16 v[146:149], v[62:65], v[182:185], v[146:149]
	v_mfma_f32_16x16x32_bf16 v[126:129], v[62:65], v[190:193], v[126:129]
	v_mfma_f32_16x16x32_bf16 v[106:109], v[62:65], v[198:201], v[106:109]
	v_mfma_f32_16x16x32_bf16 v[86:89], v[62:65], v[216:219], v[86:89]
	v_mfma_f32_16x16x32_bf16 v[142:145], v[98:101], v[182:185], v[142:145]
	v_mfma_f32_16x16x32_bf16 v[122:125], v[98:101], v[190:193], v[122:125]
	v_mfma_f32_16x16x32_bf16 v[102:105], v[98:101], v[198:201], v[102:105]
	v_mfma_f32_16x16x32_bf16 v[82:85], v[98:101], v[216:219], v[82:85]
	v_mfma_f32_16x16x32_bf16 v[146:149], v[78:81], v[186:189], v[146:149]
	v_mfma_f32_16x16x32_bf16 v[126:129], v[78:81], v[194:197], v[126:129]
	v_mfma_f32_16x16x32_bf16 v[106:109], v[78:81], v[212:215], v[106:109]
	v_mfma_f32_16x16x32_bf16 v[86:89], v[78:81], v[220:223], v[86:89]
	v_mfma_f32_16x16x32_bf16 v[142:145], v[118:121], v[186:189], v[142:145]
	v_mfma_f32_16x16x32_bf16 v[122:125], v[118:121], v[194:197], v[122:125]
	v_mfma_f32_16x16x32_bf16 v[102:105], v[118:121], v[212:215], v[102:105]
	v_mfma_f32_16x16x32_bf16 v[82:85], v[118:121], v[220:223], v[82:85]
	s_setprio 0
	s_setprio 1
	v_mfma_f32_16x16x32_bf16 v[134:137], v[138:141], v[182:185], v[134:137]
	v_mfma_f32_16x16x32_bf16 v[114:117], v[138:141], v[190:193], v[114:117]
	v_mfma_f32_16x16x32_bf16 v[94:97], v[138:141], v[198:201], v[94:97]
	v_mfma_f32_16x16x32_bf16 v[74:77], v[138:141], v[216:219], v[74:77]
	v_mfma_f32_16x16x32_bf16 v[130:133], v[154:157], v[182:185], v[130:133]
	v_mfma_f32_16x16x32_bf16 v[110:113], v[154:157], v[190:193], v[110:113]
	v_mfma_f32_16x16x32_bf16 v[90:93], v[154:157], v[198:201], v[90:93]
	v_mfma_f32_16x16x32_bf16 v[70:73], v[154:157], v[216:219], v[70:73]
	v_mfma_f32_16x16x32_bf16 v[134:137], v[150:153], v[186:189], v[134:137]
	v_mfma_f32_16x16x32_bf16 v[114:117], v[150:153], v[194:197], v[114:117]
	v_mfma_f32_16x16x32_bf16 v[94:97], v[150:153], v[212:215], v[94:97]
	v_mfma_f32_16x16x32_bf16 v[74:77], v[150:153], v[220:223], v[74:77]
	v_mfma_f32_16x16x32_bf16 v[130:133], v[178:181], v[186:189], v[130:133]
	v_mfma_f32_16x16x32_bf16 v[110:113], v[178:181], v[194:197], v[110:113]
	v_mfma_f32_16x16x32_bf16 v[90:93], v[178:181], v[212:215], v[90:93]
	v_mfma_f32_16x16x32_bf16 v[70:73], v[178:181], v[220:223], v[70:73]
	s_setprio 0
	s_barrier
	s_add_i32 s0, s59, s42
	v_lshl_add_u64 v[202:203], v[202:203], 0, s[22:23]
	s_mov_b32 m0, s0
	ds_read_b128 v[182:185], v210 offset:49152
	ds_read_b128 v[186:189], v210 offset:50176
	ds_read_b128 v[190:193], v210 offset:51200
	ds_read_b128 v[194:197], v210 offset:52224
	ds_read_b128 v[198:201], v210 offset:53248
	ds_read_b128 v[212:215], v210 offset:54272
	ds_read_b128 v[216:219], v210 offset:55296
	ds_read_b128 v[220:223], v210 offset:56320
	global_load_lds_dwordx4 v[202:203], off
	s_add_i32 m0, s0, 0x2000
	s_add_u32 s0, s2, 0x40080
	v_lshl_add_u64 v[202:203], v[224:225], 0, s[22:23]
	s_addc_u32 s1, s3, 0
	s_add_i32 s2, s60, s42
	global_load_lds_dwordx4 v[202:203], off
	v_lshl_add_u64 v[202:203], s[0:1], 0, v[162:163]
	s_mov_b32 m0, s2
	s_nop 0
	global_load_lds_dwordx4 v[202:203], off
	v_lshl_add_u64 v[202:203], s[0:1], 0, v[166:167]
	s_add_i32 m0, s2, 0x2000
	s_nop 0
	global_load_lds_dwordx4 v[202:203], off
	v_lshl_add_u64 v[202:203], v[226:227], 0, s[22:23]
	s_mov_b32 m0, s49
	s_nop 0
	global_load_lds_dwordx4 v[202:203], off
	v_lshl_add_u64 v[202:203], v[228:229], 0, s[22:23]
	s_mov_b32 m0, s50
	s_nop 0
	global_load_lds_dwordx4 v[202:203], off
	s_waitcnt vmcnt(8)
	s_waitcnt lgkmcnt(0)
	s_barrier
	s_setprio 1
	s_waitcnt lgkmcnt(0)
	v_mfma_f32_16x16x32_bf16 v[66:69], v[62:65], v[182:185], v[66:69]
	v_mfma_f32_16x16x32_bf16 v[46:49], v[62:65], v[190:193], v[46:49]
	v_mfma_f32_16x16x32_bf16 v[30:33], v[62:65], v[198:201], v[30:33]
	v_mfma_f32_16x16x32_bf16 v[14:17], v[62:65], v[216:219], v[14:17]
	v_mfma_f32_16x16x32_bf16 v[58:61], v[98:101], v[182:185], v[58:61]
	v_mfma_f32_16x16x32_bf16 v[42:45], v[98:101], v[190:193], v[42:45]
	v_mfma_f32_16x16x32_bf16 v[26:29], v[98:101], v[198:201], v[26:29]
	v_mfma_f32_16x16x32_bf16 v[10:13], v[98:101], v[216:219], v[10:13]
	v_mfma_f32_16x16x32_bf16 v[66:69], v[78:81], v[186:189], v[66:69]
	v_mfma_f32_16x16x32_bf16 v[46:49], v[78:81], v[194:197], v[46:49]
	v_mfma_f32_16x16x32_bf16 v[30:33], v[78:81], v[212:215], v[30:33]
	v_mfma_f32_16x16x32_bf16 v[14:17], v[78:81], v[220:223], v[14:17]
	v_mfma_f32_16x16x32_bf16 v[58:61], v[118:121], v[186:189], v[58:61]
	v_mfma_f32_16x16x32_bf16 v[42:45], v[118:121], v[194:197], v[42:45]
	v_mfma_f32_16x16x32_bf16 v[26:29], v[118:121], v[212:215], v[26:29]
	v_mfma_f32_16x16x32_bf16 v[10:13], v[118:121], v[220:223], v[10:13]
	s_setprio 0
	s_setprio 1
	v_mfma_f32_16x16x32_bf16 v[54:57], v[138:141], v[182:185], v[54:57]
	v_mfma_f32_16x16x32_bf16 v[38:41], v[138:141], v[190:193], v[38:41]
	v_mfma_f32_16x16x32_bf16 v[22:25], v[138:141], v[198:201], v[22:25]
	v_mfma_f32_16x16x32_bf16 v[6:9], v[138:141], v[216:219], v[6:9]
	v_mfma_f32_16x16x32_bf16 v[50:53], v[154:157], v[182:185], v[50:53]
	v_mfma_f32_16x16x32_bf16 v[34:37], v[154:157], v[190:193], v[34:37]
	v_mfma_f32_16x16x32_bf16 v[18:21], v[154:157], v[198:201], v[18:21]
	v_mfma_f32_16x16x32_bf16 v[2:5], v[154:157], v[216:219], v[2:5]
	v_mfma_f32_16x16x32_bf16 v[54:57], v[150:153], v[186:189], v[54:57]
	v_mfma_f32_16x16x32_bf16 v[38:41], v[150:153], v[194:197], v[38:41]
	v_mfma_f32_16x16x32_bf16 v[22:25], v[150:153], v[212:215], v[22:25]
	v_mfma_f32_16x16x32_bf16 v[6:9], v[150:153], v[220:223], v[6:9]
	v_mfma_f32_16x16x32_bf16 v[50:53], v[178:181], v[186:189], v[50:53]
	v_mfma_f32_16x16x32_bf16 v[34:37], v[178:181], v[194:197], v[34:37]
	v_mfma_f32_16x16x32_bf16 v[18:21], v[178:181], v[212:215], v[18:21]
	v_mfma_f32_16x16x32_bf16 v[2:5], v[178:181], v[220:223], v[2:5]
	s_setprio 0
	s_barrier
	s_add_i32 s58, s58, 2
	s_add_u32 s38, s38, 0x100
	s_addc_u32 s39, s39, 0
	s_add_u32 s31, s31, 0x100
	s_addc_u32 s57, s57, 0
	s_cmp_gt_u32 s58, 13
	s_cbranch_scc0 .LBB0_1214
	s_and_b64 vcc, exec, s[24:25]
	s_cbranch_vccz .LBB0_1217
	s_barrier

.LBB0_1626:
	ds_read_b128 v[130:133], v186
	ds_read_b128 v[134:137], v186 offset:1024
	ds_read_b128 v[138:141], v186 offset:2048
	ds_read_b128 v[142:145], v186 offset:3072
	ds_read_b128 v[146:149], v187
	ds_read_b128 v[150:153], v187 offset:1024
	ds_read_b128 v[170:173], v187 offset:2048
	ds_read_b128 v[174:177], v187 offset:3072
	s_add_u32 s0, s38, 0xfff80080
	s_addc_u32 s1, s39, -1
	s_cmp_eq_u32 s59, 28
	s_cselect_b32 s41, s11, s1
	s_cselect_b32 s40, s29, s0
	s_cselect_b32 s3, s27, s58
	s_cselect_b32 s2, s56, s57
	v_lshl_add_u64 v[218:219], s[38:39], 0, v[162:163]
	s_add_i32 m0, s37, 0xc000
	ds_read_b128 v[178:181], v188
	ds_read_b128 v[190:193], v188 offset:1024
	ds_read_b128 v[194:197], v188 offset:2048
	ds_read_b128 v[198:201], v188 offset:3072
	ds_read_b128 v[202:205], v188 offset:4096
	ds_read_b128 v[206:209], v188 offset:5120
	ds_read_b128 v[210:213], v188 offset:6144
	ds_read_b128 v[214:217], v188 offset:7168
	global_load_lds_dwordx4 v[218:219], off
	v_lshl_add_u64 v[218:219], s[38:39], 0, v[164:165]
	s_add_i32 m0, s37, 0xe000
	s_nop 0
	global_load_lds_dwordx4 v[218:219], off
	s_waitcnt vmcnt(8)
	s_waitcnt lgkmcnt(0)
	s_barrier
	s_setprio 1
	s_waitcnt lgkmcnt(0)
	v_mfma_f32_16x16x32_bf16 v[126:129], v[130:133], v[178:181], v[126:129]
	v_mfma_f32_16x16x32_bf16 v[110:113], v[130:133], v[194:197], v[110:113]
	v_mfma_f32_16x16x32_bf16 v[94:97], v[130:133], v[202:205], v[94:97]
	v_mfma_f32_16x16x32_bf16 v[78:81], v[130:133], v[210:213], v[78:81]
	v_mfma_f32_16x16x32_bf16 v[122:125], v[138:141], v[178:181], v[122:125]
	v_mfma_f32_16x16x32_bf16 v[106:109], v[138:141], v[194:197], v[106:109]
	v_mfma_f32_16x16x32_bf16 v[90:93], v[138:141], v[202:205], v[90:93]
	v_mfma_f32_16x16x32_bf16 v[74:77], v[138:141], v[210:213], v[74:77]
	v_mfma_f32_16x16x32_bf16 v[126:129], v[134:137], v[190:193], v[126:129]
	v_mfma_f32_16x16x32_bf16 v[110:113], v[134:137], v[198:201], v[110:113]
	v_mfma_f32_16x16x32_bf16 v[94:97], v[134:137], v[206:209], v[94:97]
	v_mfma_f32_16x16x32_bf16 v[78:81], v[134:137], v[214:217], v[78:81]
	v_mfma_f32_16x16x32_bf16 v[122:125], v[142:145], v[190:193], v[122:125]
	v_mfma_f32_16x16x32_bf16 v[106:109], v[142:145], v[198:201], v[106:109]
	v_mfma_f32_16x16x32_bf16 v[90:93], v[142:145], v[206:209], v[90:93]
	v_mfma_f32_16x16x32_bf16 v[74:77], v[142:145], v[214:217], v[74:77]
	s_setprio 0
	s_setprio 1
	v_mfma_f32_16x16x32_bf16 v[118:121], v[146:149], v[178:181], v[118:121]
	v_mfma_f32_16x16x32_bf16 v[102:105], v[146:149], v[194:197], v[102:105]
	v_mfma_f32_16x16x32_bf16 v[86:89], v[146:149], v[202:205], v[86:89]
	v_mfma_f32_16x16x32_bf16 v[70:73], v[146:149], v[210:213], v[70:73]
	v_mfma_f32_16x16x32_bf16 v[114:117], v[170:173], v[178:181], v[114:117]
	v_mfma_f32_16x16x32_bf16 v[98:101], v[170:173], v[194:197], v[98:101]
	v_mfma_f32_16x16x32_bf16 v[82:85], v[170:173], v[202:205], v[82:85]
	v_mfma_f32_16x16x32_bf16 v[66:69], v[170:173], v[210:213], v[66:69]
	v_mfma_f32_16x16x32_bf16 v[118:121], v[150:153], v[190:193], v[118:121]
	v_mfma_f32_16x16x32_bf16 v[102:105], v[150:153], v[198:201], v[102:105]
	v_mfma_f32_16x16x32_bf16 v[86:89], v[150:153], v[206:209], v[86:89]
	v_mfma_f32_16x16x32_bf16 v[70:73], v[150:153], v[214:217], v[70:73]
	v_mfma_f32_16x16x32_bf16 v[114:117], v[174:177], v[190:193], v[114:117]
	v_mfma_f32_16x16x32_bf16 v[98:101], v[174:177], v[198:201], v[98:101]
	v_mfma_f32_16x16x32_bf16 v[82:85], v[174:177], v[206:209], v[82:85]
	v_mfma_f32_16x16x32_bf16 v[66:69], v[174:177], v[214:217], v[66:69]
	s_setprio 0
	s_barrier
	s_add_i32 s0, s54, s45
	v_lshl_add_u64 v[218:219], s[2:3], 0, v[156:157]
	s_mov_b32 m0, s0
	ds_read_b128 v[178:181], v188 offset:16384
	ds_read_b128 v[190:193], v188 offset:17408
	ds_read_b128 v[194:197], v188 offset:18432
	ds_read_b128 v[198:201], v188 offset:19456
	ds_read_b128 v[202:205], v188 offset:20480
	ds_read_b128 v[206:209], v188 offset:21504
	ds_read_b128 v[210:213], v188 offset:22528
	ds_read_b128 v[214:217], v188 offset:23552
	global_load_lds_dwordx4 v[218:219], off
	s_add_i32 m0, s0, 0x2000
	s_add_u32 s0, s2, 0x80000
	v_lshl_add_u64 v[220:221], s[2:3], 0, v[160:161]
	s_addc_u32 s1, s3, 0
	s_add_i32 s60, s55, s45
	global_load_lds_dwordx4 v[220:221], off
	v_lshl_add_u64 v[222:223], s[0:1], 0, v[156:157]
	s_mov_b32 m0, s60
	v_lshl_add_u64 v[224:225], s[40:41], 0, v[158:159]
	global_load_lds_dwordx4 v[222:223], off
	v_lshl_add_u64 v[222:223], s[0:1], 0, v[160:161]
	s_add_i32 m0, s60, 0x2000
	s_nop 0
	global_load_lds_dwordx4 v[222:223], off
	v_lshl_add_u64 v[222:223], s[40:41], 0, v[154:155]
	s_mov_b32 m0, s37
	s_nop 0
	global_load_lds_dwordx4 v[222:223], off
	s_mov_b32 m0, s46
	s_nop 0
	global_load_lds_dwordx4 v[224:225], off
	s_waitcnt vmcnt(8)
	s_waitcnt lgkmcnt(0)
	s_barrier
	s_setprio 1
	s_waitcnt lgkmcnt(0)
	v_mfma_f32_16x16x32_bf16 v[62:65], v[130:133], v[178:181], v[62:65]
	v_mfma_f32_16x16x32_bf16 v[46:49], v[130:133], v[194:197], v[46:49]
	v_mfma_f32_16x16x32_bf16 v[30:33], v[130:133], v[202:205], v[30:33]
	v_mfma_f32_16x16x32_bf16 v[14:17], v[130:133], v[210:213], v[14:17]
	v_mfma_f32_16x16x32_bf16 v[58:61], v[138:141], v[178:181], v[58:61]
	v_mfma_f32_16x16x32_bf16 v[42:45], v[138:141], v[194:197], v[42:45]
	v_mfma_f32_16x16x32_bf16 v[26:29], v[138:141], v[202:205], v[26:29]
	v_mfma_f32_16x16x32_bf16 v[10:13], v[138:141], v[210:213], v[10:13]
	v_mfma_f32_16x16x32_bf16 v[62:65], v[134:137], v[190:193], v[62:65]
	v_mfma_f32_16x16x32_bf16 v[46:49], v[134:137], v[198:201], v[46:49]
	v_mfma_f32_16x16x32_bf16 v[30:33], v[134:137], v[206:209], v[30:33]
	v_mfma_f32_16x16x32_bf16 v[14:17], v[134:137], v[214:217], v[14:17]
	v_mfma_f32_16x16x32_bf16 v[58:61], v[142:145], v[190:193], v[58:61]
	v_mfma_f32_16x16x32_bf16 v[42:45], v[142:145], v[198:201], v[42:45]
	v_mfma_f32_16x16x32_bf16 v[26:29], v[142:145], v[206:209], v[26:29]
	v_mfma_f32_16x16x32_bf16 v[10:13], v[142:145], v[214:217], v[10:13]
	s_setprio 0
	s_setprio 1
	v_mfma_f32_16x16x32_bf16 v[54:57], v[146:149], v[178:181], v[54:57]
	v_mfma_f32_16x16x32_bf16 v[38:41], v[146:149], v[194:197], v[38:41]
	v_mfma_f32_16x16x32_bf16 v[22:25], v[146:149], v[202:205], v[22:25]
	v_mfma_f32_16x16x32_bf16 v[6:9], v[146:149], v[210:213], v[6:9]
	v_mfma_f32_16x16x32_bf16 v[50:53], v[170:173], v[178:181], v[50:53]
	v_mfma_f32_16x16x32_bf16 v[34:37], v[170:173], v[194:197], v[34:37]
	v_mfma_f32_16x16x32_bf16 v[18:21], v[170:173], v[202:205], v[18:21]
	v_mfma_f32_16x16x32_bf16 v[2:5], v[170:173], v[210:213], v[2:5]
	v_mfma_f32_16x16x32_bf16 v[54:57], v[150:153], v[190:193], v[54:57]
	v_mfma_f32_16x16x32_bf16 v[38:41], v[150:153], v[198:201], v[38:41]
	v_mfma_f32_16x16x32_bf16 v[22:25], v[150:153], v[206:209], v[22:25]
	v_mfma_f32_16x16x32_bf16 v[6:9], v[150:153], v[214:217], v[6:9]
	v_mfma_f32_16x16x32_bf16 v[50:53], v[174:177], v[190:193], v[50:53]
	v_mfma_f32_16x16x32_bf16 v[34:37], v[174:177], v[198:201], v[34:37]
	v_mfma_f32_16x16x32_bf16 v[18:21], v[174:177], v[206:209], v[18:21]
	v_mfma_f32_16x16x32_bf16 v[2:5], v[174:177], v[214:217], v[2:5]
	s_setprio 0
	s_barrier
	s_add_i32 s60, 0, 0x18000
	s_add_i32 s61, 0, 0x1c000
	v_add_u32_e32 v142, s60, v182
	v_add_u32_e32 v174, s61, v182
	ds_read_b128 v[130:133], v142
	ds_read_b128 v[134:137], v142 offset:1024
	ds_read_b128 v[138:141], v142 offset:2048
	ds_read_b128 v[142:145], v142 offset:3072
	ds_read_b128 v[146:149], v174
	ds_read_b128 v[150:153], v174 offset:1024
	ds_read_b128 v[170:173], v174 offset:2048
	ds_read_b128 v[174:177], v174 offset:3072
	s_add_u32 s0, s40, 0x80000
	s_addc_u32 s1, s41, 0
	s_mov_b32 m0, s47
	v_lshl_add_u64 v[226:227], s[0:1], 0, v[154:155]
	ds_read_b128 v[178:181], v188 offset:32768
	ds_read_b128 v[190:193], v188 offset:33792
	ds_read_b128 v[194:197], v188 offset:34816
	ds_read_b128 v[198:201], v188 offset:35840
	ds_read_b128 v[202:205], v188 offset:36864
	ds_read_b128 v[206:209], v188 offset:37888
	ds_read_b128 v[210:213], v188 offset:38912
	ds_read_b128 v[214:217], v188 offset:39936
	global_load_lds_dwordx4 v[226:227], off
	v_lshl_add_u64 v[226:227], s[0:1], 0, v[158:159]
	s_mov_b32 m0, s48
	s_nop 0
	global_load_lds_dwordx4 v[226:227], off
	s_waitcnt vmcnt(8)
	s_waitcnt lgkmcnt(0)
	s_barrier
	s_setprio 1
	s_waitcnt lgkmcnt(0)
	v_mfma_f32_16x16x32_bf16 v[126:129], v[130:133], v[178:181], v[126:129]
	v_mfma_f32_16x16x32_bf16 v[110:113], v[130:133], v[194:197], v[110:113]
	v_mfma_f32_16x16x32_bf16 v[94:97], v[130:133], v[202:205], v[94:97]
	v_mfma_f32_16x16x32_bf16 v[78:81], v[130:133], v[210:213], v[78:81]
	v_mfma_f32_16x16x32_bf16 v[122:125], v[138:141], v[178:181], v[122:125]
	v_mfma_f32_16x16x32_bf16 v[106:109], v[138:141], v[194:197], v[106:109]
	v_mfma_f32_16x16x32_bf16 v[90:93], v[138:141], v[202:205], v[90:93]
	v_mfma_f32_16x16x32_bf16 v[74:77], v[138:141], v[210:213], v[74:77]
	v_mfma_f32_16x16x32_bf16 v[126:129], v[134:137], v[190:193], v[126:129]
	v_mfma_f32_16x16x32_bf16 v[110:113], v[134:137], v[198:201], v[110:113]
	v_mfma_f32_16x16x32_bf16 v[94:97], v[134:137], v[206:209], v[94:97]
	v_mfma_f32_16x16x32_bf16 v[78:81], v[134:137], v[214:217], v[78:81]
	v_mfma_f32_16x16x32_bf16 v[122:125], v[142:145], v[190:193], v[122:125]
	v_mfma_f32_16x16x32_bf16 v[106:109], v[142:145], v[198:201], v[106:109]
	v_mfma_f32_16x16x32_bf16 v[90:93], v[142:145], v[206:209], v[90:93]
	v_mfma_f32_16x16x32_bf16 v[74:77], v[142:145], v[214:217], v[74:77]
	s_setprio 0
	s_setprio 1
	v_mfma_f32_16x16x32_bf16 v[118:121], v[146:149], v[178:181], v[118:121]
	v_mfma_f32_16x16x32_bf16 v[102:105], v[146:149], v[194:197], v[102:105]
	v_mfma_f32_16x16x32_bf16 v[86:89], v[146:149], v[202:205], v[86:89]
	v_mfma_f32_16x16x32_bf16 v[70:73], v[146:149], v[210:213], v[70:73]
	v_mfma_f32_16x16x32_bf16 v[114:117], v[170:173], v[178:181], v[114:117]
	v_mfma_f32_16x16x32_bf16 v[98:101], v[170:173], v[194:197], v[98:101]
	v_mfma_f32_16x16x32_bf16 v[82:85], v[170:173], v[202:205], v[82:85]
	v_mfma_f32_16x16x32_bf16 v[66:69], v[170:173], v[210:213], v[66:69]
	v_mfma_f32_16x16x32_bf16 v[118:121], v[150:153], v[190:193], v[118:121]
	v_mfma_f32_16x16x32_bf16 v[102:105], v[150:153], v[198:201], v[102:105]
	v_mfma_f32_16x16x32_bf16 v[86:89], v[150:153], v[206:209], v[86:89]
	v_mfma_f32_16x16x32_bf16 v[70:73], v[150:153], v[214:217], v[70:73]
	v_mfma_f32_16x16x32_bf16 v[114:117], v[174:177], v[190:193], v[114:117]
	v_mfma_f32_16x16x32_bf16 v[98:101], v[174:177], v[198:201], v[98:101]
	v_mfma_f32_16x16x32_bf16 v[82:85], v[174:177], v[206:209], v[82:85]
	v_mfma_f32_16x16x32_bf16 v[66:69], v[174:177], v[214:217], v[66:69]
	s_setprio 0
	s_barrier
	s_add_i32 s0, s60, s45
	v_lshl_add_u64 v[218:219], v[218:219], 0, s[14:15]
	s_mov_b32 m0, s0
	ds_read_b128 v[178:181], v188 offset:49152
	ds_read_b128 v[190:193], v188 offset:50176
	ds_read_b128 v[194:197], v188 offset:51200
	ds_read_b128 v[198:201], v188 offset:52224
	ds_read_b128 v[202:205], v188 offset:53248
	ds_read_b128 v[206:209], v188 offset:54272
	ds_read_b128 v[210:213], v188 offset:55296
	ds_read_b128 v[214:217], v188 offset:56320
	global_load_lds_dwordx4 v[218:219], off
	s_add_i32 m0, s0, 0x2000
	s_add_u32 s0, s2, 0x80080
	v_lshl_add_u64 v[218:219], v[220:221], 0, s[14:15]
	s_addc_u32 s1, s3, 0
	s_add_i32 s2, s61, s45
	global_load_lds_dwordx4 v[218:219], off
	v_lshl_add_u64 v[218:219], s[0:1], 0, v[156:157]
	s_mov_b32 m0, s2
	s_nop 0
	global_load_lds_dwordx4 v[218:219], off
	v_lshl_add_u64 v[218:219], s[0:1], 0, v[160:161]
	s_add_i32 m0, s2, 0x2000
	s_nop 0
	global_load_lds_dwordx4 v[218:219], off
	v_lshl_add_u64 v[218:219], v[222:223], 0, s[14:15]
	s_mov_b32 m0, s50
	s_nop 0
	global_load_lds_dwordx4 v[218:219], off
	v_lshl_add_u64 v[218:219], v[224:225], 0, s[14:15]
	s_mov_b32 m0, s51
	s_nop 0
	global_load_lds_dwordx4 v[218:219], off
	s_waitcnt vmcnt(8)
	s_waitcnt lgkmcnt(0)
	s_barrier
	s_setprio 1
	s_waitcnt lgkmcnt(0)
	v_mfma_f32_16x16x32_bf16 v[62:65], v[130:133], v[178:181], v[62:65]
	v_mfma_f32_16x16x32_bf16 v[46:49], v[130:133], v[194:197], v[46:49]
	v_mfma_f32_16x16x32_bf16 v[30:33], v[130:133], v[202:205], v[30:33]
	v_mfma_f32_16x16x32_bf16 v[14:17], v[130:133], v[210:213], v[14:17]
	v_mfma_f32_16x16x32_bf16 v[58:61], v[138:141], v[178:181], v[58:61]
	v_mfma_f32_16x16x32_bf16 v[42:45], v[138:141], v[194:197], v[42:45]
	v_mfma_f32_16x16x32_bf16 v[26:29], v[138:141], v[202:205], v[26:29]
	v_mfma_f32_16x16x32_bf16 v[10:13], v[138:141], v[210:213], v[10:13]
	v_mfma_f32_16x16x32_bf16 v[62:65], v[134:137], v[190:193], v[62:65]
	v_mfma_f32_16x16x32_bf16 v[46:49], v[134:137], v[198:201], v[46:49]
	v_mfma_f32_16x16x32_bf16 v[30:33], v[134:137], v[206:209], v[30:33]
	v_mfma_f32_16x16x32_bf16 v[14:17], v[134:137], v[214:217], v[14:17]
	v_mfma_f32_16x16x32_bf16 v[58:61], v[142:145], v[190:193], v[58:61]
	v_mfma_f32_16x16x32_bf16 v[42:45], v[142:145], v[198:201], v[42:45]
	v_mfma_f32_16x16x32_bf16 v[26:29], v[142:145], v[206:209], v[26:29]
	v_mfma_f32_16x16x32_bf16 v[10:13], v[142:145], v[214:217], v[10:13]
	s_setprio 0
	s_setprio 1
	v_mfma_f32_16x16x32_bf16 v[54:57], v[146:149], v[178:181], v[54:57]
	v_mfma_f32_16x16x32_bf16 v[38:41], v[146:149], v[194:197], v[38:41]
	v_mfma_f32_16x16x32_bf16 v[22:25], v[146:149], v[202:205], v[22:25]
	v_mfma_f32_16x16x32_bf16 v[6:9], v[146:149], v[210:213], v[6:9]
	v_mfma_f32_16x16x32_bf16 v[50:53], v[170:173], v[178:181], v[50:53]
	v_mfma_f32_16x16x32_bf16 v[34:37], v[170:173], v[194:197], v[34:37]
	v_mfma_f32_16x16x32_bf16 v[18:21], v[170:173], v[202:205], v[18:21]
	v_mfma_f32_16x16x32_bf16 v[2:5], v[170:173], v[210:213], v[2:5]
	v_mfma_f32_16x16x32_bf16 v[54:57], v[150:153], v[190:193], v[54:57]
	v_mfma_f32_16x16x32_bf16 v[38:41], v[150:153], v[198:201], v[38:41]
	v_mfma_f32_16x16x32_bf16 v[22:25], v[150:153], v[206:209], v[22:25]
	v_mfma_f32_16x16x32_bf16 v[6:9], v[150:153], v[214:217], v[6:9]
	v_mfma_f32_16x16x32_bf16 v[50:53], v[174:177], v[190:193], v[50:53]
	v_mfma_f32_16x16x32_bf16 v[34:37], v[174:177], v[198:201], v[34:37]
	v_mfma_f32_16x16x32_bf16 v[18:21], v[174:177], v[206:209], v[18:21]
	v_mfma_f32_16x16x32_bf16 v[2:5], v[174:177], v[214:217], v[2:5]
	s_setprio 0
	s_barrier
	s_add_i32 s59, s59, 2
	s_add_u32 s38, s38, 0x100
	s_addc_u32 s39, s39, 0
	s_add_u32 s57, s57, 0x100
	s_addc_u32 s58, s58, 0
	s_cmp_gt_u32 s59, 29
	s_cbranch_scc0 .LBB0_1626
	s_and_b64 vcc, exec, s[16:17]
	s_cbranch_vccz .LBB0_1629
	s_barrier

.LBB0_1715:
	ds_read_b128 v[148:151], v166
	ds_read_b128 v[152:155], v166 offset:1024
	ds_read_b128 v[156:159], v166 offset:2048
	ds_read_b128 v[160:163], v166 offset:3072
	ds_read_b128 v[170:173], v167
	ds_read_b128 v[174:177], v167 offset:1024
	ds_read_b128 v[178:181], v167 offset:2048
	ds_read_b128 v[182:185], v167 offset:3072
	s_add_u32 s0, s28, 0xfffc0080
	s_addc_u32 s1, s29, -1
	s_cmp_eq_u32 s53, 12
	s_cselect_b32 s31, s21, s1
	s_cselect_b32 s30, s49, s0
	s_cselect_b32 s3, s19, s52
	s_cselect_b32 s2, s50, s51
	v_lshl_add_u64 v[218:219], s[28:29], 0, v[140:141]
	s_add_i32 m0, s27, 0xc000
	ds_read_b128 v[186:189], v168
	ds_read_b128 v[190:193], v168 offset:1024
	ds_read_b128 v[194:197], v168 offset:2048
	ds_read_b128 v[198:201], v168 offset:3072
	ds_read_b128 v[202:205], v168 offset:4096
	ds_read_b128 v[206:209], v168 offset:5120
	ds_read_b128 v[210:213], v168 offset:6144
	ds_read_b128 v[214:217], v168 offset:7168
	global_load_lds_dwordx4 v[218:219], off
	v_lshl_add_u64 v[218:219], s[28:29], 0, v[142:143]
	s_add_i32 m0, s27, 0xe000
	s_nop 0
	global_load_lds_dwordx4 v[218:219], off
	s_waitcnt vmcnt(8)
	s_waitcnt lgkmcnt(0)
	s_barrier
	s_setprio 1
	s_waitcnt lgkmcnt(0)
	v_mfma_f32_16x16x32_bf16 v[126:129], v[148:151], v[186:189], v[126:129]
	v_mfma_f32_16x16x32_bf16 v[110:113], v[148:151], v[194:197], v[110:113]
	v_mfma_f32_16x16x32_bf16 v[94:97], v[148:151], v[202:205], v[94:97]
	v_mfma_f32_16x16x32_bf16 v[78:81], v[148:151], v[210:213], v[78:81]
	v_mfma_f32_16x16x32_bf16 v[118:121], v[156:159], v[186:189], v[118:121]
	v_mfma_f32_16x16x32_bf16 v[102:105], v[156:159], v[194:197], v[102:105]
	v_mfma_f32_16x16x32_bf16 v[86:89], v[156:159], v[202:205], v[86:89]
	v_mfma_f32_16x16x32_bf16 v[70:73], v[156:159], v[210:213], v[70:73]
	v_mfma_f32_16x16x32_bf16 v[126:129], v[152:155], v[190:193], v[126:129]
	v_mfma_f32_16x16x32_bf16 v[110:113], v[152:155], v[198:201], v[110:113]
	v_mfma_f32_16x16x32_bf16 v[94:97], v[152:155], v[206:209], v[94:97]
	v_mfma_f32_16x16x32_bf16 v[78:81], v[152:155], v[214:217], v[78:81]
	v_mfma_f32_16x16x32_bf16 v[118:121], v[160:163], v[190:193], v[118:121]
	v_mfma_f32_16x16x32_bf16 v[102:105], v[160:163], v[198:201], v[102:105]
	v_mfma_f32_16x16x32_bf16 v[86:89], v[160:163], v[206:209], v[86:89]
	v_mfma_f32_16x16x32_bf16 v[70:73], v[160:163], v[214:217], v[70:73]
	s_setprio 0
	s_setprio 1
	v_mfma_f32_16x16x32_bf16 v[122:125], v[170:173], v[186:189], v[122:125]
	v_mfma_f32_16x16x32_bf16 v[106:109], v[170:173], v[194:197], v[106:109]
	v_mfma_f32_16x16x32_bf16 v[90:93], v[170:173], v[202:205], v[90:93]
	v_mfma_f32_16x16x32_bf16 v[74:77], v[170:173], v[210:213], v[74:77]
	v_mfma_f32_16x16x32_bf16 v[114:117], v[178:181], v[186:189], v[114:117]
	v_mfma_f32_16x16x32_bf16 v[98:101], v[178:181], v[194:197], v[98:101]
	v_mfma_f32_16x16x32_bf16 v[82:85], v[178:181], v[202:205], v[82:85]
	v_mfma_f32_16x16x32_bf16 v[66:69], v[178:181], v[210:213], v[66:69]
	v_mfma_f32_16x16x32_bf16 v[122:125], v[174:177], v[190:193], v[122:125]
	v_mfma_f32_16x16x32_bf16 v[106:109], v[174:177], v[198:201], v[106:109]
	v_mfma_f32_16x16x32_bf16 v[90:93], v[174:177], v[206:209], v[90:93]
	v_mfma_f32_16x16x32_bf16 v[74:77], v[174:177], v[214:217], v[74:77]
	v_mfma_f32_16x16x32_bf16 v[114:117], v[182:185], v[190:193], v[114:117]
	v_mfma_f32_16x16x32_bf16 v[98:101], v[182:185], v[198:201], v[98:101]
	v_mfma_f32_16x16x32_bf16 v[82:85], v[182:185], v[206:209], v[82:85]
	v_mfma_f32_16x16x32_bf16 v[66:69], v[182:185], v[214:217], v[66:69]
	s_setprio 0
	s_barrier
	s_add_i32 s0, s44, s35
	v_lshl_add_u64 v[218:219], s[2:3], 0, v[134:135]
	s_mov_b32 m0, s0
	ds_read_b128 v[186:189], v168 offset:16384
	ds_read_b128 v[190:193], v168 offset:17408
	ds_read_b128 v[194:197], v168 offset:18432
	ds_read_b128 v[198:201], v168 offset:19456
	ds_read_b128 v[202:205], v168 offset:20480
	ds_read_b128 v[206:209], v168 offset:21504
	ds_read_b128 v[210:213], v168 offset:22528
	ds_read_b128 v[214:217], v168 offset:23552
	global_load_lds_dwordx4 v[218:219], off
	s_add_i32 m0, s0, 0x2000
	s_add_u32 s0, s2, 0x40000
	v_lshl_add_u64 v[220:221], s[2:3], 0, v[130:131]
	s_addc_u32 s1, s3, 0
	s_add_i32 s54, s45, s35
	global_load_lds_dwordx4 v[220:221], off
	v_lshl_add_u64 v[222:223], s[0:1], 0, v[134:135]
	s_mov_b32 m0, s54
	v_lshl_add_u64 v[224:225], s[30:31], 0, v[132:133]
	global_load_lds_dwordx4 v[222:223], off
	v_lshl_add_u64 v[222:223], s[0:1], 0, v[130:131]
	s_add_i32 m0, s54, 0x2000
	s_nop 0
	global_load_lds_dwordx4 v[222:223], off
	v_lshl_add_u64 v[222:223], s[30:31], 0, v[136:137]
	s_mov_b32 m0, s27
	s_nop 0
	global_load_lds_dwordx4 v[222:223], off
	s_mov_b32 m0, s38
	s_nop 0
	global_load_lds_dwordx4 v[224:225], off
	s_waitcnt vmcnt(8)
	s_waitcnt lgkmcnt(0)
	s_barrier
	s_setprio 1
	s_waitcnt lgkmcnt(0)
	v_mfma_f32_16x16x32_bf16 v[62:65], v[148:151], v[186:189], v[62:65]
	v_mfma_f32_16x16x32_bf16 v[46:49], v[148:151], v[194:197], v[46:49]
	v_mfma_f32_16x16x32_bf16 v[30:33], v[148:151], v[202:205], v[30:33]
	v_mfma_f32_16x16x32_bf16 v[14:17], v[148:151], v[210:213], v[14:17]
	v_mfma_f32_16x16x32_bf16 v[54:57], v[156:159], v[186:189], v[54:57]
	v_mfma_f32_16x16x32_bf16 v[38:41], v[156:159], v[194:197], v[38:41]
	v_mfma_f32_16x16x32_bf16 v[22:25], v[156:159], v[202:205], v[22:25]
	v_mfma_f32_16x16x32_bf16 v[6:9], v[156:159], v[210:213], v[6:9]
	v_mfma_f32_16x16x32_bf16 v[62:65], v[152:155], v[190:193], v[62:65]
	v_mfma_f32_16x16x32_bf16 v[46:49], v[152:155], v[198:201], v[46:49]
	v_mfma_f32_16x16x32_bf16 v[30:33], v[152:155], v[206:209], v[30:33]
	v_mfma_f32_16x16x32_bf16 v[14:17], v[152:155], v[214:217], v[14:17]
	v_mfma_f32_16x16x32_bf16 v[54:57], v[160:163], v[190:193], v[54:57]
	v_mfma_f32_16x16x32_bf16 v[38:41], v[160:163], v[198:201], v[38:41]
	v_mfma_f32_16x16x32_bf16 v[22:25], v[160:163], v[206:209], v[22:25]
	v_mfma_f32_16x16x32_bf16 v[6:9], v[160:163], v[214:217], v[6:9]
	s_setprio 0
	s_setprio 1
	v_mfma_f32_16x16x32_bf16 v[58:61], v[170:173], v[186:189], v[58:61]
	v_mfma_f32_16x16x32_bf16 v[42:45], v[170:173], v[194:197], v[42:45]
	v_mfma_f32_16x16x32_bf16 v[26:29], v[170:173], v[202:205], v[26:29]
	v_mfma_f32_16x16x32_bf16 v[10:13], v[170:173], v[210:213], v[10:13]
	v_mfma_f32_16x16x32_bf16 v[50:53], v[178:181], v[186:189], v[50:53]
	v_mfma_f32_16x16x32_bf16 v[34:37], v[178:181], v[194:197], v[34:37]
	v_mfma_f32_16x16x32_bf16 v[18:21], v[178:181], v[202:205], v[18:21]
	v_mfma_f32_16x16x32_bf16 v[2:5], v[178:181], v[210:213], v[2:5]
	v_mfma_f32_16x16x32_bf16 v[58:61], v[174:177], v[190:193], v[58:61]
	v_mfma_f32_16x16x32_bf16 v[42:45], v[174:177], v[198:201], v[42:45]
	v_mfma_f32_16x16x32_bf16 v[26:29], v[174:177], v[206:209], v[26:29]
	v_mfma_f32_16x16x32_bf16 v[10:13], v[174:177], v[214:217], v[10:13]
	v_mfma_f32_16x16x32_bf16 v[50:53], v[182:185], v[190:193], v[50:53]
	v_mfma_f32_16x16x32_bf16 v[34:37], v[182:185], v[198:201], v[34:37]
	v_mfma_f32_16x16x32_bf16 v[18:21], v[182:185], v[206:209], v[18:21]
	v_mfma_f32_16x16x32_bf16 v[2:5], v[182:185], v[214:217], v[2:5]
	s_setprio 0
	s_barrier
	s_add_i32 s54, 0, 0x18000
	s_add_i32 s55, 0, 0x1c000
	v_add_u32_e32 v160, s54, v165
	v_add_u32_e32 v182, s55, v165
	ds_read_b128 v[148:151], v160
	ds_read_b128 v[152:155], v160 offset:1024
	ds_read_b128 v[156:159], v160 offset:2048
	ds_read_b128 v[160:163], v160 offset:3072
	ds_read_b128 v[170:173], v182
	ds_read_b128 v[174:177], v182 offset:1024
	ds_read_b128 v[178:181], v182 offset:2048
	ds_read_b128 v[182:185], v182 offset:3072
	s_add_u32 s0, s30, 0x40000
	s_addc_u32 s1, s31, 0
	s_mov_b32 m0, s39
	v_lshl_add_u64 v[226:227], s[0:1], 0, v[136:137]
	ds_read_b128 v[186:189], v168 offset:32768
	ds_read_b128 v[190:193], v168 offset:33792
	ds_read_b128 v[194:197], v168 offset:34816
	ds_read_b128 v[198:201], v168 offset:35840
	ds_read_b128 v[202:205], v168 offset:36864
	ds_read_b128 v[206:209], v168 offset:37888
	ds_read_b128 v[210:213], v168 offset:38912
	ds_read_b128 v[214:217], v168 offset:39936
	global_load_lds_dwordx4 v[226:227], off
	v_lshl_add_u64 v[226:227], s[0:1], 0, v[132:133]
	s_mov_b32 m0, s40
	s_nop 0
	global_load_lds_dwordx4 v[226:227], off
	s_waitcnt vmcnt(8)
	s_waitcnt lgkmcnt(0)
	s_barrier
	s_setprio 1
	s_waitcnt lgkmcnt(0)
	v_mfma_f32_16x16x32_bf16 v[126:129], v[148:151], v[186:189], v[126:129]
	v_mfma_f32_16x16x32_bf16 v[110:113], v[148:151], v[194:197], v[110:113]
	v_mfma_f32_16x16x32_bf16 v[94:97], v[148:151], v[202:205], v[94:97]
	v_mfma_f32_16x16x32_bf16 v[78:81], v[148:151], v[210:213], v[78:81]
	v_mfma_f32_16x16x32_bf16 v[118:121], v[156:159], v[186:189], v[118:121]
	v_mfma_f32_16x16x32_bf16 v[102:105], v[156:159], v[194:197], v[102:105]
	v_mfma_f32_16x16x32_bf16 v[86:89], v[156:159], v[202:205], v[86:89]
	v_mfma_f32_16x16x32_bf16 v[70:73], v[156:159], v[210:213], v[70:73]
	v_mfma_f32_16x16x32_bf16 v[126:129], v[152:155], v[190:193], v[126:129]
	v_mfma_f32_16x16x32_bf16 v[110:113], v[152:155], v[198:201], v[110:113]
	v_mfma_f32_16x16x32_bf16 v[94:97], v[152:155], v[206:209], v[94:97]
	v_mfma_f32_16x16x32_bf16 v[78:81], v[152:155], v[214:217], v[78:81]
	v_mfma_f32_16x16x32_bf16 v[118:121], v[160:163], v[190:193], v[118:121]
	v_mfma_f32_16x16x32_bf16 v[102:105], v[160:163], v[198:201], v[102:105]
	v_mfma_f32_16x16x32_bf16 v[86:89], v[160:163], v[206:209], v[86:89]
	v_mfma_f32_16x16x32_bf16 v[70:73], v[160:163], v[214:217], v[70:73]
	s_setprio 0
	s_setprio 1
	v_mfma_f32_16x16x32_bf16 v[122:125], v[170:173], v[186:189], v[122:125]
	v_mfma_f32_16x16x32_bf16 v[106:109], v[170:173], v[194:197], v[106:109]
	v_mfma_f32_16x16x32_bf16 v[90:93], v[170:173], v[202:205], v[90:93]
	v_mfma_f32_16x16x32_bf16 v[74:77], v[170:173], v[210:213], v[74:77]
	v_mfma_f32_16x16x32_bf16 v[114:117], v[178:181], v[186:189], v[114:117]
	v_mfma_f32_16x16x32_bf16 v[98:101], v[178:181], v[194:197], v[98:101]
	v_mfma_f32_16x16x32_bf16 v[82:85], v[178:181], v[202:205], v[82:85]
	v_mfma_f32_16x16x32_bf16 v[66:69], v[178:181], v[210:213], v[66:69]
	v_mfma_f32_16x16x32_bf16 v[122:125], v[174:177], v[190:193], v[122:125]
	v_mfma_f32_16x16x32_bf16 v[106:109], v[174:177], v[198:201], v[106:109]
	v_mfma_f32_16x16x32_bf16 v[90:93], v[174:177], v[206:209], v[90:93]
	v_mfma_f32_16x16x32_bf16 v[74:77], v[174:177], v[214:217], v[74:77]
	v_mfma_f32_16x16x32_bf16 v[114:117], v[182:185], v[190:193], v[114:117]
	v_mfma_f32_16x16x32_bf16 v[98:101], v[182:185], v[198:201], v[98:101]
	v_mfma_f32_16x16x32_bf16 v[82:85], v[182:185], v[206:209], v[82:85]
	v_mfma_f32_16x16x32_bf16 v[66:69], v[182:185], v[214:217], v[66:69]
	s_setprio 0
	s_barrier
	s_add_i32 s0, s54, s35
	v_lshl_add_u64 v[218:219], v[218:219], 0, s[14:15]
	s_mov_b32 m0, s0
	ds_read_b128 v[186:189], v168 offset:49152
	ds_read_b128 v[190:193], v168 offset:50176
	ds_read_b128 v[194:197], v168 offset:51200
	ds_read_b128 v[198:201], v168 offset:52224
	ds_read_b128 v[202:205], v168 offset:53248
	ds_read_b128 v[206:209], v168 offset:54272
	ds_read_b128 v[210:213], v168 offset:55296
	ds_read_b128 v[214:217], v168 offset:56320
	global_load_lds_dwordx4 v[218:219], off
	s_add_i32 m0, s0, 0x2000
	s_add_u32 s0, s2, 0x40080
	v_lshl_add_u64 v[218:219], v[220:221], 0, s[14:15]
	s_addc_u32 s1, s3, 0
	s_add_i32 s2, s55, s35
	global_load_lds_dwordx4 v[218:219], off
	v_lshl_add_u64 v[218:219], s[0:1], 0, v[134:135]
	s_mov_b32 m0, s2
	s_nop 0
	global_load_lds_dwordx4 v[218:219], off
	v_lshl_add_u64 v[218:219], s[0:1], 0, v[130:131]
	s_add_i32 m0, s2, 0x2000
	s_nop 0
	global_load_lds_dwordx4 v[218:219], off
	v_lshl_add_u64 v[218:219], v[222:223], 0, s[14:15]
	s_mov_b32 m0, s41
	s_nop 0
	global_load_lds_dwordx4 v[218:219], off
	v_lshl_add_u64 v[218:219], v[224:225], 0, s[14:15]
	s_mov_b32 m0, s42
	s_nop 0
	global_load_lds_dwordx4 v[218:219], off
	s_waitcnt vmcnt(8)
	s_waitcnt lgkmcnt(0)
	s_barrier
	s_setprio 1
	s_waitcnt lgkmcnt(0)
	v_mfma_f32_16x16x32_bf16 v[62:65], v[148:151], v[186:189], v[62:65]
	v_mfma_f32_16x16x32_bf16 v[46:49], v[148:151], v[194:197], v[46:49]
	v_mfma_f32_16x16x32_bf16 v[30:33], v[148:151], v[202:205], v[30:33]
	v_mfma_f32_16x16x32_bf16 v[14:17], v[148:151], v[210:213], v[14:17]
	v_mfma_f32_16x16x32_bf16 v[54:57], v[156:159], v[186:189], v[54:57]
	v_mfma_f32_16x16x32_bf16 v[38:41], v[156:159], v[194:197], v[38:41]
	v_mfma_f32_16x16x32_bf16 v[22:25], v[156:159], v[202:205], v[22:25]
	v_mfma_f32_16x16x32_bf16 v[6:9], v[156:159], v[210:213], v[6:9]
	v_mfma_f32_16x16x32_bf16 v[62:65], v[152:155], v[190:193], v[62:65]
	v_mfma_f32_16x16x32_bf16 v[46:49], v[152:155], v[198:201], v[46:49]
	v_mfma_f32_16x16x32_bf16 v[30:33], v[152:155], v[206:209], v[30:33]
	v_mfma_f32_16x16x32_bf16 v[14:17], v[152:155], v[214:217], v[14:17]
	v_mfma_f32_16x16x32_bf16 v[54:57], v[160:163], v[190:193], v[54:57]
	v_mfma_f32_16x16x32_bf16 v[38:41], v[160:163], v[198:201], v[38:41]
	v_mfma_f32_16x16x32_bf16 v[22:25], v[160:163], v[206:209], v[22:25]
	v_mfma_f32_16x16x32_bf16 v[6:9], v[160:163], v[214:217], v[6:9]
	s_setprio 0
	s_setprio 1
	v_mfma_f32_16x16x32_bf16 v[58:61], v[170:173], v[186:189], v[58:61]
	v_mfma_f32_16x16x32_bf16 v[42:45], v[170:173], v[194:197], v[42:45]
	v_mfma_f32_16x16x32_bf16 v[26:29], v[170:173], v[202:205], v[26:29]
	v_mfma_f32_16x16x32_bf16 v[10:13], v[170:173], v[210:213], v[10:13]
	v_mfma_f32_16x16x32_bf16 v[50:53], v[178:181], v[186:189], v[50:53]
	v_mfma_f32_16x16x32_bf16 v[34:37], v[178:181], v[194:197], v[34:37]
	v_mfma_f32_16x16x32_bf16 v[18:21], v[178:181], v[202:205], v[18:21]
	v_mfma_f32_16x16x32_bf16 v[2:5], v[178:181], v[210:213], v[2:5]
	v_mfma_f32_16x16x32_bf16 v[58:61], v[174:177], v[190:193], v[58:61]
	v_mfma_f32_16x16x32_bf16 v[42:45], v[174:177], v[198:201], v[42:45]
	v_mfma_f32_16x16x32_bf16 v[26:29], v[174:177], v[206:209], v[26:29]
	v_mfma_f32_16x16x32_bf16 v[10:13], v[174:177], v[214:217], v[10:13]
	v_mfma_f32_16x16x32_bf16 v[50:53], v[182:185], v[190:193], v[50:53]
	v_mfma_f32_16x16x32_bf16 v[34:37], v[182:185], v[198:201], v[34:37]
	v_mfma_f32_16x16x32_bf16 v[18:21], v[182:185], v[206:209], v[18:21]
	v_mfma_f32_16x16x32_bf16 v[2:5], v[182:185], v[214:217], v[2:5]
	s_setprio 0
	s_barrier
	s_add_i32 s53, s53, 2
	s_add_u32 s28, s28, 0x100
	s_addc_u32 s29, s29, 0
	s_add_u32 s51, s51, 0x100
	s_addc_u32 s52, s52, 0
	s_cmp_gt_u32 s53, 13
	s_cbranch_scc0 .LBB0_1715
	s_and_b64 vcc, exec, s[16:17]
	s_cbranch_vccz .LBB0_1718
	s_barrier

.LBB0_1841:
	ds_read_b128 v[130:133], v186
	ds_read_b128 v[134:137], v186 offset:1024
	ds_read_b128 v[138:141], v186 offset:2048
	ds_read_b128 v[142:145], v186 offset:3072
	ds_read_b128 v[146:149], v187
	ds_read_b128 v[150:153], v187 offset:1024
	ds_read_b128 v[170:173], v187 offset:2048
	ds_read_b128 v[174:177], v187 offset:3072
	s_add_u32 s0, s30, 0xfff50080
	s_addc_u32 s1, s31, -1
	s_cmp_eq_u32 s55, 40
	s_cselect_b32 s35, s9, s1
	s_cselect_b32 s34, s8, s0
	s_cselect_b32 s3, s29, s54
	s_cselect_b32 s2, s28, s53
	v_lshl_add_u64 v[218:219], s[30:31], 0, v[162:163]
	s_add_i32 m0, s40, 0xc000
	ds_read_b128 v[178:181], v188
	ds_read_b128 v[190:193], v188 offset:1024
	ds_read_b128 v[194:197], v188 offset:2048
	ds_read_b128 v[198:201], v188 offset:3072
	ds_read_b128 v[202:205], v188 offset:4096
	ds_read_b128 v[206:209], v188 offset:5120
	ds_read_b128 v[210:213], v188 offset:6144
	ds_read_b128 v[214:217], v188 offset:7168
	global_load_lds_dwordx4 v[218:219], off
	v_lshl_add_u64 v[218:219], s[30:31], 0, v[164:165]
	s_add_i32 m0, s40, 0xe000
	s_nop 0
	global_load_lds_dwordx4 v[218:219], off
	s_waitcnt vmcnt(8)
	s_waitcnt lgkmcnt(0)
	s_barrier
	s_setprio 1
	s_waitcnt lgkmcnt(0)
	v_mfma_f32_16x16x32_bf16 v[126:129], v[130:133], v[178:181], v[126:129]
	v_mfma_f32_16x16x32_bf16 v[110:113], v[130:133], v[194:197], v[110:113]
	v_mfma_f32_16x16x32_bf16 v[94:97], v[130:133], v[202:205], v[94:97]
	v_mfma_f32_16x16x32_bf16 v[78:81], v[130:133], v[210:213], v[78:81]
	v_mfma_f32_16x16x32_bf16 v[122:125], v[138:141], v[178:181], v[122:125]
	v_mfma_f32_16x16x32_bf16 v[106:109], v[138:141], v[194:197], v[106:109]
	v_mfma_f32_16x16x32_bf16 v[90:93], v[138:141], v[202:205], v[90:93]
	v_mfma_f32_16x16x32_bf16 v[74:77], v[138:141], v[210:213], v[74:77]
	v_mfma_f32_16x16x32_bf16 v[126:129], v[134:137], v[190:193], v[126:129]
	v_mfma_f32_16x16x32_bf16 v[110:113], v[134:137], v[198:201], v[110:113]
	v_mfma_f32_16x16x32_bf16 v[94:97], v[134:137], v[206:209], v[94:97]
	v_mfma_f32_16x16x32_bf16 v[78:81], v[134:137], v[214:217], v[78:81]
	v_mfma_f32_16x16x32_bf16 v[122:125], v[142:145], v[190:193], v[122:125]
	v_mfma_f32_16x16x32_bf16 v[106:109], v[142:145], v[198:201], v[106:109]
	v_mfma_f32_16x16x32_bf16 v[90:93], v[142:145], v[206:209], v[90:93]
	v_mfma_f32_16x16x32_bf16 v[74:77], v[142:145], v[214:217], v[74:77]
	s_setprio 0
	s_setprio 1
	v_mfma_f32_16x16x32_bf16 v[118:121], v[146:149], v[178:181], v[118:121]
	v_mfma_f32_16x16x32_bf16 v[102:105], v[146:149], v[194:197], v[102:105]
	v_mfma_f32_16x16x32_bf16 v[86:89], v[146:149], v[202:205], v[86:89]
	v_mfma_f32_16x16x32_bf16 v[70:73], v[146:149], v[210:213], v[70:73]
	v_mfma_f32_16x16x32_bf16 v[114:117], v[170:173], v[178:181], v[114:117]
	v_mfma_f32_16x16x32_bf16 v[98:101], v[170:173], v[194:197], v[98:101]
	v_mfma_f32_16x16x32_bf16 v[82:85], v[170:173], v[202:205], v[82:85]
	v_mfma_f32_16x16x32_bf16 v[66:69], v[170:173], v[210:213], v[66:69]
	v_mfma_f32_16x16x32_bf16 v[118:121], v[150:153], v[190:193], v[118:121]
	v_mfma_f32_16x16x32_bf16 v[102:105], v[150:153], v[198:201], v[102:105]
	v_mfma_f32_16x16x32_bf16 v[86:89], v[150:153], v[206:209], v[86:89]
	v_mfma_f32_16x16x32_bf16 v[70:73], v[150:153], v[214:217], v[70:73]
	v_mfma_f32_16x16x32_bf16 v[114:117], v[174:177], v[190:193], v[114:117]
	v_mfma_f32_16x16x32_bf16 v[98:101], v[174:177], v[198:201], v[98:101]
	v_mfma_f32_16x16x32_bf16 v[82:85], v[174:177], v[206:209], v[82:85]
	v_mfma_f32_16x16x32_bf16 v[66:69], v[174:177], v[214:217], v[66:69]
	s_setprio 0
	s_barrier
	s_add_i32 s0, s49, s39
	v_lshl_add_u64 v[218:219], s[2:3], 0, v[156:157]
	s_mov_b32 m0, s0
	ds_read_b128 v[178:181], v188 offset:16384
	ds_read_b128 v[190:193], v188 offset:17408
	ds_read_b128 v[194:197], v188 offset:18432
	ds_read_b128 v[198:201], v188 offset:19456
	ds_read_b128 v[202:205], v188 offset:20480
	ds_read_b128 v[206:209], v188 offset:21504
	ds_read_b128 v[210:213], v188 offset:22528
	ds_read_b128 v[214:217], v188 offset:23552
	global_load_lds_dwordx4 v[218:219], off
	s_add_i32 m0, s0, 0x2000
	s_add_u32 s0, s2, 0xb0000
	v_lshl_add_u64 v[220:221], s[2:3], 0, v[160:161]
	s_addc_u32 s1, s3, 0
	s_add_i32 s56, s50, s39
	global_load_lds_dwordx4 v[220:221], off
	v_lshl_add_u64 v[222:223], s[0:1], 0, v[156:157]
	s_mov_b32 m0, s56
	v_lshl_add_u64 v[224:225], s[34:35], 0, v[158:159]
	global_load_lds_dwordx4 v[222:223], off
	v_lshl_add_u64 v[222:223], s[0:1], 0, v[160:161]
	s_add_i32 m0, s56, 0x2000
	s_nop 0
	global_load_lds_dwordx4 v[222:223], off
	v_lshl_add_u64 v[222:223], s[34:35], 0, v[154:155]
	s_mov_b32 m0, s40
	s_nop 0
	global_load_lds_dwordx4 v[222:223], off
	s_mov_b32 m0, s41
	s_nop 0
	global_load_lds_dwordx4 v[224:225], off
	s_waitcnt vmcnt(8)
	s_waitcnt lgkmcnt(0)
	s_barrier
	s_setprio 1
	s_waitcnt lgkmcnt(0)
	v_mfma_f32_16x16x32_bf16 v[62:65], v[130:133], v[178:181], v[62:65]
	v_mfma_f32_16x16x32_bf16 v[46:49], v[130:133], v[194:197], v[46:49]
	v_mfma_f32_16x16x32_bf16 v[30:33], v[130:133], v[202:205], v[30:33]
	v_mfma_f32_16x16x32_bf16 v[14:17], v[130:133], v[210:213], v[14:17]
	v_mfma_f32_16x16x32_bf16 v[58:61], v[138:141], v[178:181], v[58:61]
	v_mfma_f32_16x16x32_bf16 v[42:45], v[138:141], v[194:197], v[42:45]
	v_mfma_f32_16x16x32_bf16 v[26:29], v[138:141], v[202:205], v[26:29]
	v_mfma_f32_16x16x32_bf16 v[10:13], v[138:141], v[210:213], v[10:13]
	v_mfma_f32_16x16x32_bf16 v[62:65], v[134:137], v[190:193], v[62:65]
	v_mfma_f32_16x16x32_bf16 v[46:49], v[134:137], v[198:201], v[46:49]
	v_mfma_f32_16x16x32_bf16 v[30:33], v[134:137], v[206:209], v[30:33]
	v_mfma_f32_16x16x32_bf16 v[14:17], v[134:137], v[214:217], v[14:17]
	v_mfma_f32_16x16x32_bf16 v[58:61], v[142:145], v[190:193], v[58:61]
	v_mfma_f32_16x16x32_bf16 v[42:45], v[142:145], v[198:201], v[42:45]
	v_mfma_f32_16x16x32_bf16 v[26:29], v[142:145], v[206:209], v[26:29]
	v_mfma_f32_16x16x32_bf16 v[10:13], v[142:145], v[214:217], v[10:13]
	s_setprio 0
	s_setprio 1
	v_mfma_f32_16x16x32_bf16 v[54:57], v[146:149], v[178:181], v[54:57]
	v_mfma_f32_16x16x32_bf16 v[38:41], v[146:149], v[194:197], v[38:41]
	v_mfma_f32_16x16x32_bf16 v[22:25], v[146:149], v[202:205], v[22:25]
	v_mfma_f32_16x16x32_bf16 v[6:9], v[146:149], v[210:213], v[6:9]
	v_mfma_f32_16x16x32_bf16 v[50:53], v[170:173], v[178:181], v[50:53]
	v_mfma_f32_16x16x32_bf16 v[34:37], v[170:173], v[194:197], v[34:37]
	v_mfma_f32_16x16x32_bf16 v[18:21], v[170:173], v[202:205], v[18:21]
	v_mfma_f32_16x16x32_bf16 v[2:5], v[170:173], v[210:213], v[2:5]
	v_mfma_f32_16x16x32_bf16 v[54:57], v[150:153], v[190:193], v[54:57]
	v_mfma_f32_16x16x32_bf16 v[38:41], v[150:153], v[198:201], v[38:41]
	v_mfma_f32_16x16x32_bf16 v[22:25], v[150:153], v[206:209], v[22:25]
	v_mfma_f32_16x16x32_bf16 v[6:9], v[150:153], v[214:217], v[6:9]
	v_mfma_f32_16x16x32_bf16 v[50:53], v[174:177], v[190:193], v[50:53]
	v_mfma_f32_16x16x32_bf16 v[34:37], v[174:177], v[198:201], v[34:37]
	v_mfma_f32_16x16x32_bf16 v[18:21], v[174:177], v[206:209], v[18:21]
	v_mfma_f32_16x16x32_bf16 v[2:5], v[174:177], v[214:217], v[2:5]
	s_setprio 0
	s_barrier
	s_add_i32 s56, 0, 0x18000
	s_add_i32 s57, 0, 0x1c000
	v_add_u32_e32 v142, s56, v182
	v_add_u32_e32 v174, s57, v182
	ds_read_b128 v[130:133], v142
	ds_read_b128 v[134:137], v142 offset:1024
	ds_read_b128 v[138:141], v142 offset:2048
	ds_read_b128 v[142:145], v142 offset:3072
	ds_read_b128 v[146:149], v174
	ds_read_b128 v[150:153], v174 offset:1024
	ds_read_b128 v[170:173], v174 offset:2048
	ds_read_b128 v[174:177], v174 offset:3072
	s_add_u32 s0, s34, 0xb0000
	s_addc_u32 s1, s35, 0
	s_mov_b32 m0, s42
	v_lshl_add_u64 v[226:227], s[0:1], 0, v[154:155]
	ds_read_b128 v[178:181], v188 offset:32768
	ds_read_b128 v[190:193], v188 offset:33792
	ds_read_b128 v[194:197], v188 offset:34816
	ds_read_b128 v[198:201], v188 offset:35840
	ds_read_b128 v[202:205], v188 offset:36864
	ds_read_b128 v[206:209], v188 offset:37888
	ds_read_b128 v[210:213], v188 offset:38912
	ds_read_b128 v[214:217], v188 offset:39936
	global_load_lds_dwordx4 v[226:227], off
	v_lshl_add_u64 v[226:227], s[0:1], 0, v[158:159]
	s_mov_b32 m0, s43
	s_nop 0
	global_load_lds_dwordx4 v[226:227], off
	s_waitcnt vmcnt(8)
	s_waitcnt lgkmcnt(0)
	s_barrier
	s_setprio 1
	s_waitcnt lgkmcnt(0)
	v_mfma_f32_16x16x32_bf16 v[126:129], v[130:133], v[178:181], v[126:129]
	v_mfma_f32_16x16x32_bf16 v[110:113], v[130:133], v[194:197], v[110:113]
	v_mfma_f32_16x16x32_bf16 v[94:97], v[130:133], v[202:205], v[94:97]
	v_mfma_f32_16x16x32_bf16 v[78:81], v[130:133], v[210:213], v[78:81]
	v_mfma_f32_16x16x32_bf16 v[122:125], v[138:141], v[178:181], v[122:125]
	v_mfma_f32_16x16x32_bf16 v[106:109], v[138:141], v[194:197], v[106:109]
	v_mfma_f32_16x16x32_bf16 v[90:93], v[138:141], v[202:205], v[90:93]
	v_mfma_f32_16x16x32_bf16 v[74:77], v[138:141], v[210:213], v[74:77]
	v_mfma_f32_16x16x32_bf16 v[126:129], v[134:137], v[190:193], v[126:129]
	v_mfma_f32_16x16x32_bf16 v[110:113], v[134:137], v[198:201], v[110:113]
	v_mfma_f32_16x16x32_bf16 v[94:97], v[134:137], v[206:209], v[94:97]
	v_mfma_f32_16x16x32_bf16 v[78:81], v[134:137], v[214:217], v[78:81]
	v_mfma_f32_16x16x32_bf16 v[122:125], v[142:145], v[190:193], v[122:125]
	v_mfma_f32_16x16x32_bf16 v[106:109], v[142:145], v[198:201], v[106:109]
	v_mfma_f32_16x16x32_bf16 v[90:93], v[142:145], v[206:209], v[90:93]
	v_mfma_f32_16x16x32_bf16 v[74:77], v[142:145], v[214:217], v[74:77]
	s_setprio 0
	s_setprio 1
	v_mfma_f32_16x16x32_bf16 v[118:121], v[146:149], v[178:181], v[118:121]
	v_mfma_f32_16x16x32_bf16 v[102:105], v[146:149], v[194:197], v[102:105]
	v_mfma_f32_16x16x32_bf16 v[86:89], v[146:149], v[202:205], v[86:89]
	v_mfma_f32_16x16x32_bf16 v[70:73], v[146:149], v[210:213], v[70:73]
	v_mfma_f32_16x16x32_bf16 v[114:117], v[170:173], v[178:181], v[114:117]
	v_mfma_f32_16x16x32_bf16 v[98:101], v[170:173], v[194:197], v[98:101]
	v_mfma_f32_16x16x32_bf16 v[82:85], v[170:173], v[202:205], v[82:85]
	v_mfma_f32_16x16x32_bf16 v[66:69], v[170:173], v[210:213], v[66:69]
	v_mfma_f32_16x16x32_bf16 v[118:121], v[150:153], v[190:193], v[118:121]
	v_mfma_f32_16x16x32_bf16 v[102:105], v[150:153], v[198:201], v[102:105]
	v_mfma_f32_16x16x32_bf16 v[86:89], v[150:153], v[206:209], v[86:89]
	v_mfma_f32_16x16x32_bf16 v[70:73], v[150:153], v[214:217], v[70:73]
	v_mfma_f32_16x16x32_bf16 v[114:117], v[174:177], v[190:193], v[114:117]
	v_mfma_f32_16x16x32_bf16 v[98:101], v[174:177], v[198:201], v[98:101]
	v_mfma_f32_16x16x32_bf16 v[82:85], v[174:177], v[206:209], v[82:85]
	v_mfma_f32_16x16x32_bf16 v[66:69], v[174:177], v[214:217], v[66:69]
	s_setprio 0
	s_barrier
	s_add_i32 s0, s56, s39
	v_lshl_add_u64 v[218:219], v[218:219], 0, s[16:17]
	s_mov_b32 m0, s0
	ds_read_b128 v[178:181], v188 offset:49152
	ds_read_b128 v[190:193], v188 offset:50176
	ds_read_b128 v[194:197], v188 offset:51200
	ds_read_b128 v[198:201], v188 offset:52224
	ds_read_b128 v[202:205], v188 offset:53248
	ds_read_b128 v[206:209], v188 offset:54272
	ds_read_b128 v[210:213], v188 offset:55296
	ds_read_b128 v[214:217], v188 offset:56320
	global_load_lds_dwordx4 v[218:219], off
	s_add_i32 m0, s0, 0x2000
	s_add_u32 s0, s2, 0xb0080
	v_lshl_add_u64 v[218:219], v[220:221], 0, s[16:17]
	s_addc_u32 s1, s3, 0
	s_add_i32 s2, s57, s39
	global_load_lds_dwordx4 v[218:219], off
	v_lshl_add_u64 v[218:219], s[0:1], 0, v[156:157]
	s_mov_b32 m0, s2
	s_nop 0
	global_load_lds_dwordx4 v[218:219], off
	v_lshl_add_u64 v[218:219], s[0:1], 0, v[160:161]
	s_add_i32 m0, s2, 0x2000
	s_nop 0
	global_load_lds_dwordx4 v[218:219], off
	v_lshl_add_u64 v[218:219], v[222:223], 0, s[16:17]
	s_mov_b32 m0, s45
	s_nop 0
	global_load_lds_dwordx4 v[218:219], off
	v_lshl_add_u64 v[218:219], v[224:225], 0, s[16:17]
	s_mov_b32 m0, s46
	s_nop 0
	global_load_lds_dwordx4 v[218:219], off
	s_waitcnt vmcnt(8)
	s_waitcnt lgkmcnt(0)
	s_barrier
	s_setprio 1
	s_waitcnt lgkmcnt(0)
	v_mfma_f32_16x16x32_bf16 v[62:65], v[130:133], v[178:181], v[62:65]
	v_mfma_f32_16x16x32_bf16 v[46:49], v[130:133], v[194:197], v[46:49]
	v_mfma_f32_16x16x32_bf16 v[30:33], v[130:133], v[202:205], v[30:33]
	v_mfma_f32_16x16x32_bf16 v[14:17], v[130:133], v[210:213], v[14:17]
	v_mfma_f32_16x16x32_bf16 v[58:61], v[138:141], v[178:181], v[58:61]
	v_mfma_f32_16x16x32_bf16 v[42:45], v[138:141], v[194:197], v[42:45]
	v_mfma_f32_16x16x32_bf16 v[26:29], v[138:141], v[202:205], v[26:29]
	v_mfma_f32_16x16x32_bf16 v[10:13], v[138:141], v[210:213], v[10:13]
	v_mfma_f32_16x16x32_bf16 v[62:65], v[134:137], v[190:193], v[62:65]
	v_mfma_f32_16x16x32_bf16 v[46:49], v[134:137], v[198:201], v[46:49]
	v_mfma_f32_16x16x32_bf16 v[30:33], v[134:137], v[206:209], v[30:33]
	v_mfma_f32_16x16x32_bf16 v[14:17], v[134:137], v[214:217], v[14:17]
	v_mfma_f32_16x16x32_bf16 v[58:61], v[142:145], v[190:193], v[58:61]
	v_mfma_f32_16x16x32_bf16 v[42:45], v[142:145], v[198:201], v[42:45]
	v_mfma_f32_16x16x32_bf16 v[26:29], v[142:145], v[206:209], v[26:29]
	v_mfma_f32_16x16x32_bf16 v[10:13], v[142:145], v[214:217], v[10:13]
	s_setprio 0
	s_setprio 1
	v_mfma_f32_16x16x32_bf16 v[54:57], v[146:149], v[178:181], v[54:57]
	v_mfma_f32_16x16x32_bf16 v[38:41], v[146:149], v[194:197], v[38:41]
	v_mfma_f32_16x16x32_bf16 v[22:25], v[146:149], v[202:205], v[22:25]
	v_mfma_f32_16x16x32_bf16 v[6:9], v[146:149], v[210:213], v[6:9]
	v_mfma_f32_16x16x32_bf16 v[50:53], v[170:173], v[178:181], v[50:53]
	v_mfma_f32_16x16x32_bf16 v[34:37], v[170:173], v[194:197], v[34:37]
	v_mfma_f32_16x16x32_bf16 v[18:21], v[170:173], v[202:205], v[18:21]
	v_mfma_f32_16x16x32_bf16 v[2:5], v[170:173], v[210:213], v[2:5]
	v_mfma_f32_16x16x32_bf16 v[54:57], v[150:153], v[190:193], v[54:57]
	v_mfma_f32_16x16x32_bf16 v[38:41], v[150:153], v[198:201], v[38:41]
	v_mfma_f32_16x16x32_bf16 v[22:25], v[150:153], v[206:209], v[22:25]
	v_mfma_f32_16x16x32_bf16 v[6:9], v[150:153], v[214:217], v[6:9]
	v_mfma_f32_16x16x32_bf16 v[50:53], v[174:177], v[190:193], v[50:53]
	v_mfma_f32_16x16x32_bf16 v[34:37], v[174:177], v[198:201], v[34:37]
	v_mfma_f32_16x16x32_bf16 v[18:21], v[174:177], v[206:209], v[18:21]
	v_mfma_f32_16x16x32_bf16 v[2:5], v[174:177], v[214:217], v[2:5]
	s_setprio 0
	s_barrier
	s_add_i32 s55, s55, 2
	s_add_u32 s30, s30, 0x100
	s_addc_u32 s31, s31, 0
	s_add_u32 s53, s53, 0x100
	s_addc_u32 s54, s54, 0
	s_cmp_gt_u32 s55, 41
	s_cbranch_scc0 .LBB0_1841
	s_and_b64 vcc, exec, s[18:19]
	s_cbranch_vccz .LBB0_1844
	s_barrier

.LBB0_1938:
	ds_read_b128 v[148:151], v161
	ds_read_b128 v[152:155], v161 offset:1024
	ds_read_b128 v[156:159], v161 offset:2048
	ds_read_b128 v[166:169], v161 offset:3072
	ds_read_b128 v[170:173], v162
	ds_read_b128 v[174:177], v162 offset:1024
	ds_read_b128 v[178:181], v162 offset:2048
	ds_read_b128 v[182:185], v162 offset:3072
	s_add_u32 s0, s28, 0xfffc0080
	s_addc_u32 s1, s29, -1
	s_cmp_eq_u32 s51, 12
	s_cselect_b32 s31, s21, s1
	s_cselect_b32 s30, s47, s0
	s_cselect_b32 s3, s19, s50
	s_cselect_b32 s2, s48, s49
	v_lshl_add_u64 v[218:219], s[28:29], 0, v[140:141]
	s_add_i32 m0, s27, 0xc000
	ds_read_b128 v[186:189], v163
	ds_read_b128 v[190:193], v163 offset:1024
	ds_read_b128 v[194:197], v163 offset:2048
	ds_read_b128 v[198:201], v163 offset:3072
	ds_read_b128 v[202:205], v163 offset:4096
	ds_read_b128 v[206:209], v163 offset:5120
	ds_read_b128 v[210:213], v163 offset:6144
	ds_read_b128 v[214:217], v163 offset:7168
	global_load_lds_dwordx4 v[218:219], off
	v_lshl_add_u64 v[218:219], s[28:29], 0, v[142:143]
	s_add_i32 m0, s27, 0xe000
	s_nop 0
	global_load_lds_dwordx4 v[218:219], off
	s_waitcnt vmcnt(8)
	s_waitcnt lgkmcnt(0)
	s_barrier
	s_setprio 1
	s_waitcnt lgkmcnt(0)
	v_mfma_f32_16x16x32_bf16 v[126:129], v[148:151], v[186:189], v[126:129]
	v_mfma_f32_16x16x32_bf16 v[110:113], v[148:151], v[194:197], v[110:113]
	v_mfma_f32_16x16x32_bf16 v[94:97], v[148:151], v[202:205], v[94:97]
	v_mfma_f32_16x16x32_bf16 v[78:81], v[148:151], v[210:213], v[78:81]
	v_mfma_f32_16x16x32_bf16 v[118:121], v[156:159], v[186:189], v[118:121]
	v_mfma_f32_16x16x32_bf16 v[106:109], v[156:159], v[194:197], v[106:109]
	v_mfma_f32_16x16x32_bf16 v[90:93], v[156:159], v[202:205], v[90:93]
	v_mfma_f32_16x16x32_bf16 v[74:77], v[156:159], v[210:213], v[74:77]
	v_mfma_f32_16x16x32_bf16 v[126:129], v[152:155], v[190:193], v[126:129]
	v_mfma_f32_16x16x32_bf16 v[110:113], v[152:155], v[198:201], v[110:113]
	v_mfma_f32_16x16x32_bf16 v[94:97], v[152:155], v[206:209], v[94:97]
	v_mfma_f32_16x16x32_bf16 v[78:81], v[152:155], v[214:217], v[78:81]
	v_mfma_f32_16x16x32_bf16 v[118:121], v[166:169], v[190:193], v[118:121]
	v_mfma_f32_16x16x32_bf16 v[106:109], v[166:169], v[198:201], v[106:109]
	v_mfma_f32_16x16x32_bf16 v[90:93], v[166:169], v[206:209], v[90:93]
	v_mfma_f32_16x16x32_bf16 v[74:77], v[166:169], v[214:217], v[74:77]
	s_setprio 0
	s_setprio 1
	v_mfma_f32_16x16x32_bf16 v[122:125], v[170:173], v[186:189], v[122:125]
	v_mfma_f32_16x16x32_bf16 v[102:105], v[170:173], v[194:197], v[102:105]
	v_mfma_f32_16x16x32_bf16 v[86:89], v[170:173], v[202:205], v[86:89]
	v_mfma_f32_16x16x32_bf16 v[70:73], v[170:173], v[210:213], v[70:73]
	v_mfma_f32_16x16x32_bf16 v[114:117], v[178:181], v[186:189], v[114:117]
	v_mfma_f32_16x16x32_bf16 v[98:101], v[178:181], v[194:197], v[98:101]
	v_mfma_f32_16x16x32_bf16 v[82:85], v[178:181], v[202:205], v[82:85]
	v_mfma_f32_16x16x32_bf16 v[66:69], v[178:181], v[210:213], v[66:69]
	v_mfma_f32_16x16x32_bf16 v[122:125], v[174:177], v[190:193], v[122:125]
	v_mfma_f32_16x16x32_bf16 v[102:105], v[174:177], v[198:201], v[102:105]
	v_mfma_f32_16x16x32_bf16 v[86:89], v[174:177], v[206:209], v[86:89]
	v_mfma_f32_16x16x32_bf16 v[70:73], v[174:177], v[214:217], v[70:73]
	v_mfma_f32_16x16x32_bf16 v[114:117], v[182:185], v[190:193], v[114:117]
	v_mfma_f32_16x16x32_bf16 v[98:101], v[182:185], v[198:201], v[98:101]
	v_mfma_f32_16x16x32_bf16 v[82:85], v[182:185], v[206:209], v[82:85]
	v_mfma_f32_16x16x32_bf16 v[66:69], v[182:185], v[214:217], v[66:69]
	s_setprio 0
	s_barrier
	s_add_i32 s0, s43, s36
	v_lshl_add_u64 v[218:219], s[2:3], 0, v[132:133]
	s_mov_b32 m0, s0
	ds_read_b128 v[186:189], v163 offset:16384
	ds_read_b128 v[190:193], v163 offset:17408
	ds_read_b128 v[194:197], v163 offset:18432
	ds_read_b128 v[198:201], v163 offset:19456
	ds_read_b128 v[202:205], v163 offset:20480
	ds_read_b128 v[206:209], v163 offset:21504
	ds_read_b128 v[210:213], v163 offset:22528
	ds_read_b128 v[214:217], v163 offset:23552
	global_load_lds_dwordx4 v[218:219], off
	s_add_i32 m0, s0, 0x2000
	s_add_u32 s0, s2, 0x40000
	v_lshl_add_u64 v[220:221], s[2:3], 0, v[136:137]
	s_addc_u32 s1, s3, 0
	s_add_i32 s52, s44, s36
	global_load_lds_dwordx4 v[220:221], off
	v_lshl_add_u64 v[222:223], s[0:1], 0, v[132:133]
	s_mov_b32 m0, s52
	v_lshl_add_u64 v[224:225], s[30:31], 0, v[134:135]
	global_load_lds_dwordx4 v[222:223], off
	v_lshl_add_u64 v[222:223], s[0:1], 0, v[136:137]
	s_add_i32 m0, s52, 0x2000
	s_nop 0
	global_load_lds_dwordx4 v[222:223], off
	v_lshl_add_u64 v[222:223], s[30:31], 0, v[130:131]
	s_mov_b32 m0, s27
	s_nop 0
	global_load_lds_dwordx4 v[222:223], off
	s_mov_b32 m0, s37
	s_nop 0
	global_load_lds_dwordx4 v[224:225], off
	s_waitcnt vmcnt(8)
	s_waitcnt lgkmcnt(0)
	s_barrier
	s_setprio 1
	s_waitcnt lgkmcnt(0)
	v_mfma_f32_16x16x32_bf16 v[62:65], v[148:151], v[186:189], v[62:65]
	v_mfma_f32_16x16x32_bf16 v[46:49], v[148:151], v[194:197], v[46:49]
	v_mfma_f32_16x16x32_bf16 v[30:33], v[148:151], v[202:205], v[30:33]
	v_mfma_f32_16x16x32_bf16 v[14:17], v[148:151], v[210:213], v[14:17]
	v_mfma_f32_16x16x32_bf16 v[58:61], v[156:159], v[186:189], v[58:61]
	v_mfma_f32_16x16x32_bf16 v[42:45], v[156:159], v[194:197], v[42:45]
	v_mfma_f32_16x16x32_bf16 v[26:29], v[156:159], v[202:205], v[26:29]
	v_mfma_f32_16x16x32_bf16 v[10:13], v[156:159], v[210:213], v[10:13]
	v_mfma_f32_16x16x32_bf16 v[62:65], v[152:155], v[190:193], v[62:65]
	v_mfma_f32_16x16x32_bf16 v[46:49], v[152:155], v[198:201], v[46:49]
	v_mfma_f32_16x16x32_bf16 v[30:33], v[152:155], v[206:209], v[30:33]
	v_mfma_f32_16x16x32_bf16 v[14:17], v[152:155], v[214:217], v[14:17]
	v_mfma_f32_16x16x32_bf16 v[58:61], v[166:169], v[190:193], v[58:61]
	v_mfma_f32_16x16x32_bf16 v[42:45], v[166:169], v[198:201], v[42:45]
	v_mfma_f32_16x16x32_bf16 v[26:29], v[166:169], v[206:209], v[26:29]
	v_mfma_f32_16x16x32_bf16 v[10:13], v[166:169], v[214:217], v[10:13]
	s_setprio 0
	s_setprio 1
	v_mfma_f32_16x16x32_bf16 v[54:57], v[170:173], v[186:189], v[54:57]
	v_mfma_f32_16x16x32_bf16 v[38:41], v[170:173], v[194:197], v[38:41]
	v_mfma_f32_16x16x32_bf16 v[22:25], v[170:173], v[202:205], v[22:25]
	v_mfma_f32_16x16x32_bf16 v[6:9], v[170:173], v[210:213], v[6:9]
	v_mfma_f32_16x16x32_bf16 v[50:53], v[178:181], v[186:189], v[50:53]
	v_mfma_f32_16x16x32_bf16 v[34:37], v[178:181], v[194:197], v[34:37]
	v_mfma_f32_16x16x32_bf16 v[18:21], v[178:181], v[202:205], v[18:21]
	v_mfma_f32_16x16x32_bf16 v[2:5], v[178:181], v[210:213], v[2:5]
	v_mfma_f32_16x16x32_bf16 v[54:57], v[174:177], v[190:193], v[54:57]
	v_mfma_f32_16x16x32_bf16 v[38:41], v[174:177], v[198:201], v[38:41]
	v_mfma_f32_16x16x32_bf16 v[22:25], v[174:177], v[206:209], v[22:25]
	v_mfma_f32_16x16x32_bf16 v[6:9], v[174:177], v[214:217], v[6:9]
	v_mfma_f32_16x16x32_bf16 v[50:53], v[182:185], v[190:193], v[50:53]
	v_mfma_f32_16x16x32_bf16 v[34:37], v[182:185], v[198:201], v[34:37]
	v_mfma_f32_16x16x32_bf16 v[18:21], v[182:185], v[206:209], v[18:21]
	v_mfma_f32_16x16x32_bf16 v[2:5], v[182:185], v[214:217], v[2:5]
	s_setprio 0
	s_barrier
	s_add_i32 s52, 0, 0x18000
	v_add_u32_e32 v165, s52, v160
	s_add_i32 s53, 0, 0x1c000
	ds_read_b128 v[148:151], v165
	ds_read_b128 v[152:155], v165 offset:1024
	ds_read_b128 v[156:159], v165 offset:2048
	ds_read_b128 v[166:169], v165 offset:3072
	v_add_u32_e32 v165, s53, v160
	ds_read_b128 v[170:173], v165
	ds_read_b128 v[174:177], v165 offset:1024
	ds_read_b128 v[178:181], v165 offset:2048
	ds_read_b128 v[182:185], v165 offset:3072
	s_add_u32 s0, s30, 0x40000
	s_addc_u32 s1, s31, 0
	s_mov_b32 m0, s38
	v_lshl_add_u64 v[226:227], s[0:1], 0, v[130:131]
	ds_read_b128 v[186:189], v163 offset:32768
	ds_read_b128 v[190:193], v163 offset:33792
	ds_read_b128 v[194:197], v163 offset:34816
	ds_read_b128 v[198:201], v163 offset:35840
	ds_read_b128 v[202:205], v163 offset:36864
	ds_read_b128 v[206:209], v163 offset:37888
	ds_read_b128 v[210:213], v163 offset:38912
	ds_read_b128 v[214:217], v163 offset:39936
	global_load_lds_dwordx4 v[226:227], off
	v_lshl_add_u64 v[226:227], s[0:1], 0, v[134:135]
	s_mov_b32 m0, s39
	s_nop 0
	global_load_lds_dwordx4 v[226:227], off
	s_waitcnt vmcnt(8)
	s_waitcnt lgkmcnt(0)
	s_barrier
	s_setprio 1
	s_waitcnt lgkmcnt(0)
	v_mfma_f32_16x16x32_bf16 v[126:129], v[148:151], v[186:189], v[126:129]
	v_mfma_f32_16x16x32_bf16 v[110:113], v[148:151], v[194:197], v[110:113]
	v_mfma_f32_16x16x32_bf16 v[94:97], v[148:151], v[202:205], v[94:97]
	v_mfma_f32_16x16x32_bf16 v[78:81], v[148:151], v[210:213], v[78:81]
	v_mfma_f32_16x16x32_bf16 v[118:121], v[156:159], v[186:189], v[118:121]
	v_mfma_f32_16x16x32_bf16 v[106:109], v[156:159], v[194:197], v[106:109]
	v_mfma_f32_16x16x32_bf16 v[90:93], v[156:159], v[202:205], v[90:93]
	v_mfma_f32_16x16x32_bf16 v[74:77], v[156:159], v[210:213], v[74:77]
	v_mfma_f32_16x16x32_bf16 v[126:129], v[152:155], v[190:193], v[126:129]
	v_mfma_f32_16x16x32_bf16 v[110:113], v[152:155], v[198:201], v[110:113]
	v_mfma_f32_16x16x32_bf16 v[94:97], v[152:155], v[206:209], v[94:97]
	v_mfma_f32_16x16x32_bf16 v[78:81], v[152:155], v[214:217], v[78:81]
	v_mfma_f32_16x16x32_bf16 v[118:121], v[166:169], v[190:193], v[118:121]
	v_mfma_f32_16x16x32_bf16 v[106:109], v[166:169], v[198:201], v[106:109]
	v_mfma_f32_16x16x32_bf16 v[90:93], v[166:169], v[206:209], v[90:93]
	v_mfma_f32_16x16x32_bf16 v[74:77], v[166:169], v[214:217], v[74:77]
	s_setprio 0
	s_setprio 1
	v_mfma_f32_16x16x32_bf16 v[122:125], v[170:173], v[186:189], v[122:125]
	v_mfma_f32_16x16x32_bf16 v[102:105], v[170:173], v[194:197], v[102:105]
	v_mfma_f32_16x16x32_bf16 v[86:89], v[170:173], v[202:205], v[86:89]
	v_mfma_f32_16x16x32_bf16 v[70:73], v[170:173], v[210:213], v[70:73]
	v_mfma_f32_16x16x32_bf16 v[114:117], v[178:181], v[186:189], v[114:117]
	v_mfma_f32_16x16x32_bf16 v[98:101], v[178:181], v[194:197], v[98:101]
	v_mfma_f32_16x16x32_bf16 v[82:85], v[178:181], v[202:205], v[82:85]
	v_mfma_f32_16x16x32_bf16 v[66:69], v[178:181], v[210:213], v[66:69]
	v_mfma_f32_16x16x32_bf16 v[122:125], v[174:177], v[190:193], v[122:125]
	v_mfma_f32_16x16x32_bf16 v[102:105], v[174:177], v[198:201], v[102:105]
	v_mfma_f32_16x16x32_bf16 v[86:89], v[174:177], v[206:209], v[86:89]
	v_mfma_f32_16x16x32_bf16 v[70:73], v[174:177], v[214:217], v[70:73]
	v_mfma_f32_16x16x32_bf16 v[114:117], v[182:185], v[190:193], v[114:117]
	v_mfma_f32_16x16x32_bf16 v[98:101], v[182:185], v[198:201], v[98:101]
	v_mfma_f32_16x16x32_bf16 v[82:85], v[182:185], v[206:209], v[82:85]
	v_mfma_f32_16x16x32_bf16 v[66:69], v[182:185], v[214:217], v[66:69]
	s_setprio 0
	s_barrier
	s_add_i32 s0, s52, s36
	v_lshl_add_u64 v[218:219], v[218:219], 0, s[14:15]
	s_mov_b32 m0, s0
	ds_read_b128 v[186:189], v163 offset:49152
	ds_read_b128 v[190:193], v163 offset:50176
	ds_read_b128 v[194:197], v163 offset:51200
	ds_read_b128 v[198:201], v163 offset:52224
	ds_read_b128 v[202:205], v163 offset:53248
	ds_read_b128 v[206:209], v163 offset:54272
	ds_read_b128 v[210:213], v163 offset:55296
	ds_read_b128 v[214:217], v163 offset:56320
	global_load_lds_dwordx4 v[218:219], off
	s_add_i32 m0, s0, 0x2000
	s_add_u32 s0, s2, 0x40080
	v_lshl_add_u64 v[218:219], v[220:221], 0, s[14:15]
	s_addc_u32 s1, s3, 0
	s_add_i32 s2, s53, s36
	global_load_lds_dwordx4 v[218:219], off
	v_lshl_add_u64 v[218:219], s[0:1], 0, v[132:133]
	s_mov_b32 m0, s2
	s_nop 0
	global_load_lds_dwordx4 v[218:219], off
	v_lshl_add_u64 v[218:219], s[0:1], 0, v[136:137]
	s_add_i32 m0, s2, 0x2000
	s_nop 0
	global_load_lds_dwordx4 v[218:219], off
	v_lshl_add_u64 v[218:219], v[222:223], 0, s[14:15]
	s_mov_b32 m0, s40
	s_nop 0
	global_load_lds_dwordx4 v[218:219], off
	v_lshl_add_u64 v[218:219], v[224:225], 0, s[14:15]
	s_mov_b32 m0, s41
	s_nop 0
	global_load_lds_dwordx4 v[218:219], off
	s_waitcnt vmcnt(8)
	s_waitcnt lgkmcnt(0)
	s_barrier
	s_setprio 1
	s_waitcnt lgkmcnt(0)
	v_mfma_f32_16x16x32_bf16 v[62:65], v[148:151], v[186:189], v[62:65]
	v_mfma_f32_16x16x32_bf16 v[46:49], v[148:151], v[194:197], v[46:49]
	v_mfma_f32_16x16x32_bf16 v[30:33], v[148:151], v[202:205], v[30:33]
	v_mfma_f32_16x16x32_bf16 v[14:17], v[148:151], v[210:213], v[14:17]
	v_mfma_f32_16x16x32_bf16 v[58:61], v[156:159], v[186:189], v[58:61]
	v_mfma_f32_16x16x32_bf16 v[42:45], v[156:159], v[194:197], v[42:45]
	v_mfma_f32_16x16x32_bf16 v[26:29], v[156:159], v[202:205], v[26:29]
	v_mfma_f32_16x16x32_bf16 v[10:13], v[156:159], v[210:213], v[10:13]
	v_mfma_f32_16x16x32_bf16 v[62:65], v[152:155], v[190:193], v[62:65]
	v_mfma_f32_16x16x32_bf16 v[46:49], v[152:155], v[198:201], v[46:49]
	v_mfma_f32_16x16x32_bf16 v[30:33], v[152:155], v[206:209], v[30:33]
	v_mfma_f32_16x16x32_bf16 v[14:17], v[152:155], v[214:217], v[14:17]
	v_mfma_f32_16x16x32_bf16 v[58:61], v[166:169], v[190:193], v[58:61]
	v_mfma_f32_16x16x32_bf16 v[42:45], v[166:169], v[198:201], v[42:45]
	v_mfma_f32_16x16x32_bf16 v[26:29], v[166:169], v[206:209], v[26:29]
	v_mfma_f32_16x16x32_bf16 v[10:13], v[166:169], v[214:217], v[10:13]
	s_setprio 0
	s_setprio 1
	v_mfma_f32_16x16x32_bf16 v[54:57], v[170:173], v[186:189], v[54:57]
	v_mfma_f32_16x16x32_bf16 v[38:41], v[170:173], v[194:197], v[38:41]
	v_mfma_f32_16x16x32_bf16 v[22:25], v[170:173], v[202:205], v[22:25]
	v_mfma_f32_16x16x32_bf16 v[6:9], v[170:173], v[210:213], v[6:9]
	v_mfma_f32_16x16x32_bf16 v[50:53], v[178:181], v[186:189], v[50:53]
	v_mfma_f32_16x16x32_bf16 v[34:37], v[178:181], v[194:197], v[34:37]
	v_mfma_f32_16x16x32_bf16 v[18:21], v[178:181], v[202:205], v[18:21]
	v_mfma_f32_16x16x32_bf16 v[2:5], v[178:181], v[210:213], v[2:5]
	v_mfma_f32_16x16x32_bf16 v[54:57], v[174:177], v[190:193], v[54:57]
	v_mfma_f32_16x16x32_bf16 v[38:41], v[174:177], v[198:201], v[38:41]
	v_mfma_f32_16x16x32_bf16 v[22:25], v[174:177], v[206:209], v[22:25]
	v_mfma_f32_16x16x32_bf16 v[6:9], v[174:177], v[214:217], v[6:9]
	v_mfma_f32_16x16x32_bf16 v[50:53], v[182:185], v[190:193], v[50:53]
	v_mfma_f32_16x16x32_bf16 v[34:37], v[182:185], v[198:201], v[34:37]
	v_mfma_f32_16x16x32_bf16 v[18:21], v[182:185], v[206:209], v[18:21]
	v_mfma_f32_16x16x32_bf16 v[2:5], v[182:185], v[214:217], v[2:5]
	s_setprio 0
	s_barrier
	s_add_i32 s51, s51, 2
	s_add_u32 s28, s28, 0x100
	s_addc_u32 s29, s29, 0
	s_add_u32 s49, s49, 0x100
	s_addc_u32 s50, s50, 0
	s_cmp_gt_u32 s51, 13
	s_cbranch_scc0 .LBB0_1938
	s_and_b64 vcc, exec, s[16:17]
	s_cbranch_vccz .LBB0_1941
	s_barrier

.LBB0_2019:
	ds_read_b128 v[110:113], v227
	ds_read_b128 v[114:117], v227 offset:1024
	ds_read_b128 v[122:125], v227 offset:2048
	ds_read_b128 v[126:129], v227 offset:3072
	ds_read_b128 v[146:149], v228
	ds_read_b128 v[150:153], v228 offset:1024
	ds_read_b128 v[154:157], v228 offset:2048
	ds_read_b128 v[158:161], v228 offset:3072
	s_add_u32 s0, s10, 0xfffc0080
	s_addc_u32 s1, s11, -1
	s_cmp_eq_u32 s77, 12
	s_cselect_b32 s13, s7, s1
	s_cselect_b32 s12, s9, s0
	s_cselect_b32 s3, s55, s63
	s_cselect_b32 s2, s57, s62
	v_lshl_add_u64 v[212:213], s[10:11], 0, v[180:181]
	s_add_i32 m0, s66, 0xc000
	ds_read_b128 v[162:165], v229
	ds_read_b128 v[166:169], v229 offset:1024
	ds_read_b128 v[188:191], v229 offset:2048
	ds_read_b128 v[192:195], v229 offset:3072
	ds_read_b128 v[196:199], v229 offset:4096
	ds_read_b128 v[200:203], v229 offset:5120
	ds_read_b128 v[204:207], v229 offset:6144
	ds_read_b128 v[208:211], v229 offset:7168
	global_load_lds_dwordx4 v[212:213], off
	v_lshl_add_u64 v[212:213], s[10:11], 0, v[182:183]
	s_add_i32 m0, s66, 0xe000
	s_nop 0
	global_load_lds_dwordx4 v[212:213], off
	s_waitcnt vmcnt(8)
	s_waitcnt lgkmcnt(0)
	s_barrier
	s_setprio 1
	s_waitcnt lgkmcnt(0)
	v_mfma_f32_16x16x32_bf16 v[142:145], v[110:113], v[162:165], v[142:145]
	v_mfma_f32_16x16x32_bf16 v[134:137], v[110:113], v[188:191], v[134:137]
	v_mfma_f32_16x16x32_bf16 v[118:121], v[110:113], v[196:199], v[118:121]
	v_mfma_f32_16x16x32_bf16 v[102:105], v[110:113], v[204:207], v[102:105]
	v_mfma_f32_16x16x32_bf16 v[138:141], v[122:125], v[162:165], v[138:141]
	v_mfma_f32_16x16x32_bf16 v[130:133], v[122:125], v[188:191], v[130:133]
	v_mfma_f32_16x16x32_bf16 v[106:109], v[122:125], v[196:199], v[106:109]
	v_mfma_f32_16x16x32_bf16 v[98:101], v[122:125], v[204:207], v[98:101]
	v_mfma_f32_16x16x32_bf16 v[142:145], v[114:117], v[166:169], v[142:145]
	v_mfma_f32_16x16x32_bf16 v[134:137], v[114:117], v[192:195], v[134:137]
	v_mfma_f32_16x16x32_bf16 v[118:121], v[114:117], v[200:203], v[118:121]
	v_mfma_f32_16x16x32_bf16 v[102:105], v[114:117], v[208:211], v[102:105]
	v_mfma_f32_16x16x32_bf16 v[138:141], v[126:129], v[166:169], v[138:141]
	v_mfma_f32_16x16x32_bf16 v[130:133], v[126:129], v[192:195], v[130:133]
	v_mfma_f32_16x16x32_bf16 v[106:109], v[126:129], v[200:203], v[106:109]
	v_mfma_f32_16x16x32_bf16 v[98:101], v[126:129], v[208:211], v[98:101]
	s_setprio 0
	s_setprio 1
	v_mfma_f32_16x16x32_bf16 v[62:65], v[146:149], v[162:165], v[62:65]
	v_mfma_f32_16x16x32_bf16 v[54:57], v[146:149], v[188:191], v[54:57]
	v_mfma_f32_16x16x32_bf16 v[46:49], v[146:149], v[196:199], v[46:49]
	v_mfma_f32_16x16x32_bf16 v[38:41], v[146:149], v[204:207], v[38:41]
	v_mfma_f32_16x16x32_bf16 v[58:61], v[154:157], v[162:165], v[58:61]
	v_mfma_f32_16x16x32_bf16 v[50:53], v[154:157], v[188:191], v[50:53]
	v_mfma_f32_16x16x32_bf16 v[42:45], v[154:157], v[196:199], v[42:45]
	v_mfma_f32_16x16x32_bf16 v[34:37], v[154:157], v[204:207], v[34:37]
	v_mfma_f32_16x16x32_bf16 v[62:65], v[150:153], v[166:169], v[62:65]
	v_mfma_f32_16x16x32_bf16 v[54:57], v[150:153], v[192:195], v[54:57]
	v_mfma_f32_16x16x32_bf16 v[46:49], v[150:153], v[200:203], v[46:49]
	v_mfma_f32_16x16x32_bf16 v[38:41], v[150:153], v[208:211], v[38:41]
	v_mfma_f32_16x16x32_bf16 v[58:61], v[158:161], v[166:169], v[58:61]
	v_mfma_f32_16x16x32_bf16 v[50:53], v[158:161], v[192:195], v[50:53]
	v_mfma_f32_16x16x32_bf16 v[42:45], v[158:161], v[200:203], v[42:45]
	v_mfma_f32_16x16x32_bf16 v[34:37], v[158:161], v[208:211], v[34:37]
	s_setprio 0
	s_barrier
	s_add_i32 s0, s75, s65
	v_lshl_add_u64 v[212:213], s[2:3], 0, v[172:173]
	s_mov_b32 m0, s0
	ds_read_b128 v[162:165], v229 offset:16384
	ds_read_b128 v[166:169], v229 offset:17408
	ds_read_b128 v[188:191], v229 offset:18432
	ds_read_b128 v[192:195], v229 offset:19456
	ds_read_b128 v[196:199], v229 offset:20480
	ds_read_b128 v[200:203], v229 offset:21504
	ds_read_b128 v[204:207], v229 offset:22528
	ds_read_b128 v[208:211], v229 offset:23552
	global_load_lds_dwordx4 v[212:213], off
	s_add_i32 m0, s0, 0x2000
	s_add_u32 s0, s2, 0x40000
	v_lshl_add_u64 v[214:215], s[2:3], 0, v[176:177]
	s_addc_u32 s1, s3, 0
	s_add_i32 s78, s76, s65
	global_load_lds_dwordx4 v[214:215], off
	v_lshl_add_u64 v[216:217], s[0:1], 0, v[172:173]
	s_mov_b32 m0, s78
	v_lshl_add_u64 v[218:219], s[12:13], 0, v[174:175]
	global_load_lds_dwordx4 v[216:217], off
	v_lshl_add_u64 v[216:217], s[0:1], 0, v[176:177]
	s_add_i32 m0, s78, 0x2000
	s_nop 0
	global_load_lds_dwordx4 v[216:217], off
	v_lshl_add_u64 v[216:217], s[12:13], 0, v[170:171]
	s_mov_b32 m0, s66
	s_nop 0
	global_load_lds_dwordx4 v[216:217], off
	s_mov_b32 m0, s67
	s_nop 0
	global_load_lds_dwordx4 v[218:219], off
	s_waitcnt vmcnt(8)
	s_waitcnt lgkmcnt(0)
	s_barrier
	s_setprio 1
	s_waitcnt lgkmcnt(0)
	v_mfma_f32_16x16x32_bf16 v[94:97], v[110:113], v[162:165], v[94:97]
	v_mfma_f32_16x16x32_bf16 v[86:89], v[110:113], v[188:191], v[86:89]
	v_mfma_f32_16x16x32_bf16 v[78:81], v[110:113], v[196:199], v[78:81]
	v_mfma_f32_16x16x32_bf16 v[70:73], v[110:113], v[204:207], v[70:73]
	v_mfma_f32_16x16x32_bf16 v[90:93], v[122:125], v[162:165], v[90:93]
	v_mfma_f32_16x16x32_bf16 v[82:85], v[122:125], v[188:191], v[82:85]
	v_mfma_f32_16x16x32_bf16 v[74:77], v[122:125], v[196:199], v[74:77]
	v_mfma_f32_16x16x32_bf16 v[66:69], v[122:125], v[204:207], v[66:69]
	v_mfma_f32_16x16x32_bf16 v[94:97], v[114:117], v[166:169], v[94:97]
	v_mfma_f32_16x16x32_bf16 v[86:89], v[114:117], v[192:195], v[86:89]
	v_mfma_f32_16x16x32_bf16 v[78:81], v[114:117], v[200:203], v[78:81]
	v_mfma_f32_16x16x32_bf16 v[70:73], v[114:117], v[208:211], v[70:73]
	v_mfma_f32_16x16x32_bf16 v[90:93], v[126:129], v[166:169], v[90:93]
	v_mfma_f32_16x16x32_bf16 v[82:85], v[126:129], v[192:195], v[82:85]
	v_mfma_f32_16x16x32_bf16 v[74:77], v[126:129], v[200:203], v[74:77]
	v_mfma_f32_16x16x32_bf16 v[66:69], v[126:129], v[208:211], v[66:69]
	s_setprio 0
	s_setprio 1
	v_mfma_f32_16x16x32_bf16 v[30:33], v[146:149], v[162:165], v[30:33]
	v_mfma_f32_16x16x32_bf16 v[22:25], v[146:149], v[188:191], v[22:25]
	v_mfma_f32_16x16x32_bf16 v[14:17], v[146:149], v[196:199], v[14:17]
	v_mfma_f32_16x16x32_bf16 v[6:9], v[146:149], v[204:207], v[6:9]
	v_mfma_f32_16x16x32_bf16 v[26:29], v[154:157], v[162:165], v[26:29]
	v_mfma_f32_16x16x32_bf16 v[18:21], v[154:157], v[188:191], v[18:21]
	v_mfma_f32_16x16x32_bf16 v[10:13], v[154:157], v[196:199], v[10:13]
	v_mfma_f32_16x16x32_bf16 v[2:5], v[154:157], v[204:207], v[2:5]
	v_mfma_f32_16x16x32_bf16 v[30:33], v[150:153], v[166:169], v[30:33]
	v_mfma_f32_16x16x32_bf16 v[22:25], v[150:153], v[192:195], v[22:25]
	v_mfma_f32_16x16x32_bf16 v[14:17], v[150:153], v[200:203], v[14:17]
	v_mfma_f32_16x16x32_bf16 v[6:9], v[150:153], v[208:211], v[6:9]
	v_mfma_f32_16x16x32_bf16 v[26:29], v[158:161], v[166:169], v[26:29]
	v_mfma_f32_16x16x32_bf16 v[18:21], v[158:161], v[192:195], v[18:21]
	v_mfma_f32_16x16x32_bf16 v[10:13], v[158:161], v[200:203], v[10:13]
	v_mfma_f32_16x16x32_bf16 v[2:5], v[158:161], v[208:211], v[2:5]
	s_setprio 0
	s_barrier
	s_add_i32 s78, 0, 0x18000
	s_add_i32 s79, 0, 0x1c000
	v_add_u32_e32 v126, s78, v222
	v_add_u32_e32 v158, s79, v222
	ds_read_b128 v[110:113], v126
	ds_read_b128 v[114:117], v126 offset:1024
	ds_read_b128 v[122:125], v126 offset:2048
	ds_read_b128 v[126:129], v126 offset:3072
	ds_read_b128 v[146:149], v158
	ds_read_b128 v[150:153], v158 offset:1024
	ds_read_b128 v[154:157], v158 offset:2048
	ds_read_b128 v[158:161], v158 offset:3072
	s_add_u32 s0, s12, 0x40000
	s_addc_u32 s1, s13, 0
	s_mov_b32 m0, s68
	v_lshl_add_u64 v[220:221], s[0:1], 0, v[170:171]
	ds_read_b128 v[162:165], v229 offset:32768
	ds_read_b128 v[166:169], v229 offset:33792
	ds_read_b128 v[188:191], v229 offset:34816
	ds_read_b128 v[192:195], v229 offset:35840
	ds_read_b128 v[196:199], v229 offset:36864
	ds_read_b128 v[200:203], v229 offset:37888
	ds_read_b128 v[204:207], v229 offset:38912
	ds_read_b128 v[208:211], v229 offset:39936
	global_load_lds_dwordx4 v[220:221], off
	v_lshl_add_u64 v[220:221], s[0:1], 0, v[174:175]
	s_mov_b32 m0, s69
	s_nop 0
	global_load_lds_dwordx4 v[220:221], off
	s_waitcnt vmcnt(8)
	s_waitcnt lgkmcnt(0)
	s_barrier
	s_setprio 1
	s_waitcnt lgkmcnt(0)
	v_mfma_f32_16x16x32_bf16 v[142:145], v[110:113], v[162:165], v[142:145]
	v_mfma_f32_16x16x32_bf16 v[134:137], v[110:113], v[188:191], v[134:137]
	v_mfma_f32_16x16x32_bf16 v[118:121], v[110:113], v[196:199], v[118:121]
	v_mfma_f32_16x16x32_bf16 v[102:105], v[110:113], v[204:207], v[102:105]
	v_mfma_f32_16x16x32_bf16 v[138:141], v[122:125], v[162:165], v[138:141]
	v_mfma_f32_16x16x32_bf16 v[130:133], v[122:125], v[188:191], v[130:133]
	v_mfma_f32_16x16x32_bf16 v[106:109], v[122:125], v[196:199], v[106:109]
	v_mfma_f32_16x16x32_bf16 v[98:101], v[122:125], v[204:207], v[98:101]
	v_mfma_f32_16x16x32_bf16 v[142:145], v[114:117], v[166:169], v[142:145]
	v_mfma_f32_16x16x32_bf16 v[134:137], v[114:117], v[192:195], v[134:137]
	v_mfma_f32_16x16x32_bf16 v[118:121], v[114:117], v[200:203], v[118:121]
	v_mfma_f32_16x16x32_bf16 v[102:105], v[114:117], v[208:211], v[102:105]
	v_mfma_f32_16x16x32_bf16 v[138:141], v[126:129], v[166:169], v[138:141]
	v_mfma_f32_16x16x32_bf16 v[130:133], v[126:129], v[192:195], v[130:133]
	v_mfma_f32_16x16x32_bf16 v[106:109], v[126:129], v[200:203], v[106:109]
	v_mfma_f32_16x16x32_bf16 v[98:101], v[126:129], v[208:211], v[98:101]
	s_setprio 0
	s_setprio 1
	v_mfma_f32_16x16x32_bf16 v[62:65], v[146:149], v[162:165], v[62:65]
	v_mfma_f32_16x16x32_bf16 v[54:57], v[146:149], v[188:191], v[54:57]
	v_mfma_f32_16x16x32_bf16 v[46:49], v[146:149], v[196:199], v[46:49]
	v_mfma_f32_16x16x32_bf16 v[38:41], v[146:149], v[204:207], v[38:41]
	v_mfma_f32_16x16x32_bf16 v[58:61], v[154:157], v[162:165], v[58:61]
	v_mfma_f32_16x16x32_bf16 v[50:53], v[154:157], v[188:191], v[50:53]
	v_mfma_f32_16x16x32_bf16 v[42:45], v[154:157], v[196:199], v[42:45]
	v_mfma_f32_16x16x32_bf16 v[34:37], v[154:157], v[204:207], v[34:37]
	v_mfma_f32_16x16x32_bf16 v[62:65], v[150:153], v[166:169], v[62:65]
	v_mfma_f32_16x16x32_bf16 v[54:57], v[150:153], v[192:195], v[54:57]
	v_mfma_f32_16x16x32_bf16 v[46:49], v[150:153], v[200:203], v[46:49]
	v_mfma_f32_16x16x32_bf16 v[38:41], v[150:153], v[208:211], v[38:41]
	v_mfma_f32_16x16x32_bf16 v[58:61], v[158:161], v[166:169], v[58:61]
	v_mfma_f32_16x16x32_bf16 v[50:53], v[158:161], v[192:195], v[50:53]
	v_mfma_f32_16x16x32_bf16 v[42:45], v[158:161], v[200:203], v[42:45]
	v_mfma_f32_16x16x32_bf16 v[34:37], v[158:161], v[208:211], v[34:37]
	s_setprio 0
	s_barrier
	s_add_i32 s0, s78, s65
	v_lshl_add_u64 v[212:213], v[212:213], 0, s[24:25]
	s_mov_b32 m0, s0
	ds_read_b128 v[162:165], v229 offset:49152
	ds_read_b128 v[166:169], v229 offset:50176
	ds_read_b128 v[188:191], v229 offset:51200
	ds_read_b128 v[192:195], v229 offset:52224
	ds_read_b128 v[196:199], v229 offset:53248
	ds_read_b128 v[200:203], v229 offset:54272
	ds_read_b128 v[204:207], v229 offset:55296
	ds_read_b128 v[208:211], v229 offset:56320
	global_load_lds_dwordx4 v[212:213], off
	s_add_i32 m0, s0, 0x2000
	s_add_u32 s0, s2, 0x40080
	v_lshl_add_u64 v[212:213], v[214:215], 0, s[24:25]
	s_addc_u32 s1, s3, 0
	s_add_i32 s2, s79, s65
	global_load_lds_dwordx4 v[212:213], off
	v_lshl_add_u64 v[212:213], s[0:1], 0, v[172:173]
	s_mov_b32 m0, s2
	s_nop 0
	global_load_lds_dwordx4 v[212:213], off
	v_lshl_add_u64 v[212:213], s[0:1], 0, v[176:177]
	s_add_i32 m0, s2, 0x2000
	s_nop 0
	global_load_lds_dwordx4 v[212:213], off
	v_lshl_add_u64 v[212:213], v[216:217], 0, s[24:25]
	s_mov_b32 m0, s71
	s_nop 0
	global_load_lds_dwordx4 v[212:213], off
	v_lshl_add_u64 v[212:213], v[218:219], 0, s[24:25]
	s_mov_b32 m0, s72
	s_nop 0
	global_load_lds_dwordx4 v[212:213], off
	s_waitcnt vmcnt(8)
	s_waitcnt lgkmcnt(0)
	s_barrier
	s_setprio 1
	s_waitcnt lgkmcnt(0)
	v_mfma_f32_16x16x32_bf16 v[94:97], v[110:113], v[162:165], v[94:97]
	v_mfma_f32_16x16x32_bf16 v[86:89], v[110:113], v[188:191], v[86:89]
	v_mfma_f32_16x16x32_bf16 v[78:81], v[110:113], v[196:199], v[78:81]
	v_mfma_f32_16x16x32_bf16 v[70:73], v[110:113], v[204:207], v[70:73]
	v_mfma_f32_16x16x32_bf16 v[90:93], v[122:125], v[162:165], v[90:93]
	v_mfma_f32_16x16x32_bf16 v[82:85], v[122:125], v[188:191], v[82:85]
	v_mfma_f32_16x16x32_bf16 v[74:77], v[122:125], v[196:199], v[74:77]
	v_mfma_f32_16x16x32_bf16 v[66:69], v[122:125], v[204:207], v[66:69]
	v_mfma_f32_16x16x32_bf16 v[94:97], v[114:117], v[166:169], v[94:97]
	v_mfma_f32_16x16x32_bf16 v[86:89], v[114:117], v[192:195], v[86:89]
	v_mfma_f32_16x16x32_bf16 v[78:81], v[114:117], v[200:203], v[78:81]
	v_mfma_f32_16x16x32_bf16 v[70:73], v[114:117], v[208:211], v[70:73]
	v_mfma_f32_16x16x32_bf16 v[90:93], v[126:129], v[166:169], v[90:93]
	v_mfma_f32_16x16x32_bf16 v[82:85], v[126:129], v[192:195], v[82:85]
	v_mfma_f32_16x16x32_bf16 v[74:77], v[126:129], v[200:203], v[74:77]
	v_mfma_f32_16x16x32_bf16 v[66:69], v[126:129], v[208:211], v[66:69]
	s_setprio 0
	s_setprio 1
	v_mfma_f32_16x16x32_bf16 v[30:33], v[146:149], v[162:165], v[30:33]
	v_mfma_f32_16x16x32_bf16 v[22:25], v[146:149], v[188:191], v[22:25]
	v_mfma_f32_16x16x32_bf16 v[14:17], v[146:149], v[196:199], v[14:17]
	v_mfma_f32_16x16x32_bf16 v[6:9], v[146:149], v[204:207], v[6:9]
	v_mfma_f32_16x16x32_bf16 v[26:29], v[154:157], v[162:165], v[26:29]
	v_mfma_f32_16x16x32_bf16 v[18:21], v[154:157], v[188:191], v[18:21]
	v_mfma_f32_16x16x32_bf16 v[10:13], v[154:157], v[196:199], v[10:13]
	v_mfma_f32_16x16x32_bf16 v[2:5], v[154:157], v[204:207], v[2:5]
	v_mfma_f32_16x16x32_bf16 v[30:33], v[150:153], v[166:169], v[30:33]
	v_mfma_f32_16x16x32_bf16 v[22:25], v[150:153], v[192:195], v[22:25]
	v_mfma_f32_16x16x32_bf16 v[14:17], v[150:153], v[200:203], v[14:17]
	v_mfma_f32_16x16x32_bf16 v[6:9], v[150:153], v[208:211], v[6:9]
	v_mfma_f32_16x16x32_bf16 v[26:29], v[158:161], v[166:169], v[26:29]
	v_mfma_f32_16x16x32_bf16 v[18:21], v[158:161], v[192:195], v[18:21]
	v_mfma_f32_16x16x32_bf16 v[10:13], v[158:161], v[200:203], v[10:13]
	v_mfma_f32_16x16x32_bf16 v[2:5], v[158:161], v[208:211], v[2:5]
	s_setprio 0
	s_barrier
	s_add_i32 s77, s77, 2
	s_add_u32 s10, s10, 0x100
	s_addc_u32 s11, s11, 0
	s_add_u32 s62, s62, 0x100
	s_addc_u32 s63, s63, 0
	s_cmp_gt_u32 s77, 13
	s_cbranch_scc0 .LBB0_2019
	s_and_b64 vcc, exec, s[26:27]
	s_cbranch_vccz .LBB0_2022
	s_barrier

.LBB0_2118:
	ds_read_b128 v[130:133], v186
	ds_read_b128 v[134:137], v186 offset:1024
	ds_read_b128 v[138:141], v186 offset:2048
	ds_read_b128 v[142:145], v186 offset:3072
	ds_read_b128 v[146:149], v187
	ds_read_b128 v[150:153], v187 offset:1024
	ds_read_b128 v[170:173], v187 offset:2048
	ds_read_b128 v[174:177], v187 offset:3072
	s_add_u32 s0, s38, 0xfffc0080
	s_addc_u32 s1, s39, -1
	s_cmp_eq_u32 s59, 12
	s_cselect_b32 s41, s11, s1
	s_cselect_b32 s40, s29, s0
	s_cselect_b32 s3, s27, s58
	s_cselect_b32 s2, s56, s57
	v_lshl_add_u64 v[218:219], s[38:39], 0, v[162:163]
	s_add_i32 m0, s37, 0xc000
	ds_read_b128 v[178:181], v188
	ds_read_b128 v[190:193], v188 offset:1024
	ds_read_b128 v[194:197], v188 offset:2048
	ds_read_b128 v[198:201], v188 offset:3072
	ds_read_b128 v[202:205], v188 offset:4096
	ds_read_b128 v[206:209], v188 offset:5120
	ds_read_b128 v[210:213], v188 offset:6144
	ds_read_b128 v[214:217], v188 offset:7168
	global_load_lds_dwordx4 v[218:219], off
	v_lshl_add_u64 v[218:219], s[38:39], 0, v[164:165]
	s_add_i32 m0, s37, 0xe000
	s_nop 0
	global_load_lds_dwordx4 v[218:219], off
	s_waitcnt vmcnt(8)
	s_waitcnt lgkmcnt(0)
	s_barrier
	s_setprio 1
	s_waitcnt lgkmcnt(0)
	v_mfma_f32_16x16x32_bf16 v[126:129], v[130:133], v[178:181], v[126:129]
	v_mfma_f32_16x16x32_bf16 v[110:113], v[130:133], v[194:197], v[110:113]
	v_mfma_f32_16x16x32_bf16 v[94:97], v[130:133], v[202:205], v[94:97]
	v_mfma_f32_16x16x32_bf16 v[78:81], v[130:133], v[210:213], v[78:81]
	v_mfma_f32_16x16x32_bf16 v[122:125], v[138:141], v[178:181], v[122:125]
	v_mfma_f32_16x16x32_bf16 v[106:109], v[138:141], v[194:197], v[106:109]
	v_mfma_f32_16x16x32_bf16 v[90:93], v[138:141], v[202:205], v[90:93]
	v_mfma_f32_16x16x32_bf16 v[74:77], v[138:141], v[210:213], v[74:77]
	v_mfma_f32_16x16x32_bf16 v[126:129], v[134:137], v[190:193], v[126:129]
	v_mfma_f32_16x16x32_bf16 v[110:113], v[134:137], v[198:201], v[110:113]
	v_mfma_f32_16x16x32_bf16 v[94:97], v[134:137], v[206:209], v[94:97]
	v_mfma_f32_16x16x32_bf16 v[78:81], v[134:137], v[214:217], v[78:81]
	v_mfma_f32_16x16x32_bf16 v[122:125], v[142:145], v[190:193], v[122:125]
	v_mfma_f32_16x16x32_bf16 v[106:109], v[142:145], v[198:201], v[106:109]
	v_mfma_f32_16x16x32_bf16 v[90:93], v[142:145], v[206:209], v[90:93]
	v_mfma_f32_16x16x32_bf16 v[74:77], v[142:145], v[214:217], v[74:77]
	s_setprio 0
	s_setprio 1
	v_mfma_f32_16x16x32_bf16 v[118:121], v[146:149], v[178:181], v[118:121]
	v_mfma_f32_16x16x32_bf16 v[102:105], v[146:149], v[194:197], v[102:105]
	v_mfma_f32_16x16x32_bf16 v[86:89], v[146:149], v[202:205], v[86:89]
	v_mfma_f32_16x16x32_bf16 v[70:73], v[146:149], v[210:213], v[70:73]
	v_mfma_f32_16x16x32_bf16 v[114:117], v[170:173], v[178:181], v[114:117]
	v_mfma_f32_16x16x32_bf16 v[98:101], v[170:173], v[194:197], v[98:101]
	v_mfma_f32_16x16x32_bf16 v[82:85], v[170:173], v[202:205], v[82:85]
	v_mfma_f32_16x16x32_bf16 v[66:69], v[170:173], v[210:213], v[66:69]
	v_mfma_f32_16x16x32_bf16 v[118:121], v[150:153], v[190:193], v[118:121]
	v_mfma_f32_16x16x32_bf16 v[102:105], v[150:153], v[198:201], v[102:105]
	v_mfma_f32_16x16x32_bf16 v[86:89], v[150:153], v[206:209], v[86:89]
	v_mfma_f32_16x16x32_bf16 v[70:73], v[150:153], v[214:217], v[70:73]
	v_mfma_f32_16x16x32_bf16 v[114:117], v[174:177], v[190:193], v[114:117]
	v_mfma_f32_16x16x32_bf16 v[98:101], v[174:177], v[198:201], v[98:101]
	v_mfma_f32_16x16x32_bf16 v[82:85], v[174:177], v[206:209], v[82:85]
	v_mfma_f32_16x16x32_bf16 v[66:69], v[174:177], v[214:217], v[66:69]
	s_setprio 0
	s_barrier
	s_add_i32 s0, s54, s45
	v_lshl_add_u64 v[218:219], s[2:3], 0, v[156:157]
	s_mov_b32 m0, s0
	ds_read_b128 v[178:181], v188 offset:16384
	ds_read_b128 v[190:193], v188 offset:17408
	ds_read_b128 v[194:197], v188 offset:18432
	ds_read_b128 v[198:201], v188 offset:19456
	ds_read_b128 v[202:205], v188 offset:20480
	ds_read_b128 v[206:209], v188 offset:21504
	ds_read_b128 v[210:213], v188 offset:22528
	ds_read_b128 v[214:217], v188 offset:23552
	global_load_lds_dwordx4 v[218:219], off
	s_add_i32 m0, s0, 0x2000
	s_add_u32 s0, s2, 0x40000
	v_lshl_add_u64 v[220:221], s[2:3], 0, v[160:161]
	s_addc_u32 s1, s3, 0
	s_add_i32 s60, s55, s45
	global_load_lds_dwordx4 v[220:221], off
	v_lshl_add_u64 v[222:223], s[0:1], 0, v[156:157]
	s_mov_b32 m0, s60
	v_lshl_add_u64 v[224:225], s[40:41], 0, v[158:159]
	global_load_lds_dwordx4 v[222:223], off
	v_lshl_add_u64 v[222:223], s[0:1], 0, v[160:161]
	s_add_i32 m0, s60, 0x2000
	s_nop 0
	global_load_lds_dwordx4 v[222:223], off
	v_lshl_add_u64 v[222:223], s[40:41], 0, v[154:155]
	s_mov_b32 m0, s37
	s_nop 0
	global_load_lds_dwordx4 v[222:223], off
	s_mov_b32 m0, s46
	s_nop 0
	global_load_lds_dwordx4 v[224:225], off
	s_waitcnt vmcnt(8)
	s_waitcnt lgkmcnt(0)
	s_barrier
	s_setprio 1
	s_waitcnt lgkmcnt(0)
	v_mfma_f32_16x16x32_bf16 v[62:65], v[130:133], v[178:181], v[62:65]
	v_mfma_f32_16x16x32_bf16 v[46:49], v[130:133], v[194:197], v[46:49]
	v_mfma_f32_16x16x32_bf16 v[30:33], v[130:133], v[202:205], v[30:33]
	v_mfma_f32_16x16x32_bf16 v[14:17], v[130:133], v[210:213], v[14:17]
	v_mfma_f32_16x16x32_bf16 v[58:61], v[138:141], v[178:181], v[58:61]
	v_mfma_f32_16x16x32_bf16 v[42:45], v[138:141], v[194:197], v[42:45]
	v_mfma_f32_16x16x32_bf16 v[26:29], v[138:141], v[202:205], v[26:29]
	v_mfma_f32_16x16x32_bf16 v[10:13], v[138:141], v[210:213], v[10:13]
	v_mfma_f32_16x16x32_bf16 v[62:65], v[134:137], v[190:193], v[62:65]
	v_mfma_f32_16x16x32_bf16 v[46:49], v[134:137], v[198:201], v[46:49]
	v_mfma_f32_16x16x32_bf16 v[30:33], v[134:137], v[206:209], v[30:33]
	v_mfma_f32_16x16x32_bf16 v[14:17], v[134:137], v[214:217], v[14:17]
	v_mfma_f32_16x16x32_bf16 v[58:61], v[142:145], v[190:193], v[58:61]
	v_mfma_f32_16x16x32_bf16 v[42:45], v[142:145], v[198:201], v[42:45]
	v_mfma_f32_16x16x32_bf16 v[26:29], v[142:145], v[206:209], v[26:29]
	v_mfma_f32_16x16x32_bf16 v[10:13], v[142:145], v[214:217], v[10:13]
	s_setprio 0
	s_setprio 1
	v_mfma_f32_16x16x32_bf16 v[54:57], v[146:149], v[178:181], v[54:57]
	v_mfma_f32_16x16x32_bf16 v[38:41], v[146:149], v[194:197], v[38:41]
	v_mfma_f32_16x16x32_bf16 v[22:25], v[146:149], v[202:205], v[22:25]
	v_mfma_f32_16x16x32_bf16 v[6:9], v[146:149], v[210:213], v[6:9]
	v_mfma_f32_16x16x32_bf16 v[50:53], v[170:173], v[178:181], v[50:53]
	v_mfma_f32_16x16x32_bf16 v[34:37], v[170:173], v[194:197], v[34:37]
	v_mfma_f32_16x16x32_bf16 v[18:21], v[170:173], v[202:205], v[18:21]
	v_mfma_f32_16x16x32_bf16 v[2:5], v[170:173], v[210:213], v[2:5]
	v_mfma_f32_16x16x32_bf16 v[54:57], v[150:153], v[190:193], v[54:57]
	v_mfma_f32_16x16x32_bf16 v[38:41], v[150:153], v[198:201], v[38:41]
	v_mfma_f32_16x16x32_bf16 v[22:25], v[150:153], v[206:209], v[22:25]
	v_mfma_f32_16x16x32_bf16 v[6:9], v[150:153], v[214:217], v[6:9]
	v_mfma_f32_16x16x32_bf16 v[50:53], v[174:177], v[190:193], v[50:53]
	v_mfma_f32_16x16x32_bf16 v[34:37], v[174:177], v[198:201], v[34:37]
	v_mfma_f32_16x16x32_bf16 v[18:21], v[174:177], v[206:209], v[18:21]
	v_mfma_f32_16x16x32_bf16 v[2:5], v[174:177], v[214:217], v[2:5]
	s_setprio 0
	s_barrier
	s_add_i32 s60, 0, 0x18000
	s_add_i32 s61, 0, 0x1c000
	v_add_u32_e32 v142, s60, v182
	v_add_u32_e32 v174, s61, v182
	ds_read_b128 v[130:133], v142
	ds_read_b128 v[134:137], v142 offset:1024
	ds_read_b128 v[138:141], v142 offset:2048
	ds_read_b128 v[142:145], v142 offset:3072
	ds_read_b128 v[146:149], v174
	ds_read_b128 v[150:153], v174 offset:1024
	ds_read_b128 v[170:173], v174 offset:2048
	ds_read_b128 v[174:177], v174 offset:3072
	s_add_u32 s0, s40, 0x40000
	s_addc_u32 s1, s41, 0
	s_mov_b32 m0, s47
	v_lshl_add_u64 v[226:227], s[0:1], 0, v[154:155]
	ds_read_b128 v[178:181], v188 offset:32768
	ds_read_b128 v[190:193], v188 offset:33792
	ds_read_b128 v[194:197], v188 offset:34816
	ds_read_b128 v[198:201], v188 offset:35840
	ds_read_b128 v[202:205], v188 offset:36864
	ds_read_b128 v[206:209], v188 offset:37888
	ds_read_b128 v[210:213], v188 offset:38912
	ds_read_b128 v[214:217], v188 offset:39936
	global_load_lds_dwordx4 v[226:227], off
	v_lshl_add_u64 v[226:227], s[0:1], 0, v[158:159]
	s_mov_b32 m0, s48
	s_nop 0
	global_load_lds_dwordx4 v[226:227], off
	s_waitcnt vmcnt(8)
	s_waitcnt lgkmcnt(0)
	s_barrier
	s_setprio 1
	s_waitcnt lgkmcnt(0)
	v_mfma_f32_16x16x32_bf16 v[126:129], v[130:133], v[178:181], v[126:129]
	v_mfma_f32_16x16x32_bf16 v[110:113], v[130:133], v[194:197], v[110:113]
	v_mfma_f32_16x16x32_bf16 v[94:97], v[130:133], v[202:205], v[94:97]
	v_mfma_f32_16x16x32_bf16 v[78:81], v[130:133], v[210:213], v[78:81]
	v_mfma_f32_16x16x32_bf16 v[122:125], v[138:141], v[178:181], v[122:125]
	v_mfma_f32_16x16x32_bf16 v[106:109], v[138:141], v[194:197], v[106:109]
	v_mfma_f32_16x16x32_bf16 v[90:93], v[138:141], v[202:205], v[90:93]
	v_mfma_f32_16x16x32_bf16 v[74:77], v[138:141], v[210:213], v[74:77]
	v_mfma_f32_16x16x32_bf16 v[126:129], v[134:137], v[190:193], v[126:129]
	v_mfma_f32_16x16x32_bf16 v[110:113], v[134:137], v[198:201], v[110:113]
	v_mfma_f32_16x16x32_bf16 v[94:97], v[134:137], v[206:209], v[94:97]
	v_mfma_f32_16x16x32_bf16 v[78:81], v[134:137], v[214:217], v[78:81]
	v_mfma_f32_16x16x32_bf16 v[122:125], v[142:145], v[190:193], v[122:125]
	v_mfma_f32_16x16x32_bf16 v[106:109], v[142:145], v[198:201], v[106:109]
	v_mfma_f32_16x16x32_bf16 v[90:93], v[142:145], v[206:209], v[90:93]
	v_mfma_f32_16x16x32_bf16 v[74:77], v[142:145], v[214:217], v[74:77]
	s_setprio 0
	s_setprio 1
	v_mfma_f32_16x16x32_bf16 v[118:121], v[146:149], v[178:181], v[118:121]
	v_mfma_f32_16x16x32_bf16 v[102:105], v[146:149], v[194:197], v[102:105]
	v_mfma_f32_16x16x32_bf16 v[86:89], v[146:149], v[202:205], v[86:89]
	v_mfma_f32_16x16x32_bf16 v[70:73], v[146:149], v[210:213], v[70:73]
	v_mfma_f32_16x16x32_bf16 v[114:117], v[170:173], v[178:181], v[114:117]
	v_mfma_f32_16x16x32_bf16 v[98:101], v[170:173], v[194:197], v[98:101]
	v_mfma_f32_16x16x32_bf16 v[82:85], v[170:173], v[202:205], v[82:85]
	v_mfma_f32_16x16x32_bf16 v[66:69], v[170:173], v[210:213], v[66:69]
	v_mfma_f32_16x16x32_bf16 v[118:121], v[150:153], v[190:193], v[118:121]
	v_mfma_f32_16x16x32_bf16 v[102:105], v[150:153], v[198:201], v[102:105]
	v_mfma_f32_16x16x32_bf16 v[86:89], v[150:153], v[206:209], v[86:89]
	v_mfma_f32_16x16x32_bf16 v[70:73], v[150:153], v[214:217], v[70:73]
	v_mfma_f32_16x16x32_bf16 v[114:117], v[174:177], v[190:193], v[114:117]
	v_mfma_f32_16x16x32_bf16 v[98:101], v[174:177], v[198:201], v[98:101]
	v_mfma_f32_16x16x32_bf16 v[82:85], v[174:177], v[206:209], v[82:85]
	v_mfma_f32_16x16x32_bf16 v[66:69], v[174:177], v[214:217], v[66:69]
	s_setprio 0
	s_barrier
	s_add_i32 s0, s60, s45
	v_lshl_add_u64 v[218:219], v[218:219], 0, s[16:17]
	s_mov_b32 m0, s0
	ds_read_b128 v[178:181], v188 offset:49152
	ds_read_b128 v[190:193], v188 offset:50176
	ds_read_b128 v[194:197], v188 offset:51200
	ds_read_b128 v[198:201], v188 offset:52224
	ds_read_b128 v[202:205], v188 offset:53248
	ds_read_b128 v[206:209], v188 offset:54272
	ds_read_b128 v[210:213], v188 offset:55296
	ds_read_b128 v[214:217], v188 offset:56320
	global_load_lds_dwordx4 v[218:219], off
	s_add_i32 m0, s0, 0x2000
	s_add_u32 s0, s2, 0x40080
	v_lshl_add_u64 v[218:219], v[220:221], 0, s[16:17]
	s_addc_u32 s1, s3, 0
	s_add_i32 s2, s61, s45
	global_load_lds_dwordx4 v[218:219], off
	v_lshl_add_u64 v[218:219], s[0:1], 0, v[156:157]
	s_mov_b32 m0, s2
	s_nop 0
	global_load_lds_dwordx4 v[218:219], off
	v_lshl_add_u64 v[218:219], s[0:1], 0, v[160:161]
	s_add_i32 m0, s2, 0x2000
	s_nop 0
	global_load_lds_dwordx4 v[218:219], off
	v_lshl_add_u64 v[218:219], v[222:223], 0, s[16:17]
	s_mov_b32 m0, s50
	s_nop 0
	global_load_lds_dwordx4 v[218:219], off
	v_lshl_add_u64 v[218:219], v[224:225], 0, s[16:17]
	s_mov_b32 m0, s51
	s_nop 0
	global_load_lds_dwordx4 v[218:219], off
	s_waitcnt vmcnt(8)
	s_waitcnt lgkmcnt(0)
	s_barrier
	s_setprio 1
	s_waitcnt lgkmcnt(0)
	v_mfma_f32_16x16x32_bf16 v[62:65], v[130:133], v[178:181], v[62:65]
	v_mfma_f32_16x16x32_bf16 v[46:49], v[130:133], v[194:197], v[46:49]
	v_mfma_f32_16x16x32_bf16 v[30:33], v[130:133], v[202:205], v[30:33]
	v_mfma_f32_16x16x32_bf16 v[14:17], v[130:133], v[210:213], v[14:17]
	v_mfma_f32_16x16x32_bf16 v[58:61], v[138:141], v[178:181], v[58:61]
	v_mfma_f32_16x16x32_bf16 v[42:45], v[138:141], v[194:197], v[42:45]
	v_mfma_f32_16x16x32_bf16 v[26:29], v[138:141], v[202:205], v[26:29]
	v_mfma_f32_16x16x32_bf16 v[10:13], v[138:141], v[210:213], v[10:13]
	v_mfma_f32_16x16x32_bf16 v[62:65], v[134:137], v[190:193], v[62:65]
	v_mfma_f32_16x16x32_bf16 v[46:49], v[134:137], v[198:201], v[46:49]
	v_mfma_f32_16x16x32_bf16 v[30:33], v[134:137], v[206:209], v[30:33]
	v_mfma_f32_16x16x32_bf16 v[14:17], v[134:137], v[214:217], v[14:17]
	v_mfma_f32_16x16x32_bf16 v[58:61], v[142:145], v[190:193], v[58:61]
	v_mfma_f32_16x16x32_bf16 v[42:45], v[142:145], v[198:201], v[42:45]
	v_mfma_f32_16x16x32_bf16 v[26:29], v[142:145], v[206:209], v[26:29]
	v_mfma_f32_16x16x32_bf16 v[10:13], v[142:145], v[214:217], v[10:13]
	s_setprio 0
	s_setprio 1
	v_mfma_f32_16x16x32_bf16 v[54:57], v[146:149], v[178:181], v[54:57]
	v_mfma_f32_16x16x32_bf16 v[38:41], v[146:149], v[194:197], v[38:41]
	v_mfma_f32_16x16x32_bf16 v[22:25], v[146:149], v[202:205], v[22:25]
	v_mfma_f32_16x16x32_bf16 v[6:9], v[146:149], v[210:213], v[6:9]
	v_mfma_f32_16x16x32_bf16 v[50:53], v[170:173], v[178:181], v[50:53]
	v_mfma_f32_16x16x32_bf16 v[34:37], v[170:173], v[194:197], v[34:37]
	v_mfma_f32_16x16x32_bf16 v[18:21], v[170:173], v[202:205], v[18:21]
	v_mfma_f32_16x16x32_bf16 v[2:5], v[170:173], v[210:213], v[2:5]
	v_mfma_f32_16x16x32_bf16 v[54:57], v[150:153], v[190:193], v[54:57]
	v_mfma_f32_16x16x32_bf16 v[38:41], v[150:153], v[198:201], v[38:41]
	v_mfma_f32_16x16x32_bf16 v[22:25], v[150:153], v[206:209], v[22:25]
	v_mfma_f32_16x16x32_bf16 v[6:9], v[150:153], v[214:217], v[6:9]
	v_mfma_f32_16x16x32_bf16 v[50:53], v[174:177], v[190:193], v[50:53]
	v_mfma_f32_16x16x32_bf16 v[34:37], v[174:177], v[198:201], v[34:37]
	v_mfma_f32_16x16x32_bf16 v[18:21], v[174:177], v[206:209], v[18:21]
	v_mfma_f32_16x16x32_bf16 v[2:5], v[174:177], v[214:217], v[2:5]
	s_setprio 0
	s_barrier
	s_add_i32 s59, s59, 2
	s_add_u32 s38, s38, 0x100
	s_addc_u32 s39, s39, 0
	s_add_u32 s57, s57, 0x100
	s_addc_u32 s58, s58, 0
	s_cmp_gt_u32 s59, 13
	s_cbranch_scc0 .LBB0_2118
	s_and_b64 vcc, exec, s[18:19]
	s_cbranch_vccz .LBB0_2121
	s_barrier

.LBB0_2207:
	ds_read_b128 v[148:151], v165
	ds_read_b128 v[152:155], v165 offset:1024
	ds_read_b128 v[156:159], v165 offset:2048
	ds_read_b128 v[160:163], v165 offset:3072
	ds_read_b128 v[170:173], v166
	ds_read_b128 v[174:177], v166 offset:1024
	ds_read_b128 v[178:181], v166 offset:2048
	ds_read_b128 v[182:185], v166 offset:3072
	s_add_u32 s0, s28, 0xfffc0080
	s_addc_u32 s1, s29, -1
	s_cmp_eq_u32 s53, 12
	s_cselect_b32 s31, s21, s1
	s_cselect_b32 s30, s49, s0
	s_cselect_b32 s3, s19, s52
	s_cselect_b32 s2, s50, s51
	v_lshl_add_u64 v[218:219], s[28:29], 0, v[140:141]
	s_add_i32 m0, s27, 0xc000
	ds_read_b128 v[186:189], v167
	ds_read_b128 v[190:193], v167 offset:1024
	ds_read_b128 v[194:197], v167 offset:2048
	ds_read_b128 v[198:201], v167 offset:3072
	ds_read_b128 v[202:205], v167 offset:4096
	ds_read_b128 v[206:209], v167 offset:5120
	ds_read_b128 v[210:213], v167 offset:6144
	ds_read_b128 v[214:217], v167 offset:7168
	global_load_lds_dwordx4 v[218:219], off
	v_lshl_add_u64 v[218:219], s[28:29], 0, v[142:143]
	s_add_i32 m0, s27, 0xe000
	s_nop 0
	global_load_lds_dwordx4 v[218:219], off
	s_waitcnt vmcnt(8)
	s_waitcnt lgkmcnt(0)
	s_barrier
	s_setprio 1
	s_waitcnt lgkmcnt(0)
	v_mfma_f32_16x16x32_bf16 v[126:129], v[148:151], v[186:189], v[126:129]
	v_mfma_f32_16x16x32_bf16 v[110:113], v[148:151], v[194:197], v[110:113]
	v_mfma_f32_16x16x32_bf16 v[94:97], v[148:151], v[202:205], v[94:97]
	v_mfma_f32_16x16x32_bf16 v[78:81], v[148:151], v[210:213], v[78:81]
	v_mfma_f32_16x16x32_bf16 v[118:121], v[156:159], v[186:189], v[118:121]
	v_mfma_f32_16x16x32_bf16 v[102:105], v[156:159], v[194:197], v[102:105]
	v_mfma_f32_16x16x32_bf16 v[86:89], v[156:159], v[202:205], v[86:89]
	v_mfma_f32_16x16x32_bf16 v[70:73], v[156:159], v[210:213], v[70:73]
	v_mfma_f32_16x16x32_bf16 v[126:129], v[152:155], v[190:193], v[126:129]
	v_mfma_f32_16x16x32_bf16 v[110:113], v[152:155], v[198:201], v[110:113]
	v_mfma_f32_16x16x32_bf16 v[94:97], v[152:155], v[206:209], v[94:97]
	v_mfma_f32_16x16x32_bf16 v[78:81], v[152:155], v[214:217], v[78:81]
	v_mfma_f32_16x16x32_bf16 v[118:121], v[160:163], v[190:193], v[118:121]
	v_mfma_f32_16x16x32_bf16 v[102:105], v[160:163], v[198:201], v[102:105]
	v_mfma_f32_16x16x32_bf16 v[86:89], v[160:163], v[206:209], v[86:89]
	v_mfma_f32_16x16x32_bf16 v[70:73], v[160:163], v[214:217], v[70:73]
	s_setprio 0
	s_setprio 1
	v_mfma_f32_16x16x32_bf16 v[122:125], v[170:173], v[186:189], v[122:125]
	v_mfma_f32_16x16x32_bf16 v[106:109], v[170:173], v[194:197], v[106:109]
	v_mfma_f32_16x16x32_bf16 v[90:93], v[170:173], v[202:205], v[90:93]
	v_mfma_f32_16x16x32_bf16 v[74:77], v[170:173], v[210:213], v[74:77]
	v_mfma_f32_16x16x32_bf16 v[114:117], v[178:181], v[186:189], v[114:117]
	v_mfma_f32_16x16x32_bf16 v[98:101], v[178:181], v[194:197], v[98:101]
	v_mfma_f32_16x16x32_bf16 v[82:85], v[178:181], v[202:205], v[82:85]
	v_mfma_f32_16x16x32_bf16 v[66:69], v[178:181], v[210:213], v[66:69]
	v_mfma_f32_16x16x32_bf16 v[122:125], v[174:177], v[190:193], v[122:125]
	v_mfma_f32_16x16x32_bf16 v[106:109], v[174:177], v[198:201], v[106:109]
	v_mfma_f32_16x16x32_bf16 v[90:93], v[174:177], v[206:209], v[90:93]
	v_mfma_f32_16x16x32_bf16 v[74:77], v[174:177], v[214:217], v[74:77]
	v_mfma_f32_16x16x32_bf16 v[114:117], v[182:185], v[190:193], v[114:117]
	v_mfma_f32_16x16x32_bf16 v[98:101], v[182:185], v[198:201], v[98:101]
	v_mfma_f32_16x16x32_bf16 v[82:85], v[182:185], v[206:209], v[82:85]
	v_mfma_f32_16x16x32_bf16 v[66:69], v[182:185], v[214:217], v[66:69]
	s_setprio 0
	s_barrier
	s_add_i32 s0, s44, s35
	v_lshl_add_u64 v[218:219], s[2:3], 0, v[134:135]
	s_mov_b32 m0, s0
	ds_read_b128 v[186:189], v167 offset:16384
	ds_read_b128 v[190:193], v167 offset:17408
	ds_read_b128 v[194:197], v167 offset:18432
	ds_read_b128 v[198:201], v167 offset:19456
	ds_read_b128 v[202:205], v167 offset:20480
	ds_read_b128 v[206:209], v167 offset:21504
	ds_read_b128 v[210:213], v167 offset:22528
	ds_read_b128 v[214:217], v167 offset:23552
	global_load_lds_dwordx4 v[218:219], off
	s_add_i32 m0, s0, 0x2000
	s_add_u32 s0, s2, 0x40000
	v_lshl_add_u64 v[220:221], s[2:3], 0, v[130:131]
	s_addc_u32 s1, s3, 0
	s_add_i32 s54, s45, s35
	global_load_lds_dwordx4 v[220:221], off
	v_lshl_add_u64 v[222:223], s[0:1], 0, v[134:135]
	s_mov_b32 m0, s54
	v_lshl_add_u64 v[224:225], s[30:31], 0, v[132:133]
	global_load_lds_dwordx4 v[222:223], off
	v_lshl_add_u64 v[222:223], s[0:1], 0, v[130:131]
	s_add_i32 m0, s54, 0x2000
	s_nop 0
	global_load_lds_dwordx4 v[222:223], off
	v_lshl_add_u64 v[222:223], s[30:31], 0, v[136:137]
	s_mov_b32 m0, s27
	s_nop 0
	global_load_lds_dwordx4 v[222:223], off
	s_mov_b32 m0, s38
	s_nop 0
	global_load_lds_dwordx4 v[224:225], off
	s_waitcnt vmcnt(8)
	s_waitcnt lgkmcnt(0)
	s_barrier
	s_setprio 1
	s_waitcnt lgkmcnt(0)
	v_mfma_f32_16x16x32_bf16 v[62:65], v[148:151], v[186:189], v[62:65]
	v_mfma_f32_16x16x32_bf16 v[46:49], v[148:151], v[194:197], v[46:49]
	v_mfma_f32_16x16x32_bf16 v[30:33], v[148:151], v[202:205], v[30:33]
	v_mfma_f32_16x16x32_bf16 v[14:17], v[148:151], v[210:213], v[14:17]
	v_mfma_f32_16x16x32_bf16 v[54:57], v[156:159], v[186:189], v[54:57]
	v_mfma_f32_16x16x32_bf16 v[38:41], v[156:159], v[194:197], v[38:41]
	v_mfma_f32_16x16x32_bf16 v[22:25], v[156:159], v[202:205], v[22:25]
	v_mfma_f32_16x16x32_bf16 v[6:9], v[156:159], v[210:213], v[6:9]
	v_mfma_f32_16x16x32_bf16 v[62:65], v[152:155], v[190:193], v[62:65]
	v_mfma_f32_16x16x32_bf16 v[46:49], v[152:155], v[198:201], v[46:49]
	v_mfma_f32_16x16x32_bf16 v[30:33], v[152:155], v[206:209], v[30:33]
	v_mfma_f32_16x16x32_bf16 v[14:17], v[152:155], v[214:217], v[14:17]
	v_mfma_f32_16x16x32_bf16 v[54:57], v[160:163], v[190:193], v[54:57]
	v_mfma_f32_16x16x32_bf16 v[38:41], v[160:163], v[198:201], v[38:41]
	v_mfma_f32_16x16x32_bf16 v[22:25], v[160:163], v[206:209], v[22:25]
	v_mfma_f32_16x16x32_bf16 v[6:9], v[160:163], v[214:217], v[6:9]
	s_setprio 0
	s_setprio 1
	v_mfma_f32_16x16x32_bf16 v[58:61], v[170:173], v[186:189], v[58:61]
	v_mfma_f32_16x16x32_bf16 v[42:45], v[170:173], v[194:197], v[42:45]
	v_mfma_f32_16x16x32_bf16 v[26:29], v[170:173], v[202:205], v[26:29]
	v_mfma_f32_16x16x32_bf16 v[10:13], v[170:173], v[210:213], v[10:13]
	v_mfma_f32_16x16x32_bf16 v[50:53], v[178:181], v[186:189], v[50:53]
	v_mfma_f32_16x16x32_bf16 v[34:37], v[178:181], v[194:197], v[34:37]
	v_mfma_f32_16x16x32_bf16 v[18:21], v[178:181], v[202:205], v[18:21]
	v_mfma_f32_16x16x32_bf16 v[2:5], v[178:181], v[210:213], v[2:5]
	v_mfma_f32_16x16x32_bf16 v[58:61], v[174:177], v[190:193], v[58:61]
	v_mfma_f32_16x16x32_bf16 v[42:45], v[174:177], v[198:201], v[42:45]
	v_mfma_f32_16x16x32_bf16 v[26:29], v[174:177], v[206:209], v[26:29]
	v_mfma_f32_16x16x32_bf16 v[10:13], v[174:177], v[214:217], v[10:13]
	v_mfma_f32_16x16x32_bf16 v[50:53], v[182:185], v[190:193], v[50:53]
	v_mfma_f32_16x16x32_bf16 v[34:37], v[182:185], v[198:201], v[34:37]
	v_mfma_f32_16x16x32_bf16 v[18:21], v[182:185], v[206:209], v[18:21]
	v_mfma_f32_16x16x32_bf16 v[2:5], v[182:185], v[214:217], v[2:5]
	s_setprio 0
	s_barrier
	s_add_i32 s54, 0, 0x18000
	s_add_i32 s55, 0, 0x1c000
	v_add_u32_e32 v160, s54, v164
	v_add_u32_e32 v169, s55, v164
	ds_read_b128 v[148:151], v160
	ds_read_b128 v[152:155], v160 offset:1024
	ds_read_b128 v[156:159], v160 offset:2048
	ds_read_b128 v[160:163], v160 offset:3072
	ds_read_b128 v[170:173], v169
	ds_read_b128 v[174:177], v169 offset:1024
	ds_read_b128 v[178:181], v169 offset:2048
	ds_read_b128 v[182:185], v169 offset:3072
	s_add_u32 s0, s30, 0x40000
	s_addc_u32 s1, s31, 0
	s_mov_b32 m0, s39
	v_lshl_add_u64 v[226:227], s[0:1], 0, v[136:137]
	ds_read_b128 v[186:189], v167 offset:32768
	ds_read_b128 v[190:193], v167 offset:33792
	ds_read_b128 v[194:197], v167 offset:34816
	ds_read_b128 v[198:201], v167 offset:35840
	ds_read_b128 v[202:205], v167 offset:36864
	ds_read_b128 v[206:209], v167 offset:37888
	ds_read_b128 v[210:213], v167 offset:38912
	ds_read_b128 v[214:217], v167 offset:39936
	global_load_lds_dwordx4 v[226:227], off
	v_lshl_add_u64 v[226:227], s[0:1], 0, v[132:133]
	s_mov_b32 m0, s40
	s_nop 0
	global_load_lds_dwordx4 v[226:227], off
	s_waitcnt vmcnt(8)
	s_waitcnt lgkmcnt(0)
	s_barrier
	s_setprio 1
	s_waitcnt lgkmcnt(0)
	v_mfma_f32_16x16x32_bf16 v[126:129], v[148:151], v[186:189], v[126:129]
	v_mfma_f32_16x16x32_bf16 v[110:113], v[148:151], v[194:197], v[110:113]
	v_mfma_f32_16x16x32_bf16 v[94:97], v[148:151], v[202:205], v[94:97]
	v_mfma_f32_16x16x32_bf16 v[78:81], v[148:151], v[210:213], v[78:81]
	v_mfma_f32_16x16x32_bf16 v[118:121], v[156:159], v[186:189], v[118:121]
	v_mfma_f32_16x16x32_bf16 v[102:105], v[156:159], v[194:197], v[102:105]
	v_mfma_f32_16x16x32_bf16 v[86:89], v[156:159], v[202:205], v[86:89]
	v_mfma_f32_16x16x32_bf16 v[70:73], v[156:159], v[210:213], v[70:73]
	v_mfma_f32_16x16x32_bf16 v[126:129], v[152:155], v[190:193], v[126:129]
	v_mfma_f32_16x16x32_bf16 v[110:113], v[152:155], v[198:201], v[110:113]
	v_mfma_f32_16x16x32_bf16 v[94:97], v[152:155], v[206:209], v[94:97]
	v_mfma_f32_16x16x32_bf16 v[78:81], v[152:155], v[214:217], v[78:81]
	v_mfma_f32_16x16x32_bf16 v[118:121], v[160:163], v[190:193], v[118:121]
	v_mfma_f32_16x16x32_bf16 v[102:105], v[160:163], v[198:201], v[102:105]
	v_mfma_f32_16x16x32_bf16 v[86:89], v[160:163], v[206:209], v[86:89]
	v_mfma_f32_16x16x32_bf16 v[70:73], v[160:163], v[214:217], v[70:73]
	s_setprio 0
	s_setprio 1
	v_mfma_f32_16x16x32_bf16 v[122:125], v[170:173], v[186:189], v[122:125]
	v_mfma_f32_16x16x32_bf16 v[106:109], v[170:173], v[194:197], v[106:109]
	v_mfma_f32_16x16x32_bf16 v[90:93], v[170:173], v[202:205], v[90:93]
	v_mfma_f32_16x16x32_bf16 v[74:77], v[170:173], v[210:213], v[74:77]
	v_mfma_f32_16x16x32_bf16 v[114:117], v[178:181], v[186:189], v[114:117]
	v_mfma_f32_16x16x32_bf16 v[98:101], v[178:181], v[194:197], v[98:101]
	v_mfma_f32_16x16x32_bf16 v[82:85], v[178:181], v[202:205], v[82:85]
	v_mfma_f32_16x16x32_bf16 v[66:69], v[178:181], v[210:213], v[66:69]
	v_mfma_f32_16x16x32_bf16 v[122:125], v[174:177], v[190:193], v[122:125]
	v_mfma_f32_16x16x32_bf16 v[106:109], v[174:177], v[198:201], v[106:109]
	v_mfma_f32_16x16x32_bf16 v[90:93], v[174:177], v[206:209], v[90:93]
	v_mfma_f32_16x16x32_bf16 v[74:77], v[174:177], v[214:217], v[74:77]
	v_mfma_f32_16x16x32_bf16 v[114:117], v[182:185], v[190:193], v[114:117]
	v_mfma_f32_16x16x32_bf16 v[98:101], v[182:185], v[198:201], v[98:101]
	v_mfma_f32_16x16x32_bf16 v[82:85], v[182:185], v[206:209], v[82:85]
	v_mfma_f32_16x16x32_bf16 v[66:69], v[182:185], v[214:217], v[66:69]
	s_setprio 0
	s_barrier
	s_add_i32 s0, s54, s35
	v_lshl_add_u64 v[218:219], v[218:219], 0, s[14:15]
	s_mov_b32 m0, s0
	ds_read_b128 v[186:189], v167 offset:49152
	ds_read_b128 v[190:193], v167 offset:50176
	ds_read_b128 v[194:197], v167 offset:51200
	ds_read_b128 v[198:201], v167 offset:52224
	ds_read_b128 v[202:205], v167 offset:53248
	ds_read_b128 v[206:209], v167 offset:54272
	ds_read_b128 v[210:213], v167 offset:55296
	ds_read_b128 v[214:217], v167 offset:56320
	global_load_lds_dwordx4 v[218:219], off
	s_add_i32 m0, s0, 0x2000
	s_add_u32 s0, s2, 0x40080
	v_lshl_add_u64 v[218:219], v[220:221], 0, s[14:15]
	s_addc_u32 s1, s3, 0
	s_add_i32 s2, s55, s35
	global_load_lds_dwordx4 v[218:219], off
	v_lshl_add_u64 v[218:219], s[0:1], 0, v[134:135]
	s_mov_b32 m0, s2
	s_nop 0
	global_load_lds_dwordx4 v[218:219], off
	v_lshl_add_u64 v[218:219], s[0:1], 0, v[130:131]
	s_add_i32 m0, s2, 0x2000
	s_nop 0
	global_load_lds_dwordx4 v[218:219], off
	v_lshl_add_u64 v[218:219], v[222:223], 0, s[14:15]
	s_mov_b32 m0, s41
	s_nop 0
	global_load_lds_dwordx4 v[218:219], off
	v_lshl_add_u64 v[218:219], v[224:225], 0, s[14:15]
	s_mov_b32 m0, s42
	s_nop 0
	global_load_lds_dwordx4 v[218:219], off
	s_waitcnt vmcnt(8)
	s_waitcnt lgkmcnt(0)
	s_barrier
	s_setprio 1
	s_waitcnt lgkmcnt(0)
	v_mfma_f32_16x16x32_bf16 v[62:65], v[148:151], v[186:189], v[62:65]
	v_mfma_f32_16x16x32_bf16 v[46:49], v[148:151], v[194:197], v[46:49]
	v_mfma_f32_16x16x32_bf16 v[30:33], v[148:151], v[202:205], v[30:33]
	v_mfma_f32_16x16x32_bf16 v[14:17], v[148:151], v[210:213], v[14:17]
	v_mfma_f32_16x16x32_bf16 v[54:57], v[156:159], v[186:189], v[54:57]
	v_mfma_f32_16x16x32_bf16 v[38:41], v[156:159], v[194:197], v[38:41]
	v_mfma_f32_16x16x32_bf16 v[22:25], v[156:159], v[202:205], v[22:25]
	v_mfma_f32_16x16x32_bf16 v[6:9], v[156:159], v[210:213], v[6:9]
	v_mfma_f32_16x16x32_bf16 v[62:65], v[152:155], v[190:193], v[62:65]
	v_mfma_f32_16x16x32_bf16 v[46:49], v[152:155], v[198:201], v[46:49]
	v_mfma_f32_16x16x32_bf16 v[30:33], v[152:155], v[206:209], v[30:33]
	v_mfma_f32_16x16x32_bf16 v[14:17], v[152:155], v[214:217], v[14:17]
	v_mfma_f32_16x16x32_bf16 v[54:57], v[160:163], v[190:193], v[54:57]
	v_mfma_f32_16x16x32_bf16 v[38:41], v[160:163], v[198:201], v[38:41]
	v_mfma_f32_16x16x32_bf16 v[22:25], v[160:163], v[206:209], v[22:25]
	v_mfma_f32_16x16x32_bf16 v[6:9], v[160:163], v[214:217], v[6:9]
	s_setprio 0
	s_setprio 1
	v_mfma_f32_16x16x32_bf16 v[58:61], v[170:173], v[186:189], v[58:61]
	v_mfma_f32_16x16x32_bf16 v[42:45], v[170:173], v[194:197], v[42:45]
	v_mfma_f32_16x16x32_bf16 v[26:29], v[170:173], v[202:205], v[26:29]
	v_mfma_f32_16x16x32_bf16 v[10:13], v[170:173], v[210:213], v[10:13]
	v_mfma_f32_16x16x32_bf16 v[50:53], v[178:181], v[186:189], v[50:53]
	v_mfma_f32_16x16x32_bf16 v[34:37], v[178:181], v[194:197], v[34:37]
	v_mfma_f32_16x16x32_bf16 v[18:21], v[178:181], v[202:205], v[18:21]
	v_mfma_f32_16x16x32_bf16 v[2:5], v[178:181], v[210:213], v[2:5]
	v_mfma_f32_16x16x32_bf16 v[58:61], v[174:177], v[190:193], v[58:61]
	v_mfma_f32_16x16x32_bf16 v[42:45], v[174:177], v[198:201], v[42:45]
	v_mfma_f32_16x16x32_bf16 v[26:29], v[174:177], v[206:209], v[26:29]
	v_mfma_f32_16x16x32_bf16 v[10:13], v[174:177], v[214:217], v[10:13]
	v_mfma_f32_16x16x32_bf16 v[50:53], v[182:185], v[190:193], v[50:53]
	v_mfma_f32_16x16x32_bf16 v[34:37], v[182:185], v[198:201], v[34:37]
	v_mfma_f32_16x16x32_bf16 v[18:21], v[182:185], v[206:209], v[18:21]
	v_mfma_f32_16x16x32_bf16 v[2:5], v[182:185], v[214:217], v[2:5]
	s_setprio 0
	s_barrier
	s_add_i32 s53, s53, 2
	s_add_u32 s28, s28, 0x100
	s_addc_u32 s29, s29, 0
	s_add_u32 s51, s51, 0x100
	s_addc_u32 s52, s52, 0
	s_cmp_gt_u32 s53, 13
	s_cbranch_scc0 .LBB0_2207
	s_and_b64 vcc, exec, s[16:17]
	s_cbranch_vccz .LBB0_2210
	s_barrier

.LBB0_2290:
	ds_read_b128 v[144:147], v153
	ds_read_b128 v[156:159], v153 offset:1024
	ds_read_b128 v[160:163], v153 offset:2048
	ds_read_b128 v[164:167], v153 offset:3072
	ds_read_b128 v[168:171], v154
	ds_read_b128 v[172:175], v154 offset:1024
	ds_read_b128 v[176:179], v154 offset:2048
	ds_read_b128 v[180:183], v154 offset:3072
	s_add_u32 s2, s16, 0xfff50080
	s_addc_u32 s3, s17, -1
	s_cmp_eq_u32 s43, 40
	s_cselect_b32 s19, s5, s3
	s_cselect_b32 s18, s4, s2
	s_cselect_b32 s3, s15, s42
	s_cselect_b32 s2, s14, s41
	v_lshl_add_u64 v[148:149], s[16:17], 0, v[136:137]
	s_add_i32 m0, s26, 0xc000
	ds_read_b128 v[184:187], v155
	ds_read_b128 v[188:191], v155 offset:1024
	ds_read_b128 v[192:195], v155 offset:2048
	ds_read_b128 v[196:199], v155 offset:3072
	ds_read_b128 v[200:203], v155 offset:4096
	ds_read_b128 v[204:207], v155 offset:5120
	ds_read_b128 v[208:211], v155 offset:6144
	ds_read_b128 v[212:215], v155 offset:7168
	global_load_lds_dwordx4 v[148:149], off
	v_lshl_add_u64 v[148:149], s[16:17], 0, v[138:139]
	s_add_i32 m0, s26, 0xe000
	s_nop 0
	global_load_lds_dwordx4 v[148:149], off
	s_waitcnt vmcnt(8)
	s_waitcnt lgkmcnt(0)
	s_barrier
	s_setprio 1
	s_waitcnt lgkmcnt(0)
	v_mfma_f32_16x16x32_bf16 v[124:127], v[144:147], v[184:187], v[124:127]
	v_mfma_f32_16x16x32_bf16 v[112:115], v[144:147], v[192:195], v[112:115]
	v_mfma_f32_16x16x32_bf16 v[96:99], v[144:147], v[200:203], v[96:99]
	v_mfma_f32_16x16x32_bf16 v[80:83], v[144:147], v[208:211], v[80:83]
	v_mfma_f32_16x16x32_bf16 v[120:123], v[160:163], v[184:187], v[120:123]
	v_mfma_f32_16x16x32_bf16 v[104:107], v[160:163], v[192:195], v[104:107]
	v_mfma_f32_16x16x32_bf16 v[88:91], v[160:163], v[200:203], v[88:91]
	v_mfma_f32_16x16x32_bf16 v[72:75], v[160:163], v[208:211], v[72:75]
	v_mfma_f32_16x16x32_bf16 v[124:127], v[156:159], v[188:191], v[124:127]
	v_mfma_f32_16x16x32_bf16 v[112:115], v[156:159], v[196:199], v[112:115]
	v_mfma_f32_16x16x32_bf16 v[96:99], v[156:159], v[204:207], v[96:99]
	v_mfma_f32_16x16x32_bf16 v[80:83], v[156:159], v[212:215], v[80:83]
	v_mfma_f32_16x16x32_bf16 v[120:123], v[164:167], v[188:191], v[120:123]
	v_mfma_f32_16x16x32_bf16 v[104:107], v[164:167], v[196:199], v[104:107]
	v_mfma_f32_16x16x32_bf16 v[88:91], v[164:167], v[204:207], v[88:91]
	v_mfma_f32_16x16x32_bf16 v[72:75], v[164:167], v[212:215], v[72:75]
	s_setprio 0
	s_setprio 1
	v_mfma_f32_16x16x32_bf16 v[116:119], v[168:171], v[184:187], v[116:119]
	v_mfma_f32_16x16x32_bf16 v[100:103], v[168:171], v[192:195], v[100:103]
	v_mfma_f32_16x16x32_bf16 v[84:87], v[168:171], v[200:203], v[84:87]
	v_mfma_f32_16x16x32_bf16 v[68:71], v[168:171], v[208:211], v[68:71]
	v_mfma_f32_16x16x32_bf16 v[108:111], v[176:179], v[184:187], v[108:111]
	v_mfma_f32_16x16x32_bf16 v[92:95], v[176:179], v[192:195], v[92:95]
	v_mfma_f32_16x16x32_bf16 v[76:79], v[176:179], v[200:203], v[76:79]
	v_mfma_f32_16x16x32_bf16 v[64:67], v[176:179], v[208:211], v[64:67]
	v_mfma_f32_16x16x32_bf16 v[116:119], v[172:175], v[188:191], v[116:119]
	v_mfma_f32_16x16x32_bf16 v[100:103], v[172:175], v[196:199], v[100:103]
	v_mfma_f32_16x16x32_bf16 v[84:87], v[172:175], v[204:207], v[84:87]
	v_mfma_f32_16x16x32_bf16 v[68:71], v[172:175], v[212:215], v[68:71]
	v_mfma_f32_16x16x32_bf16 v[108:111], v[180:183], v[188:191], v[108:111]
	v_mfma_f32_16x16x32_bf16 v[92:95], v[180:183], v[196:199], v[92:95]
	v_mfma_f32_16x16x32_bf16 v[76:79], v[180:183], v[204:207], v[76:79]
	v_mfma_f32_16x16x32_bf16 v[64:67], v[180:183], v[212:215], v[64:67]
	s_setprio 0
	s_barrier
	s_add_i32 s44, s35, s25
	v_lshl_add_u64 v[148:149], s[2:3], 0, v[130:131]
	s_mov_b32 m0, s44
	ds_read_b128 v[184:187], v155 offset:16384
	ds_read_b128 v[188:191], v155 offset:17408
	ds_read_b128 v[192:195], v155 offset:18432
	ds_read_b128 v[196:199], v155 offset:19456
	ds_read_b128 v[200:203], v155 offset:20480
	ds_read_b128 v[204:207], v155 offset:21504
	ds_read_b128 v[208:211], v155 offset:22528
	ds_read_b128 v[212:215], v155 offset:23552
	global_load_lds_dwordx4 v[148:149], off
	s_add_i32 m0, s44, 0x2000
	s_add_u32 s44, s2, 0xb0000
	v_lshl_add_u64 v[216:217], s[2:3], 0, v[134:135]
	s_addc_u32 s45, s3, 0
	s_add_i32 s46, s36, s25
	global_load_lds_dwordx4 v[216:217], off
	v_lshl_add_u64 v[218:219], s[44:45], 0, v[130:131]
	s_mov_b32 m0, s46
	v_lshl_add_u64 v[220:221], s[18:19], 0, v[132:133]
	global_load_lds_dwordx4 v[218:219], off
	v_lshl_add_u64 v[218:219], s[44:45], 0, v[134:135]
	s_add_i32 m0, s46, 0x2000
	s_nop 0
	global_load_lds_dwordx4 v[218:219], off
	v_lshl_add_u64 v[218:219], s[18:19], 0, v[128:129]
	s_mov_b32 m0, s26
	s_nop 0
	global_load_lds_dwordx4 v[218:219], off
	s_mov_b32 m0, s27
	s_nop 0
	global_load_lds_dwordx4 v[220:221], off
	s_waitcnt vmcnt(8)
	s_waitcnt lgkmcnt(0)
	s_barrier
	s_setprio 1
	s_waitcnt lgkmcnt(0)
	v_mfma_f32_16x16x32_bf16 v[60:63], v[144:147], v[184:187], v[60:63]
	v_mfma_f32_16x16x32_bf16 v[48:51], v[144:147], v[192:195], v[48:51]
	v_mfma_f32_16x16x32_bf16 v[32:35], v[144:147], v[200:203], v[32:35]
	v_mfma_f32_16x16x32_bf16 v[16:19], v[144:147], v[208:211], v[16:19]
	v_mfma_f32_16x16x32_bf16 v[56:59], v[160:163], v[184:187], v[56:59]
	v_mfma_f32_16x16x32_bf16 v[40:43], v[160:163], v[192:195], v[40:43]
	v_mfma_f32_16x16x32_bf16 v[24:27], v[160:163], v[200:203], v[24:27]
	v_mfma_f32_16x16x32_bf16 v[8:11], v[160:163], v[208:211], v[8:11]
	v_mfma_f32_16x16x32_bf16 v[60:63], v[156:159], v[188:191], v[60:63]
	v_mfma_f32_16x16x32_bf16 v[48:51], v[156:159], v[196:199], v[48:51]
	v_mfma_f32_16x16x32_bf16 v[32:35], v[156:159], v[204:207], v[32:35]
	v_mfma_f32_16x16x32_bf16 v[16:19], v[156:159], v[212:215], v[16:19]
	v_mfma_f32_16x16x32_bf16 v[56:59], v[164:167], v[188:191], v[56:59]
	v_mfma_f32_16x16x32_bf16 v[40:43], v[164:167], v[196:199], v[40:43]
	v_mfma_f32_16x16x32_bf16 v[24:27], v[164:167], v[204:207], v[24:27]
	v_mfma_f32_16x16x32_bf16 v[8:11], v[164:167], v[212:215], v[8:11]
	s_setprio 0
	s_setprio 1
	v_mfma_f32_16x16x32_bf16 v[52:55], v[168:171], v[184:187], v[52:55]
	v_mfma_f32_16x16x32_bf16 v[36:39], v[168:171], v[192:195], v[36:39]
	v_mfma_f32_16x16x32_bf16 v[20:23], v[168:171], v[200:203], v[20:23]
	v_mfma_f32_16x16x32_bf16 v[4:7], v[168:171], v[208:211], v[4:7]
	v_mfma_f32_16x16x32_bf16 v[44:47], v[176:179], v[184:187], v[44:47]
	v_mfma_f32_16x16x32_bf16 v[28:31], v[176:179], v[192:195], v[28:31]
	v_mfma_f32_16x16x32_bf16 v[12:15], v[176:179], v[200:203], v[12:15]
	v_mfma_f32_16x16x32_bf16 v[0:3], v[176:179], v[208:211], v[0:3]
	v_mfma_f32_16x16x32_bf16 v[52:55], v[172:175], v[188:191], v[52:55]
	v_mfma_f32_16x16x32_bf16 v[36:39], v[172:175], v[196:199], v[36:39]
	v_mfma_f32_16x16x32_bf16 v[20:23], v[172:175], v[204:207], v[20:23]
	v_mfma_f32_16x16x32_bf16 v[4:7], v[172:175], v[212:215], v[4:7]
	v_mfma_f32_16x16x32_bf16 v[44:47], v[180:183], v[188:191], v[44:47]
	v_mfma_f32_16x16x32_bf16 v[28:31], v[180:183], v[196:199], v[28:31]
	v_mfma_f32_16x16x32_bf16 v[12:15], v[180:183], v[204:207], v[12:15]
	v_mfma_f32_16x16x32_bf16 v[0:3], v[180:183], v[212:215], v[0:3]
	s_setprio 0
	s_barrier
	s_add_i32 s44, 0, 0x18000
	s_add_i32 s45, 0, 0x1c000
	v_add_u32_e32 v164, s44, v151
	v_add_u32_e32 v180, s45, v151
	ds_read_b128 v[144:147], v164
	ds_read_b128 v[156:159], v164 offset:1024
	ds_read_b128 v[160:163], v164 offset:2048
	ds_read_b128 v[164:167], v164 offset:3072
	ds_read_b128 v[168:171], v180
	ds_read_b128 v[172:175], v180 offset:1024
	ds_read_b128 v[176:179], v180 offset:2048
	ds_read_b128 v[180:183], v180 offset:3072
	s_add_u32 s18, s18, 0xb0000
	s_addc_u32 s19, s19, 0
	s_mov_b32 m0, s28
	v_lshl_add_u64 v[222:223], s[18:19], 0, v[128:129]
	ds_read_b128 v[184:187], v155 offset:32768
	ds_read_b128 v[188:191], v155 offset:33792
	ds_read_b128 v[192:195], v155 offset:34816
	ds_read_b128 v[196:199], v155 offset:35840
	ds_read_b128 v[200:203], v155 offset:36864
	ds_read_b128 v[204:207], v155 offset:37888
	ds_read_b128 v[208:211], v155 offset:38912
	ds_read_b128 v[212:215], v155 offset:39936
	global_load_lds_dwordx4 v[222:223], off
	v_lshl_add_u64 v[222:223], s[18:19], 0, v[132:133]
	s_mov_b32 m0, s29
	s_nop 0
	global_load_lds_dwordx4 v[222:223], off
	s_waitcnt vmcnt(8)
	s_waitcnt lgkmcnt(0)
	s_barrier
	s_setprio 1
	s_waitcnt lgkmcnt(0)
	v_mfma_f32_16x16x32_bf16 v[124:127], v[144:147], v[184:187], v[124:127]
	v_mfma_f32_16x16x32_bf16 v[112:115], v[144:147], v[192:195], v[112:115]
	v_mfma_f32_16x16x32_bf16 v[96:99], v[144:147], v[200:203], v[96:99]
	v_mfma_f32_16x16x32_bf16 v[80:83], v[144:147], v[208:211], v[80:83]
	v_mfma_f32_16x16x32_bf16 v[120:123], v[160:163], v[184:187], v[120:123]
	v_mfma_f32_16x16x32_bf16 v[104:107], v[160:163], v[192:195], v[104:107]
	v_mfma_f32_16x16x32_bf16 v[88:91], v[160:163], v[200:203], v[88:91]
	v_mfma_f32_16x16x32_bf16 v[72:75], v[160:163], v[208:211], v[72:75]
	v_mfma_f32_16x16x32_bf16 v[124:127], v[156:159], v[188:191], v[124:127]
	v_mfma_f32_16x16x32_bf16 v[112:115], v[156:159], v[196:199], v[112:115]
	v_mfma_f32_16x16x32_bf16 v[96:99], v[156:159], v[204:207], v[96:99]
	v_mfma_f32_16x16x32_bf16 v[80:83], v[156:159], v[212:215], v[80:83]
	v_mfma_f32_16x16x32_bf16 v[120:123], v[164:167], v[188:191], v[120:123]
	v_mfma_f32_16x16x32_bf16 v[104:107], v[164:167], v[196:199], v[104:107]
	v_mfma_f32_16x16x32_bf16 v[88:91], v[164:167], v[204:207], v[88:91]
	v_mfma_f32_16x16x32_bf16 v[72:75], v[164:167], v[212:215], v[72:75]
	s_setprio 0
	s_setprio 1
	v_mfma_f32_16x16x32_bf16 v[116:119], v[168:171], v[184:187], v[116:119]
	v_mfma_f32_16x16x32_bf16 v[100:103], v[168:171], v[192:195], v[100:103]
	v_mfma_f32_16x16x32_bf16 v[84:87], v[168:171], v[200:203], v[84:87]
	v_mfma_f32_16x16x32_bf16 v[68:71], v[168:171], v[208:211], v[68:71]
	v_mfma_f32_16x16x32_bf16 v[108:111], v[176:179], v[184:187], v[108:111]
	v_mfma_f32_16x16x32_bf16 v[92:95], v[176:179], v[192:195], v[92:95]
	v_mfma_f32_16x16x32_bf16 v[76:79], v[176:179], v[200:203], v[76:79]
	v_mfma_f32_16x16x32_bf16 v[64:67], v[176:179], v[208:211], v[64:67]
	v_mfma_f32_16x16x32_bf16 v[116:119], v[172:175], v[188:191], v[116:119]
	v_mfma_f32_16x16x32_bf16 v[100:103], v[172:175], v[196:199], v[100:103]
	v_mfma_f32_16x16x32_bf16 v[84:87], v[172:175], v[204:207], v[84:87]
	v_mfma_f32_16x16x32_bf16 v[68:71], v[172:175], v[212:215], v[68:71]
	v_mfma_f32_16x16x32_bf16 v[108:111], v[180:183], v[188:191], v[108:111]
	v_mfma_f32_16x16x32_bf16 v[92:95], v[180:183], v[196:199], v[92:95]
	v_mfma_f32_16x16x32_bf16 v[76:79], v[180:183], v[204:207], v[76:79]
	v_mfma_f32_16x16x32_bf16 v[64:67], v[180:183], v[212:215], v[64:67]
	s_setprio 0
	s_barrier
	s_add_i32 s18, s44, s25
	v_lshl_add_u64 v[148:149], v[148:149], 0, s[10:11]
	s_mov_b32 m0, s18
	ds_read_b128 v[184:187], v155 offset:49152
	ds_read_b128 v[188:191], v155 offset:50176
	ds_read_b128 v[192:195], v155 offset:51200
	ds_read_b128 v[196:199], v155 offset:52224
	ds_read_b128 v[200:203], v155 offset:53248
	ds_read_b128 v[204:207], v155 offset:54272
	ds_read_b128 v[208:211], v155 offset:55296
	ds_read_b128 v[212:215], v155 offset:56320
	global_load_lds_dwordx4 v[148:149], off
	s_add_i32 m0, s18, 0x2000
	s_add_u32 s2, s2, 0xb0080
	v_lshl_add_u64 v[148:149], v[216:217], 0, s[10:11]
	s_addc_u32 s3, s3, 0
	s_add_i32 s18, s45, s25
	global_load_lds_dwordx4 v[148:149], off
	v_lshl_add_u64 v[148:149], s[2:3], 0, v[130:131]
	s_mov_b32 m0, s18
	s_nop 0
	global_load_lds_dwordx4 v[148:149], off
	v_lshl_add_u64 v[148:149], s[2:3], 0, v[134:135]
	s_add_i32 m0, s18, 0x2000
	s_nop 0
	global_load_lds_dwordx4 v[148:149], off
	v_lshl_add_u64 v[148:149], v[218:219], 0, s[10:11]
	s_mov_b32 m0, s31
	s_nop 0
	global_load_lds_dwordx4 v[148:149], off
	v_lshl_add_u64 v[148:149], v[220:221], 0, s[10:11]
	s_mov_b32 m0, s33
	s_nop 0
	global_load_lds_dwordx4 v[148:149], off
	s_waitcnt vmcnt(8)
	s_waitcnt lgkmcnt(0)
	s_barrier
	s_setprio 1
	s_waitcnt lgkmcnt(0)
	v_mfma_f32_16x16x32_bf16 v[60:63], v[144:147], v[184:187], v[60:63]
	v_mfma_f32_16x16x32_bf16 v[48:51], v[144:147], v[192:195], v[48:51]
	v_mfma_f32_16x16x32_bf16 v[32:35], v[144:147], v[200:203], v[32:35]
	v_mfma_f32_16x16x32_bf16 v[16:19], v[144:147], v[208:211], v[16:19]
	v_mfma_f32_16x16x32_bf16 v[56:59], v[160:163], v[184:187], v[56:59]
	v_mfma_f32_16x16x32_bf16 v[40:43], v[160:163], v[192:195], v[40:43]
	v_mfma_f32_16x16x32_bf16 v[24:27], v[160:163], v[200:203], v[24:27]
	v_mfma_f32_16x16x32_bf16 v[8:11], v[160:163], v[208:211], v[8:11]
	v_mfma_f32_16x16x32_bf16 v[60:63], v[156:159], v[188:191], v[60:63]
	v_mfma_f32_16x16x32_bf16 v[48:51], v[156:159], v[196:199], v[48:51]
	v_mfma_f32_16x16x32_bf16 v[32:35], v[156:159], v[204:207], v[32:35]
	v_mfma_f32_16x16x32_bf16 v[16:19], v[156:159], v[212:215], v[16:19]
	v_mfma_f32_16x16x32_bf16 v[56:59], v[164:167], v[188:191], v[56:59]
	v_mfma_f32_16x16x32_bf16 v[40:43], v[164:167], v[196:199], v[40:43]
	v_mfma_f32_16x16x32_bf16 v[24:27], v[164:167], v[204:207], v[24:27]
	v_mfma_f32_16x16x32_bf16 v[8:11], v[164:167], v[212:215], v[8:11]
	s_setprio 0
	s_setprio 1
	v_mfma_f32_16x16x32_bf16 v[52:55], v[168:171], v[184:187], v[52:55]
	v_mfma_f32_16x16x32_bf16 v[36:39], v[168:171], v[192:195], v[36:39]
	v_mfma_f32_16x16x32_bf16 v[20:23], v[168:171], v[200:203], v[20:23]
	v_mfma_f32_16x16x32_bf16 v[4:7], v[168:171], v[208:211], v[4:7]
	v_mfma_f32_16x16x32_bf16 v[44:47], v[176:179], v[184:187], v[44:47]
	v_mfma_f32_16x16x32_bf16 v[28:31], v[176:179], v[192:195], v[28:31]
	v_mfma_f32_16x16x32_bf16 v[12:15], v[176:179], v[200:203], v[12:15]
	v_mfma_f32_16x16x32_bf16 v[0:3], v[176:179], v[208:211], v[0:3]
	v_mfma_f32_16x16x32_bf16 v[52:55], v[172:175], v[188:191], v[52:55]
	v_mfma_f32_16x16x32_bf16 v[36:39], v[172:175], v[196:199], v[36:39]
	v_mfma_f32_16x16x32_bf16 v[20:23], v[172:175], v[204:207], v[20:23]
	v_mfma_f32_16x16x32_bf16 v[4:7], v[172:175], v[212:215], v[4:7]
	v_mfma_f32_16x16x32_bf16 v[44:47], v[180:183], v[188:191], v[44:47]
	v_mfma_f32_16x16x32_bf16 v[28:31], v[180:183], v[196:199], v[28:31]
	v_mfma_f32_16x16x32_bf16 v[12:15], v[180:183], v[204:207], v[12:15]
	v_mfma_f32_16x16x32_bf16 v[0:3], v[180:183], v[212:215], v[0:3]
	s_setprio 0
	s_barrier
	s_add_i32 s43, s43, 2
	s_add_u32 s16, s16, 0x100
	s_addc_u32 s17, s17, 0
	s_add_u32 s41, s41, 0x100
	s_addc_u32 s42, s42, 0
	s_cmp_gt_u32 s43, 41
	s_cbranch_scc0 .LBB0_2290
	s_and_b64 vcc, exec, s[12:13]
	s_cbranch_vccz .LBB0_2293
	s_barrier
